# v68 + GEMM K-loops: the back-to-back s_setprio 0 / s_setprio 1 pair in the middle of each 32-MFMA block removed (76 sites); the block now runs at priority 1 throughout
# speedup vs baseline: 1.0020x; 1.0020x over previous
.LBB0_126:
	ds_read_b128 v[152:155], v149
	ds_read_b128 v[156:159], v149 offset:1024
	ds_read_b128 v[160:163], v149 offset:2048
	ds_read_b128 v[164:167], v149 offset:3072
	ds_read_b128 v[168:171], v150
	ds_read_b128 v[172:175], v150 offset:1024
	ds_read_b128 v[176:179], v150 offset:2048
	ds_read_b128 v[180:183], v150 offset:3072
	s_add_u32 s26, s24, 0xfffc0080
	s_addc_u32 s27, s25, -1
	s_cmp_eq_u32 s49, 12
	s_cselect_b32 s29, s19, s27
	s_cselect_b32 s28, s45, s26
	s_cselect_b32 s27, s17, s48
	s_cselect_b32 s26, s46, s47
	v_lshl_add_u64 v[144:145], s[24:25], 0, v[138:139]
	s_add_i32 m0, s31, 0xc000
	ds_read_b128 v[184:187], v151
	ds_read_b128 v[188:191], v151 offset:1024
	ds_read_b128 v[192:195], v151 offset:2048
	ds_read_b128 v[196:199], v151 offset:3072
	ds_read_b128 v[200:203], v151 offset:4096
	ds_read_b128 v[204:207], v151 offset:5120
	ds_read_b128 v[208:211], v151 offset:6144
	ds_read_b128 v[212:215], v151 offset:7168
	global_load_lds_dwordx4 v[144:145], off
	v_lshl_add_u64 v[144:145], s[24:25], 0, v[136:137]
	s_add_i32 m0, s31, 0xe000
	s_nop 0
	global_load_lds_dwordx4 v[144:145], off
	s_waitcnt vmcnt(8)
	s_waitcnt lgkmcnt(0)
	s_barrier
	s_setprio 1
	s_waitcnt lgkmcnt(0)
	v_mfma_f32_16x16x32_bf16 v[124:127], v[152:155], v[184:187], v[124:127]
	v_mfma_f32_16x16x32_bf16 v[120:123], v[160:163], v[184:187], v[120:123]
	v_mfma_f32_16x16x32_bf16 v[108:111], v[152:155], v[192:195], v[108:111]
	v_mfma_f32_16x16x32_bf16 v[104:107], v[160:163], v[192:195], v[104:107]
	v_mfma_f32_16x16x32_bf16 v[92:95], v[152:155], v[200:203], v[92:95]
	v_mfma_f32_16x16x32_bf16 v[88:91], v[160:163], v[200:203], v[88:91]
	v_mfma_f32_16x16x32_bf16 v[76:79], v[152:155], v[208:211], v[76:79]
	v_mfma_f32_16x16x32_bf16 v[72:75], v[160:163], v[208:211], v[72:75]
	v_mfma_f32_16x16x32_bf16 v[124:127], v[156:159], v[188:191], v[124:127]
	v_mfma_f32_16x16x32_bf16 v[120:123], v[164:167], v[188:191], v[120:123]
	v_mfma_f32_16x16x32_bf16 v[108:111], v[156:159], v[196:199], v[108:111]
	v_mfma_f32_16x16x32_bf16 v[104:107], v[164:167], v[196:199], v[104:107]
	v_mfma_f32_16x16x32_bf16 v[92:95], v[156:159], v[204:207], v[92:95]
	v_mfma_f32_16x16x32_bf16 v[88:91], v[164:167], v[204:207], v[88:91]
	v_mfma_f32_16x16x32_bf16 v[76:79], v[156:159], v[212:215], v[76:79]
	v_mfma_f32_16x16x32_bf16 v[72:75], v[164:167], v[212:215], v[72:75]
	v_mfma_f32_16x16x32_bf16 v[116:119], v[168:171], v[184:187], v[116:119]
	v_mfma_f32_16x16x32_bf16 v[112:115], v[176:179], v[184:187], v[112:115]
	v_mfma_f32_16x16x32_bf16 v[100:103], v[168:171], v[192:195], v[100:103]
	v_mfma_f32_16x16x32_bf16 v[96:99], v[176:179], v[192:195], v[96:99]
	v_mfma_f32_16x16x32_bf16 v[84:87], v[168:171], v[200:203], v[84:87]
	v_mfma_f32_16x16x32_bf16 v[80:83], v[176:179], v[200:203], v[80:83]
	v_mfma_f32_16x16x32_bf16 v[68:71], v[168:171], v[208:211], v[68:71]
	v_mfma_f32_16x16x32_bf16 v[64:67], v[176:179], v[208:211], v[64:67]
	v_mfma_f32_16x16x32_bf16 v[116:119], v[172:175], v[188:191], v[116:119]
	v_mfma_f32_16x16x32_bf16 v[112:115], v[180:183], v[188:191], v[112:115]
	v_mfma_f32_16x16x32_bf16 v[100:103], v[172:175], v[196:199], v[100:103]
	v_mfma_f32_16x16x32_bf16 v[96:99], v[180:183], v[196:199], v[96:99]
	v_mfma_f32_16x16x32_bf16 v[84:87], v[172:175], v[204:207], v[84:87]
	v_mfma_f32_16x16x32_bf16 v[80:83], v[180:183], v[204:207], v[80:83]
	v_mfma_f32_16x16x32_bf16 v[68:71], v[172:175], v[212:215], v[68:71]
	v_mfma_f32_16x16x32_bf16 v[64:67], v[180:183], v[212:215], v[64:67]
	s_setprio 0
	s_barrier
	s_add_i32 s50, s40, s30
	v_lshl_add_u64 v[144:145], s[26:27], 0, v[132:133]
	s_mov_b32 m0, s50
	ds_read_b128 v[184:187], v151 offset:16384
	ds_read_b128 v[188:191], v151 offset:17408
	ds_read_b128 v[192:195], v151 offset:18432
	ds_read_b128 v[196:199], v151 offset:19456
	ds_read_b128 v[200:203], v151 offset:20480
	ds_read_b128 v[204:207], v151 offset:21504
	ds_read_b128 v[208:211], v151 offset:22528
	ds_read_b128 v[212:215], v151 offset:23552
	global_load_lds_dwordx4 v[144:145], off
	s_add_i32 m0, s50, 0x2000
	s_add_u32 s50, s26, 0x40000
	v_lshl_add_u64 v[216:217], s[26:27], 0, v[128:129]
	s_addc_u32 s51, s27, 0
	s_add_i32 s52, s41, s30
	global_load_lds_dwordx4 v[216:217], off
	v_lshl_add_u64 v[218:219], s[50:51], 0, v[132:133]
	s_mov_b32 m0, s52
	v_lshl_add_u64 v[220:221], s[28:29], 0, v[130:131]
	global_load_lds_dwordx4 v[218:219], off
	v_lshl_add_u64 v[218:219], s[50:51], 0, v[128:129]
	s_add_i32 m0, s52, 0x2000
	s_nop 0
	global_load_lds_dwordx4 v[218:219], off
	v_lshl_add_u64 v[218:219], s[28:29], 0, v[134:135]
	s_mov_b32 m0, s31
	s_nop 0
	global_load_lds_dwordx4 v[218:219], off
	s_mov_b32 m0, s33
	s_nop 0
	global_load_lds_dwordx4 v[220:221], off
	s_waitcnt vmcnt(8)
	s_waitcnt lgkmcnt(0)
	s_barrier
	s_setprio 1
	s_waitcnt lgkmcnt(0)
	v_mfma_f32_16x16x32_bf16 v[60:63], v[152:155], v[184:187], v[60:63]
	v_mfma_f32_16x16x32_bf16 v[56:59], v[160:163], v[184:187], v[56:59]
	v_mfma_f32_16x16x32_bf16 v[44:47], v[152:155], v[192:195], v[44:47]
	v_mfma_f32_16x16x32_bf16 v[40:43], v[160:163], v[192:195], v[40:43]
	v_mfma_f32_16x16x32_bf16 v[28:31], v[152:155], v[200:203], v[28:31]
	v_mfma_f32_16x16x32_bf16 v[24:27], v[160:163], v[200:203], v[24:27]
	v_mfma_f32_16x16x32_bf16 v[12:15], v[152:155], v[208:211], v[12:15]
	v_mfma_f32_16x16x32_bf16 v[8:11], v[160:163], v[208:211], v[8:11]
	v_mfma_f32_16x16x32_bf16 v[60:63], v[156:159], v[188:191], v[60:63]
	v_mfma_f32_16x16x32_bf16 v[56:59], v[164:167], v[188:191], v[56:59]
	v_mfma_f32_16x16x32_bf16 v[44:47], v[156:159], v[196:199], v[44:47]
	v_mfma_f32_16x16x32_bf16 v[40:43], v[164:167], v[196:199], v[40:43]
	v_mfma_f32_16x16x32_bf16 v[28:31], v[156:159], v[204:207], v[28:31]
	v_mfma_f32_16x16x32_bf16 v[24:27], v[164:167], v[204:207], v[24:27]
	v_mfma_f32_16x16x32_bf16 v[12:15], v[156:159], v[212:215], v[12:15]
	v_mfma_f32_16x16x32_bf16 v[8:11], v[164:167], v[212:215], v[8:11]
	v_mfma_f32_16x16x32_bf16 v[52:55], v[168:171], v[184:187], v[52:55]
	v_mfma_f32_16x16x32_bf16 v[48:51], v[176:179], v[184:187], v[48:51]
	v_mfma_f32_16x16x32_bf16 v[36:39], v[168:171], v[192:195], v[36:39]
	v_mfma_f32_16x16x32_bf16 v[32:35], v[176:179], v[192:195], v[32:35]
	v_mfma_f32_16x16x32_bf16 v[20:23], v[168:171], v[200:203], v[20:23]
	v_mfma_f32_16x16x32_bf16 v[16:19], v[176:179], v[200:203], v[16:19]
	v_mfma_f32_16x16x32_bf16 v[4:7], v[168:171], v[208:211], v[4:7]
	v_mfma_f32_16x16x32_bf16 v[0:3], v[176:179], v[208:211], v[0:3]
	v_mfma_f32_16x16x32_bf16 v[52:55], v[172:175], v[188:191], v[52:55]
	v_mfma_f32_16x16x32_bf16 v[48:51], v[180:183], v[188:191], v[48:51]
	v_mfma_f32_16x16x32_bf16 v[36:39], v[172:175], v[196:199], v[36:39]
	v_mfma_f32_16x16x32_bf16 v[32:35], v[180:183], v[196:199], v[32:35]
	v_mfma_f32_16x16x32_bf16 v[20:23], v[172:175], v[204:207], v[20:23]
	v_mfma_f32_16x16x32_bf16 v[16:19], v[180:183], v[204:207], v[16:19]
	v_mfma_f32_16x16x32_bf16 v[4:7], v[172:175], v[212:215], v[4:7]
	v_mfma_f32_16x16x32_bf16 v[0:3], v[180:183], v[212:215], v[0:3]
	s_setprio 0
	s_barrier
	s_add_i32 s50, 0, 0x18000
	s_add_i32 s51, 0, 0x1c000
	v_add_u32_e32 v164, s50, v147
	v_add_u32_e32 v180, s51, v147
	ds_read_b128 v[152:155], v164
	ds_read_b128 v[156:159], v164 offset:1024
	ds_read_b128 v[160:163], v164 offset:2048
	ds_read_b128 v[164:167], v164 offset:3072
	ds_read_b128 v[168:171], v180
	ds_read_b128 v[172:175], v180 offset:1024
	ds_read_b128 v[176:179], v180 offset:2048
	ds_read_b128 v[180:183], v180 offset:3072
	s_add_u32 s28, s28, 0x40000
	s_addc_u32 s29, s29, 0
	s_mov_b32 m0, s34
	v_lshl_add_u64 v[222:223], s[28:29], 0, v[134:135]
	ds_read_b128 v[184:187], v151 offset:32768
	ds_read_b128 v[188:191], v151 offset:33792
	ds_read_b128 v[192:195], v151 offset:34816
	ds_read_b128 v[196:199], v151 offset:35840
	ds_read_b128 v[200:203], v151 offset:36864
	ds_read_b128 v[204:207], v151 offset:37888
	ds_read_b128 v[208:211], v151 offset:38912
	ds_read_b128 v[212:215], v151 offset:39936
	global_load_lds_dwordx4 v[222:223], off
	v_lshl_add_u64 v[222:223], s[28:29], 0, v[130:131]
	s_mov_b32 m0, s35
	s_nop 0
	global_load_lds_dwordx4 v[222:223], off
	s_waitcnt vmcnt(8)
	s_waitcnt lgkmcnt(0)
	s_barrier
	s_setprio 1
	s_waitcnt lgkmcnt(0)
	v_mfma_f32_16x16x32_bf16 v[124:127], v[152:155], v[184:187], v[124:127]
	v_mfma_f32_16x16x32_bf16 v[120:123], v[160:163], v[184:187], v[120:123]
	v_mfma_f32_16x16x32_bf16 v[108:111], v[152:155], v[192:195], v[108:111]
	v_mfma_f32_16x16x32_bf16 v[104:107], v[160:163], v[192:195], v[104:107]
	v_mfma_f32_16x16x32_bf16 v[92:95], v[152:155], v[200:203], v[92:95]
	v_mfma_f32_16x16x32_bf16 v[88:91], v[160:163], v[200:203], v[88:91]
	v_mfma_f32_16x16x32_bf16 v[76:79], v[152:155], v[208:211], v[76:79]
	v_mfma_f32_16x16x32_bf16 v[72:75], v[160:163], v[208:211], v[72:75]
	v_mfma_f32_16x16x32_bf16 v[124:127], v[156:159], v[188:191], v[124:127]
	v_mfma_f32_16x16x32_bf16 v[120:123], v[164:167], v[188:191], v[120:123]
	v_mfma_f32_16x16x32_bf16 v[108:111], v[156:159], v[196:199], v[108:111]
	v_mfma_f32_16x16x32_bf16 v[104:107], v[164:167], v[196:199], v[104:107]
	v_mfma_f32_16x16x32_bf16 v[92:95], v[156:159], v[204:207], v[92:95]
	v_mfma_f32_16x16x32_bf16 v[88:91], v[164:167], v[204:207], v[88:91]
	v_mfma_f32_16x16x32_bf16 v[76:79], v[156:159], v[212:215], v[76:79]
	v_mfma_f32_16x16x32_bf16 v[72:75], v[164:167], v[212:215], v[72:75]
	v_mfma_f32_16x16x32_bf16 v[116:119], v[168:171], v[184:187], v[116:119]
	v_mfma_f32_16x16x32_bf16 v[112:115], v[176:179], v[184:187], v[112:115]
	v_mfma_f32_16x16x32_bf16 v[100:103], v[168:171], v[192:195], v[100:103]
	v_mfma_f32_16x16x32_bf16 v[96:99], v[176:179], v[192:195], v[96:99]
	v_mfma_f32_16x16x32_bf16 v[84:87], v[168:171], v[200:203], v[84:87]
	v_mfma_f32_16x16x32_bf16 v[80:83], v[176:179], v[200:203], v[80:83]
	v_mfma_f32_16x16x32_bf16 v[68:71], v[168:171], v[208:211], v[68:71]
	v_mfma_f32_16x16x32_bf16 v[64:67], v[176:179], v[208:211], v[64:67]
	v_mfma_f32_16x16x32_bf16 v[116:119], v[172:175], v[188:191], v[116:119]
	v_mfma_f32_16x16x32_bf16 v[112:115], v[180:183], v[188:191], v[112:115]
	v_mfma_f32_16x16x32_bf16 v[100:103], v[172:175], v[196:199], v[100:103]
	v_mfma_f32_16x16x32_bf16 v[96:99], v[180:183], v[196:199], v[96:99]
	v_mfma_f32_16x16x32_bf16 v[84:87], v[172:175], v[204:207], v[84:87]
	v_mfma_f32_16x16x32_bf16 v[80:83], v[180:183], v[204:207], v[80:83]
	v_mfma_f32_16x16x32_bf16 v[68:71], v[172:175], v[212:215], v[68:71]
	v_mfma_f32_16x16x32_bf16 v[64:67], v[180:183], v[212:215], v[64:67]
	s_setprio 0
	s_barrier
	s_add_i32 s28, s50, s30
	v_lshl_add_u64 v[144:145], v[144:145], 0, s[12:13]
	s_mov_b32 m0, s28
	ds_read_b128 v[184:187], v151 offset:49152
	ds_read_b128 v[188:191], v151 offset:50176
	ds_read_b128 v[192:195], v151 offset:51200
	ds_read_b128 v[196:199], v151 offset:52224
	ds_read_b128 v[200:203], v151 offset:53248
	ds_read_b128 v[204:207], v151 offset:54272
	ds_read_b128 v[208:211], v151 offset:55296
	ds_read_b128 v[212:215], v151 offset:56320
	global_load_lds_dwordx4 v[144:145], off
	s_add_i32 m0, s28, 0x2000
	s_add_u32 s26, s26, 0x40080
	v_lshl_add_u64 v[144:145], v[216:217], 0, s[12:13]
	s_addc_u32 s27, s27, 0
	s_add_i32 s28, s51, s30
	global_load_lds_dwordx4 v[144:145], off
	v_lshl_add_u64 v[144:145], s[26:27], 0, v[132:133]
	s_mov_b32 m0, s28
	s_nop 0
	global_load_lds_dwordx4 v[144:145], off
	v_lshl_add_u64 v[144:145], s[26:27], 0, v[128:129]
	s_add_i32 m0, s28, 0x2000
	s_nop 0
	global_load_lds_dwordx4 v[144:145], off
	v_lshl_add_u64 v[144:145], v[218:219], 0, s[12:13]
	s_mov_b32 m0, s36
	s_nop 0
	global_load_lds_dwordx4 v[144:145], off
	v_lshl_add_u64 v[144:145], v[220:221], 0, s[12:13]
	s_mov_b32 m0, s37
	s_nop 0
	global_load_lds_dwordx4 v[144:145], off
	s_waitcnt vmcnt(8)
	s_waitcnt lgkmcnt(0)
	s_barrier
	s_setprio 1
	s_waitcnt lgkmcnt(0)
	v_mfma_f32_16x16x32_bf16 v[60:63], v[152:155], v[184:187], v[60:63]
	v_mfma_f32_16x16x32_bf16 v[56:59], v[160:163], v[184:187], v[56:59]
	v_mfma_f32_16x16x32_bf16 v[44:47], v[152:155], v[192:195], v[44:47]
	v_mfma_f32_16x16x32_bf16 v[40:43], v[160:163], v[192:195], v[40:43]
	v_mfma_f32_16x16x32_bf16 v[28:31], v[152:155], v[200:203], v[28:31]
	v_mfma_f32_16x16x32_bf16 v[24:27], v[160:163], v[200:203], v[24:27]
	v_mfma_f32_16x16x32_bf16 v[12:15], v[152:155], v[208:211], v[12:15]
	v_mfma_f32_16x16x32_bf16 v[8:11], v[160:163], v[208:211], v[8:11]
	v_mfma_f32_16x16x32_bf16 v[60:63], v[156:159], v[188:191], v[60:63]
	v_mfma_f32_16x16x32_bf16 v[56:59], v[164:167], v[188:191], v[56:59]
	v_mfma_f32_16x16x32_bf16 v[44:47], v[156:159], v[196:199], v[44:47]
	v_mfma_f32_16x16x32_bf16 v[40:43], v[164:167], v[196:199], v[40:43]
	v_mfma_f32_16x16x32_bf16 v[28:31], v[156:159], v[204:207], v[28:31]
	v_mfma_f32_16x16x32_bf16 v[24:27], v[164:167], v[204:207], v[24:27]
	v_mfma_f32_16x16x32_bf16 v[12:15], v[156:159], v[212:215], v[12:15]
	v_mfma_f32_16x16x32_bf16 v[8:11], v[164:167], v[212:215], v[8:11]
	v_mfma_f32_16x16x32_bf16 v[52:55], v[168:171], v[184:187], v[52:55]
	v_mfma_f32_16x16x32_bf16 v[48:51], v[176:179], v[184:187], v[48:51]
	v_mfma_f32_16x16x32_bf16 v[36:39], v[168:171], v[192:195], v[36:39]
	v_mfma_f32_16x16x32_bf16 v[32:35], v[176:179], v[192:195], v[32:35]
	v_mfma_f32_16x16x32_bf16 v[20:23], v[168:171], v[200:203], v[20:23]
	v_mfma_f32_16x16x32_bf16 v[16:19], v[176:179], v[200:203], v[16:19]
	v_mfma_f32_16x16x32_bf16 v[4:7], v[168:171], v[208:211], v[4:7]
	v_mfma_f32_16x16x32_bf16 v[0:3], v[176:179], v[208:211], v[0:3]
	v_mfma_f32_16x16x32_bf16 v[52:55], v[172:175], v[188:191], v[52:55]
	v_mfma_f32_16x16x32_bf16 v[48:51], v[180:183], v[188:191], v[48:51]
	v_mfma_f32_16x16x32_bf16 v[36:39], v[172:175], v[196:199], v[36:39]
	v_mfma_f32_16x16x32_bf16 v[32:35], v[180:183], v[196:199], v[32:35]
	v_mfma_f32_16x16x32_bf16 v[20:23], v[172:175], v[204:207], v[20:23]
	v_mfma_f32_16x16x32_bf16 v[16:19], v[180:183], v[204:207], v[16:19]
	v_mfma_f32_16x16x32_bf16 v[4:7], v[172:175], v[212:215], v[4:7]
	v_mfma_f32_16x16x32_bf16 v[0:3], v[180:183], v[212:215], v[0:3]
	s_setprio 0
	s_barrier
	s_add_i32 s49, s49, 2
	s_add_u32 s47, s47, 0x100
	s_addc_u32 s48, s48, 0
	s_add_u32 s24, s24, 0x100
	s_addc_u32 s25, s25, 0
	s_cmp_gt_u32 s49, 13
	s_cbranch_scc0 .LBB0_126
	s_and_b64 vcc, exec, s[14:15]
	s_cbranch_vccz .LBB0_129
	s_barrier

.LBB0_198:
	ds_read_b128 v[150:153], v147
	ds_read_b128 v[154:157], v147 offset:1024
	ds_read_b128 v[158:161], v147 offset:2048
	ds_read_b128 v[162:165], v147 offset:3072
	ds_read_b128 v[166:169], v148
	ds_read_b128 v[170:173], v148 offset:1024
	ds_read_b128 v[174:177], v148 offset:2048
	ds_read_b128 v[178:181], v148 offset:3072
	s_add_u32 s34, s30, 0x100
	s_addc_u32 s35, s31, 0
	s_cmp_eq_u32 s58, 40
	s_cselect_b32 s39, s7, s35
	s_cselect_b32 s38, s6, s34
	s_cselect_b32 s37, s29, s57
	s_cselect_b32 s36, s28, s56
	v_lshl_add_u64 v[214:215], s[30:31], 0, v[138:139]
	s_add_i32 m0, s33, 0xc000
	ds_read_b128 v[182:185], v149
	ds_read_b128 v[186:189], v149 offset:1024
	ds_read_b128 v[190:193], v149 offset:2048
	ds_read_b128 v[194:197], v149 offset:3072
	ds_read_b128 v[198:201], v149 offset:4096
	ds_read_b128 v[202:205], v149 offset:5120
	ds_read_b128 v[206:209], v149 offset:6144
	ds_read_b128 v[210:213], v149 offset:7168
	global_load_lds_dwordx4 v[214:215], off
	v_lshl_add_u64 v[214:215], s[30:31], 0, v[136:137]
	s_add_i32 m0, s33, 0xe000
	s_nop 0
	global_load_lds_dwordx4 v[214:215], off
	s_waitcnt vmcnt(8)
	s_waitcnt lgkmcnt(0)
	s_barrier
	s_setprio 1
	s_waitcnt lgkmcnt(0)
	v_mfma_f32_16x16x32_bf16 v[124:127], v[150:153], v[182:185], v[124:127]
	v_mfma_f32_16x16x32_bf16 v[120:123], v[158:161], v[182:185], v[120:123]
	v_mfma_f32_16x16x32_bf16 v[116:119], v[150:153], v[190:193], v[116:119]
	v_mfma_f32_16x16x32_bf16 v[112:115], v[158:161], v[190:193], v[112:115]
	v_mfma_f32_16x16x32_bf16 v[100:103], v[150:153], v[198:201], v[100:103]
	v_mfma_f32_16x16x32_bf16 v[96:99], v[158:161], v[198:201], v[96:99]
	v_mfma_f32_16x16x32_bf16 v[84:87], v[150:153], v[206:209], v[84:87]
	v_mfma_f32_16x16x32_bf16 v[80:83], v[158:161], v[206:209], v[80:83]
	v_mfma_f32_16x16x32_bf16 v[124:127], v[154:157], v[186:189], v[124:127]
	v_mfma_f32_16x16x32_bf16 v[120:123], v[162:165], v[186:189], v[120:123]
	v_mfma_f32_16x16x32_bf16 v[116:119], v[154:157], v[194:197], v[116:119]
	v_mfma_f32_16x16x32_bf16 v[112:115], v[162:165], v[194:197], v[112:115]
	v_mfma_f32_16x16x32_bf16 v[100:103], v[154:157], v[202:205], v[100:103]
	v_mfma_f32_16x16x32_bf16 v[96:99], v[162:165], v[202:205], v[96:99]
	v_mfma_f32_16x16x32_bf16 v[84:87], v[154:157], v[210:213], v[84:87]
	v_mfma_f32_16x16x32_bf16 v[80:83], v[162:165], v[210:213], v[80:83]
	v_mfma_f32_16x16x32_bf16 v[108:111], v[166:169], v[182:185], v[108:111]
	v_mfma_f32_16x16x32_bf16 v[104:107], v[174:177], v[182:185], v[104:107]
	v_mfma_f32_16x16x32_bf16 v[92:95], v[166:169], v[190:193], v[92:95]
	v_mfma_f32_16x16x32_bf16 v[88:91], v[174:177], v[190:193], v[88:91]
	v_mfma_f32_16x16x32_bf16 v[76:79], v[166:169], v[198:201], v[76:79]
	v_mfma_f32_16x16x32_bf16 v[72:75], v[174:177], v[198:201], v[72:75]
	v_mfma_f32_16x16x32_bf16 v[68:71], v[166:169], v[206:209], v[68:71]
	v_mfma_f32_16x16x32_bf16 v[64:67], v[174:177], v[206:209], v[64:67]
	v_mfma_f32_16x16x32_bf16 v[108:111], v[170:173], v[186:189], v[108:111]
	v_mfma_f32_16x16x32_bf16 v[104:107], v[178:181], v[186:189], v[104:107]
	v_mfma_f32_16x16x32_bf16 v[92:95], v[170:173], v[194:197], v[92:95]
	v_mfma_f32_16x16x32_bf16 v[88:91], v[178:181], v[194:197], v[88:91]
	v_mfma_f32_16x16x32_bf16 v[76:79], v[170:173], v[202:205], v[76:79]
	v_mfma_f32_16x16x32_bf16 v[72:75], v[178:181], v[202:205], v[72:75]
	v_mfma_f32_16x16x32_bf16 v[68:71], v[170:173], v[210:213], v[68:71]
	v_mfma_f32_16x16x32_bf16 v[64:67], v[178:181], v[210:213], v[64:67]
	s_setprio 0
	s_barrier
	s_add_i32 s30, s46, s1
	v_lshl_add_u64 v[214:215], s[36:37], 0, v[132:133]
	s_mov_b32 m0, s30
	ds_read_b128 v[182:185], v149 offset:16384
	ds_read_b128 v[186:189], v149 offset:17408
	ds_read_b128 v[190:193], v149 offset:18432
	ds_read_b128 v[194:197], v149 offset:19456
	ds_read_b128 v[198:201], v149 offset:20480
	ds_read_b128 v[202:205], v149 offset:21504
	ds_read_b128 v[206:209], v149 offset:22528
	ds_read_b128 v[210:213], v149 offset:23552
	global_load_lds_dwordx4 v[214:215], off
	s_add_i32 m0, s30, 0x2000
	s_add_u32 s30, s36, 0xb0000
	v_lshl_add_u64 v[216:217], s[36:37], 0, v[128:129]
	s_addc_u32 s31, s37, 0
	s_add_i32 s59, s47, s1
	global_load_lds_dwordx4 v[216:217], off
	v_lshl_add_u64 v[218:219], s[30:31], 0, v[132:133]
	s_mov_b32 m0, s59
	v_lshl_add_u64 v[220:221], s[38:39], 0, v[130:131]
	global_load_lds_dwordx4 v[218:219], off
	v_lshl_add_u64 v[218:219], s[30:31], 0, v[128:129]
	s_add_i32 m0, s59, 0x2000
	s_nop 0
	global_load_lds_dwordx4 v[218:219], off
	v_lshl_add_u64 v[218:219], s[38:39], 0, v[134:135]
	s_mov_b32 m0, s33
	s_nop 0
	global_load_lds_dwordx4 v[218:219], off
	s_mov_b32 m0, s40
	s_nop 0
	global_load_lds_dwordx4 v[220:221], off
	s_waitcnt vmcnt(8)
	s_waitcnt lgkmcnt(0)
	s_barrier
	s_setprio 1
	s_waitcnt lgkmcnt(0)
	v_mfma_f32_16x16x32_bf16 v[60:63], v[150:153], v[182:185], v[60:63]
	v_mfma_f32_16x16x32_bf16 v[56:59], v[158:161], v[182:185], v[56:59]
	v_mfma_f32_16x16x32_bf16 v[52:55], v[150:153], v[190:193], v[52:55]
	v_mfma_f32_16x16x32_bf16 v[48:51], v[158:161], v[190:193], v[48:51]
	v_mfma_f32_16x16x32_bf16 v[36:39], v[150:153], v[198:201], v[36:39]
	v_mfma_f32_16x16x32_bf16 v[32:35], v[158:161], v[198:201], v[32:35]
	v_mfma_f32_16x16x32_bf16 v[20:23], v[150:153], v[206:209], v[20:23]
	v_mfma_f32_16x16x32_bf16 v[16:19], v[158:161], v[206:209], v[16:19]
	v_mfma_f32_16x16x32_bf16 v[60:63], v[154:157], v[186:189], v[60:63]
	v_mfma_f32_16x16x32_bf16 v[56:59], v[162:165], v[186:189], v[56:59]
	v_mfma_f32_16x16x32_bf16 v[52:55], v[154:157], v[194:197], v[52:55]
	v_mfma_f32_16x16x32_bf16 v[48:51], v[162:165], v[194:197], v[48:51]
	v_mfma_f32_16x16x32_bf16 v[36:39], v[154:157], v[202:205], v[36:39]
	v_mfma_f32_16x16x32_bf16 v[32:35], v[162:165], v[202:205], v[32:35]
	v_mfma_f32_16x16x32_bf16 v[20:23], v[154:157], v[210:213], v[20:23]
	v_mfma_f32_16x16x32_bf16 v[16:19], v[162:165], v[210:213], v[16:19]
	v_mfma_f32_16x16x32_bf16 v[44:47], v[166:169], v[182:185], v[44:47]
	v_mfma_f32_16x16x32_bf16 v[40:43], v[174:177], v[182:185], v[40:43]
	v_mfma_f32_16x16x32_bf16 v[28:31], v[166:169], v[190:193], v[28:31]
	v_mfma_f32_16x16x32_bf16 v[24:27], v[174:177], v[190:193], v[24:27]
	v_mfma_f32_16x16x32_bf16 v[12:15], v[166:169], v[198:201], v[12:15]
	v_mfma_f32_16x16x32_bf16 v[8:11], v[174:177], v[198:201], v[8:11]
	v_mfma_f32_16x16x32_bf16 v[4:7], v[166:169], v[206:209], v[4:7]
	v_mfma_f32_16x16x32_bf16 v[0:3], v[174:177], v[206:209], v[0:3]
	v_mfma_f32_16x16x32_bf16 v[44:47], v[170:173], v[186:189], v[44:47]
	v_mfma_f32_16x16x32_bf16 v[40:43], v[178:181], v[186:189], v[40:43]
	v_mfma_f32_16x16x32_bf16 v[28:31], v[170:173], v[194:197], v[28:31]
	v_mfma_f32_16x16x32_bf16 v[24:27], v[178:181], v[194:197], v[24:27]
	v_mfma_f32_16x16x32_bf16 v[12:15], v[170:173], v[202:205], v[12:15]
	v_mfma_f32_16x16x32_bf16 v[8:11], v[178:181], v[202:205], v[8:11]
	v_mfma_f32_16x16x32_bf16 v[4:7], v[170:173], v[210:213], v[4:7]
	v_mfma_f32_16x16x32_bf16 v[0:3], v[178:181], v[210:213], v[0:3]
	s_setprio 0
	s_barrier
	s_add_i32 s59, 0, 0x18000
	s_add_i32 s60, 0, 0x1c000
	v_add_u32_e32 v162, s59, v145
	v_add_u32_e32 v178, s60, v145
	ds_read_b128 v[150:153], v162
	ds_read_b128 v[154:157], v162 offset:1024
	ds_read_b128 v[158:161], v162 offset:2048
	ds_read_b128 v[162:165], v162 offset:3072
	ds_read_b128 v[166:169], v178
	ds_read_b128 v[170:173], v178 offset:1024
	ds_read_b128 v[174:177], v178 offset:2048
	ds_read_b128 v[178:181], v178 offset:3072
	s_add_u32 s30, s38, 0xb0000
	s_addc_u32 s31, s39, 0
	s_mov_b32 m0, s41
	v_lshl_add_u64 v[222:223], s[30:31], 0, v[134:135]
	ds_read_b128 v[182:185], v149 offset:32768
	ds_read_b128 v[186:189], v149 offset:33792
	ds_read_b128 v[190:193], v149 offset:34816
	ds_read_b128 v[194:197], v149 offset:35840
	ds_read_b128 v[198:201], v149 offset:36864
	ds_read_b128 v[202:205], v149 offset:37888
	ds_read_b128 v[206:209], v149 offset:38912
	ds_read_b128 v[210:213], v149 offset:39936
	global_load_lds_dwordx4 v[222:223], off
	v_lshl_add_u64 v[222:223], s[30:31], 0, v[130:131]
	s_mov_b32 m0, s42
	s_nop 0
	global_load_lds_dwordx4 v[222:223], off
	s_waitcnt vmcnt(8)
	s_waitcnt lgkmcnt(0)
	s_barrier
	s_setprio 1
	s_waitcnt lgkmcnt(0)
	v_mfma_f32_16x16x32_bf16 v[124:127], v[150:153], v[182:185], v[124:127]
	v_mfma_f32_16x16x32_bf16 v[120:123], v[158:161], v[182:185], v[120:123]
	v_mfma_f32_16x16x32_bf16 v[116:119], v[150:153], v[190:193], v[116:119]
	v_mfma_f32_16x16x32_bf16 v[112:115], v[158:161], v[190:193], v[112:115]
	v_mfma_f32_16x16x32_bf16 v[100:103], v[150:153], v[198:201], v[100:103]
	v_mfma_f32_16x16x32_bf16 v[96:99], v[158:161], v[198:201], v[96:99]
	v_mfma_f32_16x16x32_bf16 v[84:87], v[150:153], v[206:209], v[84:87]
	v_mfma_f32_16x16x32_bf16 v[80:83], v[158:161], v[206:209], v[80:83]
	v_mfma_f32_16x16x32_bf16 v[124:127], v[154:157], v[186:189], v[124:127]
	v_mfma_f32_16x16x32_bf16 v[120:123], v[162:165], v[186:189], v[120:123]
	v_mfma_f32_16x16x32_bf16 v[116:119], v[154:157], v[194:197], v[116:119]
	v_mfma_f32_16x16x32_bf16 v[112:115], v[162:165], v[194:197], v[112:115]
	v_mfma_f32_16x16x32_bf16 v[100:103], v[154:157], v[202:205], v[100:103]
	v_mfma_f32_16x16x32_bf16 v[96:99], v[162:165], v[202:205], v[96:99]
	v_mfma_f32_16x16x32_bf16 v[84:87], v[154:157], v[210:213], v[84:87]
	v_mfma_f32_16x16x32_bf16 v[80:83], v[162:165], v[210:213], v[80:83]
	v_mfma_f32_16x16x32_bf16 v[108:111], v[166:169], v[182:185], v[108:111]
	v_mfma_f32_16x16x32_bf16 v[104:107], v[174:177], v[182:185], v[104:107]
	v_mfma_f32_16x16x32_bf16 v[92:95], v[166:169], v[190:193], v[92:95]
	v_mfma_f32_16x16x32_bf16 v[88:91], v[174:177], v[190:193], v[88:91]
	v_mfma_f32_16x16x32_bf16 v[76:79], v[166:169], v[198:201], v[76:79]
	v_mfma_f32_16x16x32_bf16 v[72:75], v[174:177], v[198:201], v[72:75]
	v_mfma_f32_16x16x32_bf16 v[68:71], v[166:169], v[206:209], v[68:71]
	v_mfma_f32_16x16x32_bf16 v[64:67], v[174:177], v[206:209], v[64:67]
	v_mfma_f32_16x16x32_bf16 v[108:111], v[170:173], v[186:189], v[108:111]
	v_mfma_f32_16x16x32_bf16 v[104:107], v[178:181], v[186:189], v[104:107]
	v_mfma_f32_16x16x32_bf16 v[92:95], v[170:173], v[194:197], v[92:95]
	v_mfma_f32_16x16x32_bf16 v[88:91], v[178:181], v[194:197], v[88:91]
	v_mfma_f32_16x16x32_bf16 v[76:79], v[170:173], v[202:205], v[76:79]
	v_mfma_f32_16x16x32_bf16 v[72:75], v[178:181], v[202:205], v[72:75]
	v_mfma_f32_16x16x32_bf16 v[68:71], v[170:173], v[210:213], v[68:71]
	v_mfma_f32_16x16x32_bf16 v[64:67], v[178:181], v[210:213], v[64:67]
	s_setprio 0
	s_barrier
	s_add_i32 s30, s59, s1
	v_lshl_add_u64 v[214:215], v[214:215], 0, s[16:17]
	s_mov_b32 m0, s30
	ds_read_b128 v[182:185], v149 offset:49152
	ds_read_b128 v[186:189], v149 offset:50176
	ds_read_b128 v[190:193], v149 offset:51200
	ds_read_b128 v[194:197], v149 offset:52224
	ds_read_b128 v[198:201], v149 offset:53248
	ds_read_b128 v[202:205], v149 offset:54272
	ds_read_b128 v[206:209], v149 offset:55296
	ds_read_b128 v[210:213], v149 offset:56320
	global_load_lds_dwordx4 v[214:215], off
	s_add_i32 m0, s30, 0x2000
	s_add_u32 s30, s36, 0xb0080
	v_lshl_add_u64 v[214:215], v[216:217], 0, s[16:17]
	s_addc_u32 s31, s37, 0
	s_add_i32 s36, s60, s1
	global_load_lds_dwordx4 v[214:215], off
	v_lshl_add_u64 v[214:215], s[30:31], 0, v[132:133]
	s_mov_b32 m0, s36
	s_nop 0
	global_load_lds_dwordx4 v[214:215], off
	v_lshl_add_u64 v[214:215], s[30:31], 0, v[128:129]
	s_add_i32 m0, s36, 0x2000
	s_nop 0
	global_load_lds_dwordx4 v[214:215], off
	v_lshl_add_u64 v[214:215], v[218:219], 0, s[16:17]
	s_mov_b32 m0, s44
	s_nop 0
	global_load_lds_dwordx4 v[214:215], off
	v_lshl_add_u64 v[214:215], v[220:221], 0, s[16:17]
	s_mov_b32 m0, s45
	s_nop 0
	global_load_lds_dwordx4 v[214:215], off
	s_waitcnt vmcnt(8)
	s_waitcnt lgkmcnt(0)
	s_barrier
	s_setprio 1
	s_waitcnt lgkmcnt(0)
	v_mfma_f32_16x16x32_bf16 v[60:63], v[150:153], v[182:185], v[60:63]
	v_mfma_f32_16x16x32_bf16 v[56:59], v[158:161], v[182:185], v[56:59]
	v_mfma_f32_16x16x32_bf16 v[52:55], v[150:153], v[190:193], v[52:55]
	v_mfma_f32_16x16x32_bf16 v[48:51], v[158:161], v[190:193], v[48:51]
	v_mfma_f32_16x16x32_bf16 v[36:39], v[150:153], v[198:201], v[36:39]
	v_mfma_f32_16x16x32_bf16 v[32:35], v[158:161], v[198:201], v[32:35]
	v_mfma_f32_16x16x32_bf16 v[20:23], v[150:153], v[206:209], v[20:23]
	v_mfma_f32_16x16x32_bf16 v[16:19], v[158:161], v[206:209], v[16:19]
	v_mfma_f32_16x16x32_bf16 v[60:63], v[154:157], v[186:189], v[60:63]
	v_mfma_f32_16x16x32_bf16 v[56:59], v[162:165], v[186:189], v[56:59]
	v_mfma_f32_16x16x32_bf16 v[52:55], v[154:157], v[194:197], v[52:55]
	v_mfma_f32_16x16x32_bf16 v[48:51], v[162:165], v[194:197], v[48:51]
	v_mfma_f32_16x16x32_bf16 v[36:39], v[154:157], v[202:205], v[36:39]
	v_mfma_f32_16x16x32_bf16 v[32:35], v[162:165], v[202:205], v[32:35]
	v_mfma_f32_16x16x32_bf16 v[20:23], v[154:157], v[210:213], v[20:23]
	v_mfma_f32_16x16x32_bf16 v[16:19], v[162:165], v[210:213], v[16:19]
	v_mfma_f32_16x16x32_bf16 v[44:47], v[166:169], v[182:185], v[44:47]
	v_mfma_f32_16x16x32_bf16 v[40:43], v[174:177], v[182:185], v[40:43]
	v_mfma_f32_16x16x32_bf16 v[28:31], v[166:169], v[190:193], v[28:31]
	v_mfma_f32_16x16x32_bf16 v[24:27], v[174:177], v[190:193], v[24:27]
	v_mfma_f32_16x16x32_bf16 v[12:15], v[166:169], v[198:201], v[12:15]
	v_mfma_f32_16x16x32_bf16 v[8:11], v[174:177], v[198:201], v[8:11]
	v_mfma_f32_16x16x32_bf16 v[4:7], v[166:169], v[206:209], v[4:7]
	v_mfma_f32_16x16x32_bf16 v[0:3], v[174:177], v[206:209], v[0:3]
	v_mfma_f32_16x16x32_bf16 v[44:47], v[170:173], v[186:189], v[44:47]
	v_mfma_f32_16x16x32_bf16 v[40:43], v[178:181], v[186:189], v[40:43]
	v_mfma_f32_16x16x32_bf16 v[28:31], v[170:173], v[194:197], v[28:31]
	v_mfma_f32_16x16x32_bf16 v[24:27], v[178:181], v[194:197], v[24:27]
	v_mfma_f32_16x16x32_bf16 v[12:15], v[170:173], v[202:205], v[12:15]
	v_mfma_f32_16x16x32_bf16 v[8:11], v[178:181], v[202:205], v[8:11]
	v_mfma_f32_16x16x32_bf16 v[4:7], v[170:173], v[210:213], v[4:7]
	v_mfma_f32_16x16x32_bf16 v[0:3], v[178:181], v[210:213], v[0:3]
	s_setprio 0
	s_barrier
	s_add_i32 s58, s58, 2
	s_add_u32 s56, s56, 0x100
	s_addc_u32 s57, s57, 0
	s_cmp_gt_u32 s58, 41
	s_mov_b64 s[30:31], s[34:35]
	s_cbranch_scc0 .LBB0_198
	s_and_b64 vcc, exec, s[18:19]
	s_cbranch_vccz .LBB0_201
	s_barrier

.LBB0_356:
	ds_read_b128 v[152:155], v148
	ds_read_b128 v[156:159], v148 offset:1024
	ds_read_b128 v[160:163], v148 offset:2048
	ds_read_b128 v[164:167], v148 offset:3072
	ds_read_b128 v[168:171], v149
	ds_read_b128 v[172:175], v149 offset:1024
	ds_read_b128 v[176:179], v149 offset:2048
	ds_read_b128 v[180:183], v149 offset:3072
	s_add_u32 s28, s26, 0xfffc0080
	s_addc_u32 s29, s27, -1
	s_cmp_eq_u32 s49, 12
	s_cselect_b32 s31, s19, s29
	s_cselect_b32 s30, s45, s28
	s_cselect_b32 s29, s17, s48
	s_cselect_b32 s28, s46, s47
	v_lshl_add_u64 v[216:217], s[26:27], 0, v[138:139]
	s_add_i32 m0, s25, 0xc000
	ds_read_b128 v[184:187], v150
	ds_read_b128 v[188:191], v150 offset:1024
	ds_read_b128 v[192:195], v150 offset:2048
	ds_read_b128 v[196:199], v150 offset:3072
	ds_read_b128 v[200:203], v150 offset:4096
	ds_read_b128 v[204:207], v150 offset:5120
	ds_read_b128 v[208:211], v150 offset:6144
	ds_read_b128 v[212:215], v150 offset:7168
	global_load_lds_dwordx4 v[216:217], off
	v_lshl_add_u64 v[216:217], s[26:27], 0, v[136:137]
	s_add_i32 m0, s25, 0xe000
	s_nop 0
	global_load_lds_dwordx4 v[216:217], off
	s_waitcnt vmcnt(8)
	s_waitcnt lgkmcnt(0)
	s_barrier
	s_setprio 1
	s_waitcnt lgkmcnt(0)
	v_mfma_f32_16x16x32_bf16 v[124:127], v[152:155], v[184:187], v[124:127]
	v_mfma_f32_16x16x32_bf16 v[120:123], v[160:163], v[184:187], v[120:123]
	v_mfma_f32_16x16x32_bf16 v[116:119], v[152:155], v[192:195], v[116:119]
	v_mfma_f32_16x16x32_bf16 v[108:111], v[160:163], v[192:195], v[108:111]
	v_mfma_f32_16x16x32_bf16 v[100:103], v[152:155], v[200:203], v[100:103]
	v_mfma_f32_16x16x32_bf16 v[92:95], v[160:163], v[200:203], v[92:95]
	v_mfma_f32_16x16x32_bf16 v[84:87], v[152:155], v[208:211], v[84:87]
	v_mfma_f32_16x16x32_bf16 v[76:79], v[160:163], v[208:211], v[76:79]
	v_mfma_f32_16x16x32_bf16 v[124:127], v[156:159], v[188:191], v[124:127]
	v_mfma_f32_16x16x32_bf16 v[120:123], v[164:167], v[188:191], v[120:123]
	v_mfma_f32_16x16x32_bf16 v[116:119], v[156:159], v[196:199], v[116:119]
	v_mfma_f32_16x16x32_bf16 v[108:111], v[164:167], v[196:199], v[108:111]
	v_mfma_f32_16x16x32_bf16 v[100:103], v[156:159], v[204:207], v[100:103]
	v_mfma_f32_16x16x32_bf16 v[92:95], v[164:167], v[204:207], v[92:95]
	v_mfma_f32_16x16x32_bf16 v[84:87], v[156:159], v[212:215], v[84:87]
	v_mfma_f32_16x16x32_bf16 v[76:79], v[164:167], v[212:215], v[76:79]
	v_mfma_f32_16x16x32_bf16 v[112:115], v[168:171], v[184:187], v[112:115]
	v_mfma_f32_16x16x32_bf16 v[104:107], v[176:179], v[184:187], v[104:107]
	v_mfma_f32_16x16x32_bf16 v[96:99], v[168:171], v[192:195], v[96:99]
	v_mfma_f32_16x16x32_bf16 v[88:91], v[176:179], v[192:195], v[88:91]
	v_mfma_f32_16x16x32_bf16 v[80:83], v[168:171], v[200:203], v[80:83]
	v_mfma_f32_16x16x32_bf16 v[72:75], v[176:179], v[200:203], v[72:75]
	v_mfma_f32_16x16x32_bf16 v[68:71], v[168:171], v[208:211], v[68:71]
	v_mfma_f32_16x16x32_bf16 v[64:67], v[176:179], v[208:211], v[64:67]
	v_mfma_f32_16x16x32_bf16 v[112:115], v[172:175], v[188:191], v[112:115]
	v_mfma_f32_16x16x32_bf16 v[104:107], v[180:183], v[188:191], v[104:107]
	v_mfma_f32_16x16x32_bf16 v[96:99], v[172:175], v[196:199], v[96:99]
	v_mfma_f32_16x16x32_bf16 v[88:91], v[180:183], v[196:199], v[88:91]
	v_mfma_f32_16x16x32_bf16 v[80:83], v[172:175], v[204:207], v[80:83]
	v_mfma_f32_16x16x32_bf16 v[72:75], v[180:183], v[204:207], v[72:75]
	v_mfma_f32_16x16x32_bf16 v[68:71], v[172:175], v[212:215], v[68:71]
	v_mfma_f32_16x16x32_bf16 v[64:67], v[180:183], v[212:215], v[64:67]
	s_setprio 0
	s_barrier
	s_add_i32 s50, s41, s33
	v_lshl_add_u64 v[216:217], s[28:29], 0, v[132:133]
	s_mov_b32 m0, s50
	ds_read_b128 v[184:187], v150 offset:16384
	ds_read_b128 v[188:191], v150 offset:17408
	ds_read_b128 v[192:195], v150 offset:18432
	ds_read_b128 v[196:199], v150 offset:19456
	ds_read_b128 v[200:203], v150 offset:20480
	ds_read_b128 v[204:207], v150 offset:21504
	ds_read_b128 v[208:211], v150 offset:22528
	ds_read_b128 v[212:215], v150 offset:23552
	global_load_lds_dwordx4 v[216:217], off
	s_add_i32 m0, s50, 0x2000
	s_add_u32 s50, s28, 0x40000
	v_lshl_add_u64 v[218:219], s[28:29], 0, v[128:129]
	s_addc_u32 s51, s29, 0
	s_add_i32 s52, s42, s33
	global_load_lds_dwordx4 v[218:219], off
	v_lshl_add_u64 v[220:221], s[50:51], 0, v[132:133]
	s_mov_b32 m0, s52
	v_lshl_add_u64 v[222:223], s[30:31], 0, v[130:131]
	global_load_lds_dwordx4 v[220:221], off
	v_lshl_add_u64 v[220:221], s[50:51], 0, v[128:129]
	s_add_i32 m0, s52, 0x2000
	s_nop 0
	global_load_lds_dwordx4 v[220:221], off
	v_lshl_add_u64 v[220:221], s[30:31], 0, v[134:135]
	s_mov_b32 m0, s25
	s_nop 0
	global_load_lds_dwordx4 v[220:221], off
	s_mov_b32 m0, s35
	s_nop 0
	global_load_lds_dwordx4 v[222:223], off
	s_waitcnt vmcnt(8)
	s_waitcnt lgkmcnt(0)
	s_barrier
	s_setprio 1
	s_waitcnt lgkmcnt(0)
	v_mfma_f32_16x16x32_bf16 v[60:63], v[152:155], v[184:187], v[60:63]
	v_mfma_f32_16x16x32_bf16 v[56:59], v[160:163], v[184:187], v[56:59]
	v_mfma_f32_16x16x32_bf16 v[52:55], v[152:155], v[192:195], v[52:55]
	v_mfma_f32_16x16x32_bf16 v[44:47], v[160:163], v[192:195], v[44:47]
	v_mfma_f32_16x16x32_bf16 v[36:39], v[152:155], v[200:203], v[36:39]
	v_mfma_f32_16x16x32_bf16 v[28:31], v[160:163], v[200:203], v[28:31]
	v_mfma_f32_16x16x32_bf16 v[20:23], v[152:155], v[208:211], v[20:23]
	v_mfma_f32_16x16x32_bf16 v[12:15], v[160:163], v[208:211], v[12:15]
	v_mfma_f32_16x16x32_bf16 v[60:63], v[156:159], v[188:191], v[60:63]
	v_mfma_f32_16x16x32_bf16 v[56:59], v[164:167], v[188:191], v[56:59]
	v_mfma_f32_16x16x32_bf16 v[52:55], v[156:159], v[196:199], v[52:55]
	v_mfma_f32_16x16x32_bf16 v[44:47], v[164:167], v[196:199], v[44:47]
	v_mfma_f32_16x16x32_bf16 v[36:39], v[156:159], v[204:207], v[36:39]
	v_mfma_f32_16x16x32_bf16 v[28:31], v[164:167], v[204:207], v[28:31]
	v_mfma_f32_16x16x32_bf16 v[20:23], v[156:159], v[212:215], v[20:23]
	v_mfma_f32_16x16x32_bf16 v[12:15], v[164:167], v[212:215], v[12:15]
	v_mfma_f32_16x16x32_bf16 v[48:51], v[168:171], v[184:187], v[48:51]
	v_mfma_f32_16x16x32_bf16 v[40:43], v[176:179], v[184:187], v[40:43]
	v_mfma_f32_16x16x32_bf16 v[32:35], v[168:171], v[192:195], v[32:35]
	v_mfma_f32_16x16x32_bf16 v[24:27], v[176:179], v[192:195], v[24:27]
	v_mfma_f32_16x16x32_bf16 v[16:19], v[168:171], v[200:203], v[16:19]
	v_mfma_f32_16x16x32_bf16 v[8:11], v[176:179], v[200:203], v[8:11]
	v_mfma_f32_16x16x32_bf16 v[4:7], v[168:171], v[208:211], v[4:7]
	v_mfma_f32_16x16x32_bf16 v[0:3], v[176:179], v[208:211], v[0:3]
	v_mfma_f32_16x16x32_bf16 v[48:51], v[172:175], v[188:191], v[48:51]
	v_mfma_f32_16x16x32_bf16 v[40:43], v[180:183], v[188:191], v[40:43]
	v_mfma_f32_16x16x32_bf16 v[32:35], v[172:175], v[196:199], v[32:35]
	v_mfma_f32_16x16x32_bf16 v[24:27], v[180:183], v[196:199], v[24:27]
	v_mfma_f32_16x16x32_bf16 v[16:19], v[172:175], v[204:207], v[16:19]
	v_mfma_f32_16x16x32_bf16 v[8:11], v[180:183], v[204:207], v[8:11]
	v_mfma_f32_16x16x32_bf16 v[4:7], v[172:175], v[212:215], v[4:7]
	v_mfma_f32_16x16x32_bf16 v[0:3], v[180:183], v[212:215], v[0:3]
	s_setprio 0
	s_barrier
	s_add_i32 s50, 0, 0x18000
	v_add_u32_e32 v144, s50, v146
	s_add_i32 s51, 0, 0x1c000
	ds_read_b128 v[152:155], v144
	ds_read_b128 v[156:159], v144 offset:1024
	ds_read_b128 v[160:163], v144 offset:2048
	ds_read_b128 v[164:167], v144 offset:3072
	v_add_u32_e32 v144, s51, v146
	ds_read_b128 v[168:171], v144
	ds_read_b128 v[172:175], v144 offset:1024
	ds_read_b128 v[176:179], v144 offset:2048
	ds_read_b128 v[180:183], v144 offset:3072
	s_add_u32 s30, s30, 0x40000
	s_addc_u32 s31, s31, 0
	s_mov_b32 m0, s36
	v_lshl_add_u64 v[224:225], s[30:31], 0, v[134:135]
	ds_read_b128 v[184:187], v150 offset:32768
	ds_read_b128 v[188:191], v150 offset:33792
	ds_read_b128 v[192:195], v150 offset:34816
	ds_read_b128 v[196:199], v150 offset:35840
	ds_read_b128 v[200:203], v150 offset:36864
	ds_read_b128 v[204:207], v150 offset:37888
	ds_read_b128 v[208:211], v150 offset:38912
	ds_read_b128 v[212:215], v150 offset:39936
	global_load_lds_dwordx4 v[224:225], off
	v_lshl_add_u64 v[224:225], s[30:31], 0, v[130:131]
	s_mov_b32 m0, s37
	s_nop 0
	global_load_lds_dwordx4 v[224:225], off
	s_waitcnt vmcnt(8)
	s_waitcnt lgkmcnt(0)
	s_barrier
	s_setprio 1
	s_waitcnt lgkmcnt(0)
	v_mfma_f32_16x16x32_bf16 v[124:127], v[152:155], v[184:187], v[124:127]
	v_mfma_f32_16x16x32_bf16 v[120:123], v[160:163], v[184:187], v[120:123]
	v_mfma_f32_16x16x32_bf16 v[116:119], v[152:155], v[192:195], v[116:119]
	v_mfma_f32_16x16x32_bf16 v[108:111], v[160:163], v[192:195], v[108:111]
	v_mfma_f32_16x16x32_bf16 v[100:103], v[152:155], v[200:203], v[100:103]
	v_mfma_f32_16x16x32_bf16 v[92:95], v[160:163], v[200:203], v[92:95]
	v_mfma_f32_16x16x32_bf16 v[84:87], v[152:155], v[208:211], v[84:87]
	v_mfma_f32_16x16x32_bf16 v[76:79], v[160:163], v[208:211], v[76:79]
	v_mfma_f32_16x16x32_bf16 v[124:127], v[156:159], v[188:191], v[124:127]
	v_mfma_f32_16x16x32_bf16 v[120:123], v[164:167], v[188:191], v[120:123]
	v_mfma_f32_16x16x32_bf16 v[116:119], v[156:159], v[196:199], v[116:119]
	v_mfma_f32_16x16x32_bf16 v[108:111], v[164:167], v[196:199], v[108:111]
	v_mfma_f32_16x16x32_bf16 v[100:103], v[156:159], v[204:207], v[100:103]
	v_mfma_f32_16x16x32_bf16 v[92:95], v[164:167], v[204:207], v[92:95]
	v_mfma_f32_16x16x32_bf16 v[84:87], v[156:159], v[212:215], v[84:87]
	v_mfma_f32_16x16x32_bf16 v[76:79], v[164:167], v[212:215], v[76:79]
	v_mfma_f32_16x16x32_bf16 v[112:115], v[168:171], v[184:187], v[112:115]
	v_mfma_f32_16x16x32_bf16 v[104:107], v[176:179], v[184:187], v[104:107]
	v_mfma_f32_16x16x32_bf16 v[96:99], v[168:171], v[192:195], v[96:99]
	v_mfma_f32_16x16x32_bf16 v[88:91], v[176:179], v[192:195], v[88:91]
	v_mfma_f32_16x16x32_bf16 v[80:83], v[168:171], v[200:203], v[80:83]
	v_mfma_f32_16x16x32_bf16 v[72:75], v[176:179], v[200:203], v[72:75]
	v_mfma_f32_16x16x32_bf16 v[68:71], v[168:171], v[208:211], v[68:71]
	v_mfma_f32_16x16x32_bf16 v[64:67], v[176:179], v[208:211], v[64:67]
	v_mfma_f32_16x16x32_bf16 v[112:115], v[172:175], v[188:191], v[112:115]
	v_mfma_f32_16x16x32_bf16 v[104:107], v[180:183], v[188:191], v[104:107]
	v_mfma_f32_16x16x32_bf16 v[96:99], v[172:175], v[196:199], v[96:99]
	v_mfma_f32_16x16x32_bf16 v[88:91], v[180:183], v[196:199], v[88:91]
	v_mfma_f32_16x16x32_bf16 v[80:83], v[172:175], v[204:207], v[80:83]
	v_mfma_f32_16x16x32_bf16 v[72:75], v[180:183], v[204:207], v[72:75]
	v_mfma_f32_16x16x32_bf16 v[68:71], v[172:175], v[212:215], v[68:71]
	v_mfma_f32_16x16x32_bf16 v[64:67], v[180:183], v[212:215], v[64:67]
	s_setprio 0
	s_barrier
	s_add_i32 s30, s50, s33
	v_lshl_add_u64 v[216:217], v[216:217], 0, s[12:13]
	s_mov_b32 m0, s30
	ds_read_b128 v[184:187], v150 offset:49152
	ds_read_b128 v[188:191], v150 offset:50176
	ds_read_b128 v[192:195], v150 offset:51200
	ds_read_b128 v[196:199], v150 offset:52224
	ds_read_b128 v[200:203], v150 offset:53248
	ds_read_b128 v[204:207], v150 offset:54272
	ds_read_b128 v[208:211], v150 offset:55296
	ds_read_b128 v[212:215], v150 offset:56320
	global_load_lds_dwordx4 v[216:217], off
	s_add_i32 m0, s30, 0x2000
	s_add_u32 s28, s28, 0x40080
	v_lshl_add_u64 v[216:217], v[218:219], 0, s[12:13]
	s_addc_u32 s29, s29, 0
	s_add_i32 s30, s51, s33
	global_load_lds_dwordx4 v[216:217], off
	v_lshl_add_u64 v[216:217], s[28:29], 0, v[132:133]
	s_mov_b32 m0, s30
	s_nop 0
	global_load_lds_dwordx4 v[216:217], off
	v_lshl_add_u64 v[216:217], s[28:29], 0, v[128:129]
	s_add_i32 m0, s30, 0x2000
	s_nop 0
	global_load_lds_dwordx4 v[216:217], off
	v_lshl_add_u64 v[216:217], v[220:221], 0, s[12:13]
	s_mov_b32 m0, s39
	s_nop 0
	global_load_lds_dwordx4 v[216:217], off
	v_lshl_add_u64 v[216:217], v[222:223], 0, s[12:13]
	s_mov_b32 m0, s40
	s_nop 0
	global_load_lds_dwordx4 v[216:217], off
	s_waitcnt vmcnt(8)
	s_waitcnt lgkmcnt(0)
	s_barrier
	s_setprio 1
	s_waitcnt lgkmcnt(0)
	v_mfma_f32_16x16x32_bf16 v[60:63], v[152:155], v[184:187], v[60:63]
	v_mfma_f32_16x16x32_bf16 v[56:59], v[160:163], v[184:187], v[56:59]
	v_mfma_f32_16x16x32_bf16 v[52:55], v[152:155], v[192:195], v[52:55]
	v_mfma_f32_16x16x32_bf16 v[44:47], v[160:163], v[192:195], v[44:47]
	v_mfma_f32_16x16x32_bf16 v[36:39], v[152:155], v[200:203], v[36:39]
	v_mfma_f32_16x16x32_bf16 v[28:31], v[160:163], v[200:203], v[28:31]
	v_mfma_f32_16x16x32_bf16 v[20:23], v[152:155], v[208:211], v[20:23]
	v_mfma_f32_16x16x32_bf16 v[12:15], v[160:163], v[208:211], v[12:15]
	v_mfma_f32_16x16x32_bf16 v[60:63], v[156:159], v[188:191], v[60:63]
	v_mfma_f32_16x16x32_bf16 v[56:59], v[164:167], v[188:191], v[56:59]
	v_mfma_f32_16x16x32_bf16 v[52:55], v[156:159], v[196:199], v[52:55]
	v_mfma_f32_16x16x32_bf16 v[44:47], v[164:167], v[196:199], v[44:47]
	v_mfma_f32_16x16x32_bf16 v[36:39], v[156:159], v[204:207], v[36:39]
	v_mfma_f32_16x16x32_bf16 v[28:31], v[164:167], v[204:207], v[28:31]
	v_mfma_f32_16x16x32_bf16 v[20:23], v[156:159], v[212:215], v[20:23]
	v_mfma_f32_16x16x32_bf16 v[12:15], v[164:167], v[212:215], v[12:15]
	v_mfma_f32_16x16x32_bf16 v[48:51], v[168:171], v[184:187], v[48:51]
	v_mfma_f32_16x16x32_bf16 v[40:43], v[176:179], v[184:187], v[40:43]
	v_mfma_f32_16x16x32_bf16 v[32:35], v[168:171], v[192:195], v[32:35]
	v_mfma_f32_16x16x32_bf16 v[24:27], v[176:179], v[192:195], v[24:27]
	v_mfma_f32_16x16x32_bf16 v[16:19], v[168:171], v[200:203], v[16:19]
	v_mfma_f32_16x16x32_bf16 v[8:11], v[176:179], v[200:203], v[8:11]
	v_mfma_f32_16x16x32_bf16 v[4:7], v[168:171], v[208:211], v[4:7]
	v_mfma_f32_16x16x32_bf16 v[0:3], v[176:179], v[208:211], v[0:3]
	v_mfma_f32_16x16x32_bf16 v[48:51], v[172:175], v[188:191], v[48:51]
	v_mfma_f32_16x16x32_bf16 v[40:43], v[180:183], v[188:191], v[40:43]
	v_mfma_f32_16x16x32_bf16 v[32:35], v[172:175], v[196:199], v[32:35]
	v_mfma_f32_16x16x32_bf16 v[24:27], v[180:183], v[196:199], v[24:27]
	v_mfma_f32_16x16x32_bf16 v[16:19], v[172:175], v[204:207], v[16:19]
	v_mfma_f32_16x16x32_bf16 v[8:11], v[180:183], v[204:207], v[8:11]
	v_mfma_f32_16x16x32_bf16 v[4:7], v[172:175], v[212:215], v[4:7]
	v_mfma_f32_16x16x32_bf16 v[0:3], v[180:183], v[212:215], v[0:3]
	s_setprio 0
	s_barrier
	s_add_i32 s49, s49, 2
	s_add_u32 s47, s47, 0x100
	s_addc_u32 s48, s48, 0
	s_add_u32 s26, s26, 0x100
	s_addc_u32 s27, s27, 0
	s_cmp_gt_u32 s49, 13
	s_cbranch_scc0 .LBB0_356
	s_and_b64 vcc, exec, s[14:15]
	s_cbranch_vccz .LBB0_359
	s_barrier

.LBB0_729:
	ds_read_b128 v[150:153], v147
	ds_read_b128 v[154:157], v147 offset:1024
	ds_read_b128 v[158:161], v147 offset:2048
	ds_read_b128 v[162:165], v147 offset:3072
	ds_read_b128 v[166:169], v148
	ds_read_b128 v[170:173], v148 offset:1024
	ds_read_b128 v[174:177], v148 offset:2048
	ds_read_b128 v[178:181], v148 offset:3072
	s_add_u32 s36, s34, 0xfffc0080
	s_addc_u32 s37, s35, -1
	s_cmp_eq_u32 s59, 12
	s_cselect_b32 s39, s27, s37
	s_cselect_b32 s38, s55, s36
	s_cselect_b32 s37, s25, s58
	s_cselect_b32 s36, s56, s57
	v_lshl_add_u64 v[214:215], s[34:35], 0, v[138:139]
	s_add_i32 m0, s40, 0xc000
	ds_read_b128 v[182:185], v149
	ds_read_b128 v[186:189], v149 offset:1024
	ds_read_b128 v[190:193], v149 offset:2048
	ds_read_b128 v[194:197], v149 offset:3072
	ds_read_b128 v[198:201], v149 offset:4096
	ds_read_b128 v[202:205], v149 offset:5120
	ds_read_b128 v[206:209], v149 offset:6144
	ds_read_b128 v[210:213], v149 offset:7168
	global_load_lds_dwordx4 v[214:215], off
	v_lshl_add_u64 v[214:215], s[34:35], 0, v[136:137]
	s_add_i32 m0, s40, 0xe000
	s_nop 0
	global_load_lds_dwordx4 v[214:215], off
	s_waitcnt vmcnt(8)
	s_waitcnt lgkmcnt(0)
	s_barrier
	s_setprio 1
	s_waitcnt lgkmcnt(0)
	v_mfma_f32_16x16x32_bf16 v[124:127], v[150:153], v[182:185], v[124:127]
	v_mfma_f32_16x16x32_bf16 v[120:123], v[158:161], v[182:185], v[120:123]
	v_mfma_f32_16x16x32_bf16 v[116:119], v[150:153], v[190:193], v[116:119]
	v_mfma_f32_16x16x32_bf16 v[112:115], v[158:161], v[190:193], v[112:115]
	v_mfma_f32_16x16x32_bf16 v[100:103], v[150:153], v[198:201], v[100:103]
	v_mfma_f32_16x16x32_bf16 v[96:99], v[158:161], v[198:201], v[96:99]
	v_mfma_f32_16x16x32_bf16 v[84:87], v[150:153], v[206:209], v[84:87]
	v_mfma_f32_16x16x32_bf16 v[80:83], v[158:161], v[206:209], v[80:83]
	v_mfma_f32_16x16x32_bf16 v[124:127], v[154:157], v[186:189], v[124:127]
	v_mfma_f32_16x16x32_bf16 v[120:123], v[162:165], v[186:189], v[120:123]
	v_mfma_f32_16x16x32_bf16 v[116:119], v[154:157], v[194:197], v[116:119]
	v_mfma_f32_16x16x32_bf16 v[112:115], v[162:165], v[194:197], v[112:115]
	v_mfma_f32_16x16x32_bf16 v[100:103], v[154:157], v[202:205], v[100:103]
	v_mfma_f32_16x16x32_bf16 v[96:99], v[162:165], v[202:205], v[96:99]
	v_mfma_f32_16x16x32_bf16 v[84:87], v[154:157], v[210:213], v[84:87]
	v_mfma_f32_16x16x32_bf16 v[80:83], v[162:165], v[210:213], v[80:83]
	v_mfma_f32_16x16x32_bf16 v[108:111], v[166:169], v[182:185], v[108:111]
	v_mfma_f32_16x16x32_bf16 v[104:107], v[174:177], v[182:185], v[104:107]
	v_mfma_f32_16x16x32_bf16 v[92:95], v[166:169], v[190:193], v[92:95]
	v_mfma_f32_16x16x32_bf16 v[88:91], v[174:177], v[190:193], v[88:91]
	v_mfma_f32_16x16x32_bf16 v[76:79], v[166:169], v[198:201], v[76:79]
	v_mfma_f32_16x16x32_bf16 v[72:75], v[174:177], v[198:201], v[72:75]
	v_mfma_f32_16x16x32_bf16 v[68:71], v[166:169], v[206:209], v[68:71]
	v_mfma_f32_16x16x32_bf16 v[64:67], v[174:177], v[206:209], v[64:67]
	v_mfma_f32_16x16x32_bf16 v[108:111], v[170:173], v[186:189], v[108:111]
	v_mfma_f32_16x16x32_bf16 v[104:107], v[178:181], v[186:189], v[104:107]
	v_mfma_f32_16x16x32_bf16 v[92:95], v[170:173], v[194:197], v[92:95]
	v_mfma_f32_16x16x32_bf16 v[88:91], v[178:181], v[194:197], v[88:91]
	v_mfma_f32_16x16x32_bf16 v[76:79], v[170:173], v[202:205], v[76:79]
	v_mfma_f32_16x16x32_bf16 v[72:75], v[178:181], v[202:205], v[72:75]
	v_mfma_f32_16x16x32_bf16 v[68:71], v[170:173], v[210:213], v[68:71]
	v_mfma_f32_16x16x32_bf16 v[64:67], v[178:181], v[210:213], v[64:67]
	s_setprio 0
	s_barrier
	s_add_i32 s60, s47, s33
	v_lshl_add_u64 v[214:215], s[36:37], 0, v[132:133]
	s_mov_b32 m0, s60
	ds_read_b128 v[182:185], v149 offset:16384
	ds_read_b128 v[186:189], v149 offset:17408
	ds_read_b128 v[190:193], v149 offset:18432
	ds_read_b128 v[194:197], v149 offset:19456
	ds_read_b128 v[198:201], v149 offset:20480
	ds_read_b128 v[202:205], v149 offset:21504
	ds_read_b128 v[206:209], v149 offset:22528
	ds_read_b128 v[210:213], v149 offset:23552
	global_load_lds_dwordx4 v[214:215], off
	s_add_i32 m0, s60, 0x2000
	s_add_u32 s60, s36, 0x40000
	v_lshl_add_u64 v[216:217], s[36:37], 0, v[128:129]
	s_addc_u32 s61, s37, 0
	s_add_i32 s62, s48, s33
	global_load_lds_dwordx4 v[216:217], off
	v_lshl_add_u64 v[218:219], s[60:61], 0, v[132:133]
	s_mov_b32 m0, s62
	v_lshl_add_u64 v[220:221], s[38:39], 0, v[130:131]
	global_load_lds_dwordx4 v[218:219], off
	v_lshl_add_u64 v[218:219], s[60:61], 0, v[128:129]
	s_add_i32 m0, s62, 0x2000
	s_nop 0
	global_load_lds_dwordx4 v[218:219], off
	v_lshl_add_u64 v[218:219], s[38:39], 0, v[134:135]
	s_mov_b32 m0, s40
	s_nop 0
	global_load_lds_dwordx4 v[218:219], off
	s_mov_b32 m0, s41
	s_nop 0
	global_load_lds_dwordx4 v[220:221], off
	s_waitcnt vmcnt(8)
	s_waitcnt lgkmcnt(0)
	s_barrier
	s_setprio 1
	s_waitcnt lgkmcnt(0)
	v_mfma_f32_16x16x32_bf16 v[60:63], v[150:153], v[182:185], v[60:63]
	v_mfma_f32_16x16x32_bf16 v[56:59], v[158:161], v[182:185], v[56:59]
	v_mfma_f32_16x16x32_bf16 v[52:55], v[150:153], v[190:193], v[52:55]
	v_mfma_f32_16x16x32_bf16 v[48:51], v[158:161], v[190:193], v[48:51]
	v_mfma_f32_16x16x32_bf16 v[36:39], v[150:153], v[198:201], v[36:39]
	v_mfma_f32_16x16x32_bf16 v[32:35], v[158:161], v[198:201], v[32:35]
	v_mfma_f32_16x16x32_bf16 v[20:23], v[150:153], v[206:209], v[20:23]
	v_mfma_f32_16x16x32_bf16 v[16:19], v[158:161], v[206:209], v[16:19]
	v_mfma_f32_16x16x32_bf16 v[60:63], v[154:157], v[186:189], v[60:63]
	v_mfma_f32_16x16x32_bf16 v[56:59], v[162:165], v[186:189], v[56:59]
	v_mfma_f32_16x16x32_bf16 v[52:55], v[154:157], v[194:197], v[52:55]
	v_mfma_f32_16x16x32_bf16 v[48:51], v[162:165], v[194:197], v[48:51]
	v_mfma_f32_16x16x32_bf16 v[36:39], v[154:157], v[202:205], v[36:39]
	v_mfma_f32_16x16x32_bf16 v[32:35], v[162:165], v[202:205], v[32:35]
	v_mfma_f32_16x16x32_bf16 v[20:23], v[154:157], v[210:213], v[20:23]
	v_mfma_f32_16x16x32_bf16 v[16:19], v[162:165], v[210:213], v[16:19]
	v_mfma_f32_16x16x32_bf16 v[44:47], v[166:169], v[182:185], v[44:47]
	v_mfma_f32_16x16x32_bf16 v[40:43], v[174:177], v[182:185], v[40:43]
	v_mfma_f32_16x16x32_bf16 v[28:31], v[166:169], v[190:193], v[28:31]
	v_mfma_f32_16x16x32_bf16 v[24:27], v[174:177], v[190:193], v[24:27]
	v_mfma_f32_16x16x32_bf16 v[12:15], v[166:169], v[198:201], v[12:15]
	v_mfma_f32_16x16x32_bf16 v[8:11], v[174:177], v[198:201], v[8:11]
	v_mfma_f32_16x16x32_bf16 v[4:7], v[166:169], v[206:209], v[4:7]
	v_mfma_f32_16x16x32_bf16 v[0:3], v[174:177], v[206:209], v[0:3]
	v_mfma_f32_16x16x32_bf16 v[44:47], v[170:173], v[186:189], v[44:47]
	v_mfma_f32_16x16x32_bf16 v[40:43], v[178:181], v[186:189], v[40:43]
	v_mfma_f32_16x16x32_bf16 v[28:31], v[170:173], v[194:197], v[28:31]
	v_mfma_f32_16x16x32_bf16 v[24:27], v[178:181], v[194:197], v[24:27]
	v_mfma_f32_16x16x32_bf16 v[12:15], v[170:173], v[202:205], v[12:15]
	v_mfma_f32_16x16x32_bf16 v[8:11], v[178:181], v[202:205], v[8:11]
	v_mfma_f32_16x16x32_bf16 v[4:7], v[170:173], v[210:213], v[4:7]
	v_mfma_f32_16x16x32_bf16 v[0:3], v[178:181], v[210:213], v[0:3]
	s_setprio 0
	s_barrier
	s_add_i32 s60, 0, 0x18000
	s_add_i32 s61, 0, 0x1c000
	v_add_u32_e32 v162, s60, v145
	v_add_u32_e32 v178, s61, v145
	ds_read_b128 v[150:153], v162
	ds_read_b128 v[154:157], v162 offset:1024
	ds_read_b128 v[158:161], v162 offset:2048
	ds_read_b128 v[162:165], v162 offset:3072
	ds_read_b128 v[166:169], v178
	ds_read_b128 v[170:173], v178 offset:1024
	ds_read_b128 v[174:177], v178 offset:2048
	ds_read_b128 v[178:181], v178 offset:3072
	s_add_u32 s38, s38, 0x40000
	s_addc_u32 s39, s39, 0
	s_mov_b32 m0, s42
	v_lshl_add_u64 v[222:223], s[38:39], 0, v[134:135]
	ds_read_b128 v[182:185], v149 offset:32768
	ds_read_b128 v[186:189], v149 offset:33792
	ds_read_b128 v[190:193], v149 offset:34816
	ds_read_b128 v[194:197], v149 offset:35840
	ds_read_b128 v[198:201], v149 offset:36864
	ds_read_b128 v[202:205], v149 offset:37888
	ds_read_b128 v[206:209], v149 offset:38912
	ds_read_b128 v[210:213], v149 offset:39936
	global_load_lds_dwordx4 v[222:223], off
	v_lshl_add_u64 v[222:223], s[38:39], 0, v[130:131]
	s_mov_b32 m0, s43
	s_nop 0
	global_load_lds_dwordx4 v[222:223], off
	s_waitcnt vmcnt(8)
	s_waitcnt lgkmcnt(0)
	s_barrier
	s_setprio 1
	s_waitcnt lgkmcnt(0)
	v_mfma_f32_16x16x32_bf16 v[124:127], v[150:153], v[182:185], v[124:127]
	v_mfma_f32_16x16x32_bf16 v[120:123], v[158:161], v[182:185], v[120:123]
	v_mfma_f32_16x16x32_bf16 v[116:119], v[150:153], v[190:193], v[116:119]
	v_mfma_f32_16x16x32_bf16 v[112:115], v[158:161], v[190:193], v[112:115]
	v_mfma_f32_16x16x32_bf16 v[100:103], v[150:153], v[198:201], v[100:103]
	v_mfma_f32_16x16x32_bf16 v[96:99], v[158:161], v[198:201], v[96:99]
	v_mfma_f32_16x16x32_bf16 v[84:87], v[150:153], v[206:209], v[84:87]
	v_mfma_f32_16x16x32_bf16 v[80:83], v[158:161], v[206:209], v[80:83]
	v_mfma_f32_16x16x32_bf16 v[124:127], v[154:157], v[186:189], v[124:127]
	v_mfma_f32_16x16x32_bf16 v[120:123], v[162:165], v[186:189], v[120:123]
	v_mfma_f32_16x16x32_bf16 v[116:119], v[154:157], v[194:197], v[116:119]
	v_mfma_f32_16x16x32_bf16 v[112:115], v[162:165], v[194:197], v[112:115]
	v_mfma_f32_16x16x32_bf16 v[100:103], v[154:157], v[202:205], v[100:103]
	v_mfma_f32_16x16x32_bf16 v[96:99], v[162:165], v[202:205], v[96:99]
	v_mfma_f32_16x16x32_bf16 v[84:87], v[154:157], v[210:213], v[84:87]
	v_mfma_f32_16x16x32_bf16 v[80:83], v[162:165], v[210:213], v[80:83]
	v_mfma_f32_16x16x32_bf16 v[108:111], v[166:169], v[182:185], v[108:111]
	v_mfma_f32_16x16x32_bf16 v[104:107], v[174:177], v[182:185], v[104:107]
	v_mfma_f32_16x16x32_bf16 v[92:95], v[166:169], v[190:193], v[92:95]
	v_mfma_f32_16x16x32_bf16 v[88:91], v[174:177], v[190:193], v[88:91]
	v_mfma_f32_16x16x32_bf16 v[76:79], v[166:169], v[198:201], v[76:79]
	v_mfma_f32_16x16x32_bf16 v[72:75], v[174:177], v[198:201], v[72:75]
	v_mfma_f32_16x16x32_bf16 v[68:71], v[166:169], v[206:209], v[68:71]
	v_mfma_f32_16x16x32_bf16 v[64:67], v[174:177], v[206:209], v[64:67]
	v_mfma_f32_16x16x32_bf16 v[108:111], v[170:173], v[186:189], v[108:111]
	v_mfma_f32_16x16x32_bf16 v[104:107], v[178:181], v[186:189], v[104:107]
	v_mfma_f32_16x16x32_bf16 v[92:95], v[170:173], v[194:197], v[92:95]
	v_mfma_f32_16x16x32_bf16 v[88:91], v[178:181], v[194:197], v[88:91]
	v_mfma_f32_16x16x32_bf16 v[76:79], v[170:173], v[202:205], v[76:79]
	v_mfma_f32_16x16x32_bf16 v[72:75], v[178:181], v[202:205], v[72:75]
	v_mfma_f32_16x16x32_bf16 v[68:71], v[170:173], v[210:213], v[68:71]
	v_mfma_f32_16x16x32_bf16 v[64:67], v[178:181], v[210:213], v[64:67]
	s_setprio 0
	s_barrier
	s_add_i32 s38, s60, s33
	v_lshl_add_u64 v[214:215], v[214:215], 0, s[14:15]
	s_mov_b32 m0, s38
	ds_read_b128 v[182:185], v149 offset:49152
	ds_read_b128 v[186:189], v149 offset:50176
	ds_read_b128 v[190:193], v149 offset:51200
	ds_read_b128 v[194:197], v149 offset:52224
	ds_read_b128 v[198:201], v149 offset:53248
	ds_read_b128 v[202:205], v149 offset:54272
	ds_read_b128 v[206:209], v149 offset:55296
	ds_read_b128 v[210:213], v149 offset:56320
	global_load_lds_dwordx4 v[214:215], off
	s_add_i32 m0, s38, 0x2000
	s_add_u32 s36, s36, 0x40080
	v_lshl_add_u64 v[214:215], v[216:217], 0, s[14:15]
	s_addc_u32 s37, s37, 0
	s_add_i32 s38, s61, s33
	global_load_lds_dwordx4 v[214:215], off
	v_lshl_add_u64 v[214:215], s[36:37], 0, v[132:133]
	s_mov_b32 m0, s38
	s_nop 0
	global_load_lds_dwordx4 v[214:215], off
	v_lshl_add_u64 v[214:215], s[36:37], 0, v[128:129]
	s_add_i32 m0, s38, 0x2000
	s_nop 0
	global_load_lds_dwordx4 v[214:215], off
	v_lshl_add_u64 v[214:215], v[218:219], 0, s[14:15]
	s_mov_b32 m0, s45
	s_nop 0
	global_load_lds_dwordx4 v[214:215], off
	v_lshl_add_u64 v[214:215], v[220:221], 0, s[14:15]
	s_mov_b32 m0, s46
	s_nop 0
	global_load_lds_dwordx4 v[214:215], off
	s_waitcnt vmcnt(8)
	s_waitcnt lgkmcnt(0)
	s_barrier
	s_setprio 1
	s_waitcnt lgkmcnt(0)
	v_mfma_f32_16x16x32_bf16 v[60:63], v[150:153], v[182:185], v[60:63]
	v_mfma_f32_16x16x32_bf16 v[56:59], v[158:161], v[182:185], v[56:59]
	v_mfma_f32_16x16x32_bf16 v[52:55], v[150:153], v[190:193], v[52:55]
	v_mfma_f32_16x16x32_bf16 v[48:51], v[158:161], v[190:193], v[48:51]
	v_mfma_f32_16x16x32_bf16 v[36:39], v[150:153], v[198:201], v[36:39]
	v_mfma_f32_16x16x32_bf16 v[32:35], v[158:161], v[198:201], v[32:35]
	v_mfma_f32_16x16x32_bf16 v[20:23], v[150:153], v[206:209], v[20:23]
	v_mfma_f32_16x16x32_bf16 v[16:19], v[158:161], v[206:209], v[16:19]
	v_mfma_f32_16x16x32_bf16 v[60:63], v[154:157], v[186:189], v[60:63]
	v_mfma_f32_16x16x32_bf16 v[56:59], v[162:165], v[186:189], v[56:59]
	v_mfma_f32_16x16x32_bf16 v[52:55], v[154:157], v[194:197], v[52:55]
	v_mfma_f32_16x16x32_bf16 v[48:51], v[162:165], v[194:197], v[48:51]
	v_mfma_f32_16x16x32_bf16 v[36:39], v[154:157], v[202:205], v[36:39]
	v_mfma_f32_16x16x32_bf16 v[32:35], v[162:165], v[202:205], v[32:35]
	v_mfma_f32_16x16x32_bf16 v[20:23], v[154:157], v[210:213], v[20:23]
	v_mfma_f32_16x16x32_bf16 v[16:19], v[162:165], v[210:213], v[16:19]
	v_mfma_f32_16x16x32_bf16 v[44:47], v[166:169], v[182:185], v[44:47]
	v_mfma_f32_16x16x32_bf16 v[40:43], v[174:177], v[182:185], v[40:43]
	v_mfma_f32_16x16x32_bf16 v[28:31], v[166:169], v[190:193], v[28:31]
	v_mfma_f32_16x16x32_bf16 v[24:27], v[174:177], v[190:193], v[24:27]
	v_mfma_f32_16x16x32_bf16 v[12:15], v[166:169], v[198:201], v[12:15]
	v_mfma_f32_16x16x32_bf16 v[8:11], v[174:177], v[198:201], v[8:11]
	v_mfma_f32_16x16x32_bf16 v[4:7], v[166:169], v[206:209], v[4:7]
	v_mfma_f32_16x16x32_bf16 v[0:3], v[174:177], v[206:209], v[0:3]
	v_mfma_f32_16x16x32_bf16 v[44:47], v[170:173], v[186:189], v[44:47]
	v_mfma_f32_16x16x32_bf16 v[40:43], v[178:181], v[186:189], v[40:43]
	v_mfma_f32_16x16x32_bf16 v[28:31], v[170:173], v[194:197], v[28:31]
	v_mfma_f32_16x16x32_bf16 v[24:27], v[178:181], v[194:197], v[24:27]
	v_mfma_f32_16x16x32_bf16 v[12:15], v[170:173], v[202:205], v[12:15]
	v_mfma_f32_16x16x32_bf16 v[8:11], v[178:181], v[202:205], v[8:11]
	v_mfma_f32_16x16x32_bf16 v[4:7], v[170:173], v[210:213], v[4:7]
	v_mfma_f32_16x16x32_bf16 v[0:3], v[178:181], v[210:213], v[0:3]
	s_setprio 0
	s_barrier
	s_add_i32 s59, s59, 2
	s_add_u32 s57, s57, 0x100
	s_addc_u32 s58, s58, 0
	s_add_u32 s34, s34, 0x100
	s_addc_u32 s35, s35, 0
	s_cmp_gt_u32 s59, 13
	s_cbranch_scc0 .LBB0_729
	s_and_b64 vcc, exec, s[16:17]
	s_cbranch_vccz .LBB0_732
	s_barrier

.LBB0_877:
	ds_read_b128 v[152:155], v149
	ds_read_b128 v[156:159], v149 offset:1024
	ds_read_b128 v[160:163], v149 offset:2048
	ds_read_b128 v[164:167], v149 offset:3072
	ds_read_b128 v[168:171], v150
	ds_read_b128 v[172:175], v150 offset:1024
	ds_read_b128 v[176:179], v150 offset:2048
	ds_read_b128 v[180:183], v150 offset:3072
	s_add_u32 s26, s24, 0xfffc0080
	s_addc_u32 s27, s25, -1
	s_cmp_eq_u32 s49, 12
	s_cselect_b32 s29, s19, s27
	s_cselect_b32 s28, s45, s26
	s_cselect_b32 s27, s17, s48
	s_cselect_b32 s26, s46, s47
	v_lshl_add_u64 v[144:145], s[24:25], 0, v[138:139]
	s_add_i32 m0, s31, 0xc000
	ds_read_b128 v[184:187], v151
	ds_read_b128 v[188:191], v151 offset:1024
	ds_read_b128 v[192:195], v151 offset:2048
	ds_read_b128 v[196:199], v151 offset:3072
	ds_read_b128 v[200:203], v151 offset:4096
	ds_read_b128 v[204:207], v151 offset:5120
	ds_read_b128 v[208:211], v151 offset:6144
	ds_read_b128 v[212:215], v151 offset:7168
	global_load_lds_dwordx4 v[144:145], off
	v_lshl_add_u64 v[144:145], s[24:25], 0, v[136:137]
	s_add_i32 m0, s31, 0xe000
	s_nop 0
	global_load_lds_dwordx4 v[144:145], off
	s_waitcnt vmcnt(8)
	s_waitcnt lgkmcnt(0)
	s_barrier
	s_setprio 1
	s_waitcnt lgkmcnt(0)
	v_mfma_f32_16x16x32_bf16 v[124:127], v[152:155], v[184:187], v[124:127]
	v_mfma_f32_16x16x32_bf16 v[120:123], v[160:163], v[184:187], v[120:123]
	v_mfma_f32_16x16x32_bf16 v[108:111], v[152:155], v[192:195], v[108:111]
	v_mfma_f32_16x16x32_bf16 v[104:107], v[160:163], v[192:195], v[104:107]
	v_mfma_f32_16x16x32_bf16 v[92:95], v[152:155], v[200:203], v[92:95]
	v_mfma_f32_16x16x32_bf16 v[88:91], v[160:163], v[200:203], v[88:91]
	v_mfma_f32_16x16x32_bf16 v[76:79], v[152:155], v[208:211], v[76:79]
	v_mfma_f32_16x16x32_bf16 v[72:75], v[160:163], v[208:211], v[72:75]
	v_mfma_f32_16x16x32_bf16 v[124:127], v[156:159], v[188:191], v[124:127]
	v_mfma_f32_16x16x32_bf16 v[120:123], v[164:167], v[188:191], v[120:123]
	v_mfma_f32_16x16x32_bf16 v[108:111], v[156:159], v[196:199], v[108:111]
	v_mfma_f32_16x16x32_bf16 v[104:107], v[164:167], v[196:199], v[104:107]
	v_mfma_f32_16x16x32_bf16 v[92:95], v[156:159], v[204:207], v[92:95]
	v_mfma_f32_16x16x32_bf16 v[88:91], v[164:167], v[204:207], v[88:91]
	v_mfma_f32_16x16x32_bf16 v[76:79], v[156:159], v[212:215], v[76:79]
	v_mfma_f32_16x16x32_bf16 v[72:75], v[164:167], v[212:215], v[72:75]
	v_mfma_f32_16x16x32_bf16 v[116:119], v[168:171], v[184:187], v[116:119]
	v_mfma_f32_16x16x32_bf16 v[112:115], v[176:179], v[184:187], v[112:115]
	v_mfma_f32_16x16x32_bf16 v[100:103], v[168:171], v[192:195], v[100:103]
	v_mfma_f32_16x16x32_bf16 v[96:99], v[176:179], v[192:195], v[96:99]
	v_mfma_f32_16x16x32_bf16 v[84:87], v[168:171], v[200:203], v[84:87]
	v_mfma_f32_16x16x32_bf16 v[80:83], v[176:179], v[200:203], v[80:83]
	v_mfma_f32_16x16x32_bf16 v[68:71], v[168:171], v[208:211], v[68:71]
	v_mfma_f32_16x16x32_bf16 v[64:67], v[176:179], v[208:211], v[64:67]
	v_mfma_f32_16x16x32_bf16 v[116:119], v[172:175], v[188:191], v[116:119]
	v_mfma_f32_16x16x32_bf16 v[112:115], v[180:183], v[188:191], v[112:115]
	v_mfma_f32_16x16x32_bf16 v[100:103], v[172:175], v[196:199], v[100:103]
	v_mfma_f32_16x16x32_bf16 v[96:99], v[180:183], v[196:199], v[96:99]
	v_mfma_f32_16x16x32_bf16 v[84:87], v[172:175], v[204:207], v[84:87]
	v_mfma_f32_16x16x32_bf16 v[80:83], v[180:183], v[204:207], v[80:83]
	v_mfma_f32_16x16x32_bf16 v[68:71], v[172:175], v[212:215], v[68:71]
	v_mfma_f32_16x16x32_bf16 v[64:67], v[180:183], v[212:215], v[64:67]
	s_setprio 0
	s_barrier
	s_add_i32 s50, s40, s30
	v_lshl_add_u64 v[144:145], s[26:27], 0, v[132:133]
	s_mov_b32 m0, s50
	ds_read_b128 v[184:187], v151 offset:16384
	ds_read_b128 v[188:191], v151 offset:17408
	ds_read_b128 v[192:195], v151 offset:18432
	ds_read_b128 v[196:199], v151 offset:19456
	ds_read_b128 v[200:203], v151 offset:20480
	ds_read_b128 v[204:207], v151 offset:21504
	ds_read_b128 v[208:211], v151 offset:22528
	ds_read_b128 v[212:215], v151 offset:23552
	global_load_lds_dwordx4 v[144:145], off
	s_add_i32 m0, s50, 0x2000
	s_add_u32 s50, s26, 0x40000
	v_lshl_add_u64 v[216:217], s[26:27], 0, v[128:129]
	s_addc_u32 s51, s27, 0
	s_add_i32 s52, s41, s30
	global_load_lds_dwordx4 v[216:217], off
	v_lshl_add_u64 v[218:219], s[50:51], 0, v[132:133]
	s_mov_b32 m0, s52
	v_lshl_add_u64 v[220:221], s[28:29], 0, v[130:131]
	global_load_lds_dwordx4 v[218:219], off
	v_lshl_add_u64 v[218:219], s[50:51], 0, v[128:129]
	s_add_i32 m0, s52, 0x2000
	s_nop 0
	global_load_lds_dwordx4 v[218:219], off
	v_lshl_add_u64 v[218:219], s[28:29], 0, v[134:135]
	s_mov_b32 m0, s31
	s_nop 0
	global_load_lds_dwordx4 v[218:219], off
	s_mov_b32 m0, s33
	s_nop 0
	global_load_lds_dwordx4 v[220:221], off
	s_waitcnt vmcnt(8)
	s_waitcnt lgkmcnt(0)
	s_barrier
	s_setprio 1
	s_waitcnt lgkmcnt(0)
	v_mfma_f32_16x16x32_bf16 v[60:63], v[152:155], v[184:187], v[60:63]
	v_mfma_f32_16x16x32_bf16 v[56:59], v[160:163], v[184:187], v[56:59]
	v_mfma_f32_16x16x32_bf16 v[44:47], v[152:155], v[192:195], v[44:47]
	v_mfma_f32_16x16x32_bf16 v[40:43], v[160:163], v[192:195], v[40:43]
	v_mfma_f32_16x16x32_bf16 v[28:31], v[152:155], v[200:203], v[28:31]
	v_mfma_f32_16x16x32_bf16 v[24:27], v[160:163], v[200:203], v[24:27]
	v_mfma_f32_16x16x32_bf16 v[12:15], v[152:155], v[208:211], v[12:15]
	v_mfma_f32_16x16x32_bf16 v[8:11], v[160:163], v[208:211], v[8:11]
	v_mfma_f32_16x16x32_bf16 v[60:63], v[156:159], v[188:191], v[60:63]
	v_mfma_f32_16x16x32_bf16 v[56:59], v[164:167], v[188:191], v[56:59]
	v_mfma_f32_16x16x32_bf16 v[44:47], v[156:159], v[196:199], v[44:47]
	v_mfma_f32_16x16x32_bf16 v[40:43], v[164:167], v[196:199], v[40:43]
	v_mfma_f32_16x16x32_bf16 v[28:31], v[156:159], v[204:207], v[28:31]
	v_mfma_f32_16x16x32_bf16 v[24:27], v[164:167], v[204:207], v[24:27]
	v_mfma_f32_16x16x32_bf16 v[12:15], v[156:159], v[212:215], v[12:15]
	v_mfma_f32_16x16x32_bf16 v[8:11], v[164:167], v[212:215], v[8:11]
	v_mfma_f32_16x16x32_bf16 v[52:55], v[168:171], v[184:187], v[52:55]
	v_mfma_f32_16x16x32_bf16 v[48:51], v[176:179], v[184:187], v[48:51]
	v_mfma_f32_16x16x32_bf16 v[36:39], v[168:171], v[192:195], v[36:39]
	v_mfma_f32_16x16x32_bf16 v[32:35], v[176:179], v[192:195], v[32:35]
	v_mfma_f32_16x16x32_bf16 v[20:23], v[168:171], v[200:203], v[20:23]
	v_mfma_f32_16x16x32_bf16 v[16:19], v[176:179], v[200:203], v[16:19]
	v_mfma_f32_16x16x32_bf16 v[4:7], v[168:171], v[208:211], v[4:7]
	v_mfma_f32_16x16x32_bf16 v[0:3], v[176:179], v[208:211], v[0:3]
	v_mfma_f32_16x16x32_bf16 v[52:55], v[172:175], v[188:191], v[52:55]
	v_mfma_f32_16x16x32_bf16 v[48:51], v[180:183], v[188:191], v[48:51]
	v_mfma_f32_16x16x32_bf16 v[36:39], v[172:175], v[196:199], v[36:39]
	v_mfma_f32_16x16x32_bf16 v[32:35], v[180:183], v[196:199], v[32:35]
	v_mfma_f32_16x16x32_bf16 v[20:23], v[172:175], v[204:207], v[20:23]
	v_mfma_f32_16x16x32_bf16 v[16:19], v[180:183], v[204:207], v[16:19]
	v_mfma_f32_16x16x32_bf16 v[4:7], v[172:175], v[212:215], v[4:7]
	v_mfma_f32_16x16x32_bf16 v[0:3], v[180:183], v[212:215], v[0:3]
	s_setprio 0
	s_barrier
	s_add_i32 s50, 0, 0x18000
	s_add_i32 s51, 0, 0x1c000
	v_add_u32_e32 v164, s50, v147
	v_add_u32_e32 v180, s51, v147
	ds_read_b128 v[152:155], v164
	ds_read_b128 v[156:159], v164 offset:1024
	ds_read_b128 v[160:163], v164 offset:2048
	ds_read_b128 v[164:167], v164 offset:3072
	ds_read_b128 v[168:171], v180
	ds_read_b128 v[172:175], v180 offset:1024
	ds_read_b128 v[176:179], v180 offset:2048
	ds_read_b128 v[180:183], v180 offset:3072
	s_add_u32 s28, s28, 0x40000
	s_addc_u32 s29, s29, 0
	s_mov_b32 m0, s34
	v_lshl_add_u64 v[222:223], s[28:29], 0, v[134:135]
	ds_read_b128 v[184:187], v151 offset:32768
	ds_read_b128 v[188:191], v151 offset:33792
	ds_read_b128 v[192:195], v151 offset:34816
	ds_read_b128 v[196:199], v151 offset:35840
	ds_read_b128 v[200:203], v151 offset:36864
	ds_read_b128 v[204:207], v151 offset:37888
	ds_read_b128 v[208:211], v151 offset:38912
	ds_read_b128 v[212:215], v151 offset:39936
	global_load_lds_dwordx4 v[222:223], off
	v_lshl_add_u64 v[222:223], s[28:29], 0, v[130:131]
	s_mov_b32 m0, s35
	s_nop 0
	global_load_lds_dwordx4 v[222:223], off
	s_waitcnt vmcnt(8)
	s_waitcnt lgkmcnt(0)
	s_barrier
	s_setprio 1
	s_waitcnt lgkmcnt(0)
	v_mfma_f32_16x16x32_bf16 v[124:127], v[152:155], v[184:187], v[124:127]
	v_mfma_f32_16x16x32_bf16 v[120:123], v[160:163], v[184:187], v[120:123]
	v_mfma_f32_16x16x32_bf16 v[108:111], v[152:155], v[192:195], v[108:111]
	v_mfma_f32_16x16x32_bf16 v[104:107], v[160:163], v[192:195], v[104:107]
	v_mfma_f32_16x16x32_bf16 v[92:95], v[152:155], v[200:203], v[92:95]
	v_mfma_f32_16x16x32_bf16 v[88:91], v[160:163], v[200:203], v[88:91]
	v_mfma_f32_16x16x32_bf16 v[76:79], v[152:155], v[208:211], v[76:79]
	v_mfma_f32_16x16x32_bf16 v[72:75], v[160:163], v[208:211], v[72:75]
	v_mfma_f32_16x16x32_bf16 v[124:127], v[156:159], v[188:191], v[124:127]
	v_mfma_f32_16x16x32_bf16 v[120:123], v[164:167], v[188:191], v[120:123]
	v_mfma_f32_16x16x32_bf16 v[108:111], v[156:159], v[196:199], v[108:111]
	v_mfma_f32_16x16x32_bf16 v[104:107], v[164:167], v[196:199], v[104:107]
	v_mfma_f32_16x16x32_bf16 v[92:95], v[156:159], v[204:207], v[92:95]
	v_mfma_f32_16x16x32_bf16 v[88:91], v[164:167], v[204:207], v[88:91]
	v_mfma_f32_16x16x32_bf16 v[76:79], v[156:159], v[212:215], v[76:79]
	v_mfma_f32_16x16x32_bf16 v[72:75], v[164:167], v[212:215], v[72:75]
	v_mfma_f32_16x16x32_bf16 v[116:119], v[168:171], v[184:187], v[116:119]
	v_mfma_f32_16x16x32_bf16 v[112:115], v[176:179], v[184:187], v[112:115]
	v_mfma_f32_16x16x32_bf16 v[100:103], v[168:171], v[192:195], v[100:103]
	v_mfma_f32_16x16x32_bf16 v[96:99], v[176:179], v[192:195], v[96:99]
	v_mfma_f32_16x16x32_bf16 v[84:87], v[168:171], v[200:203], v[84:87]
	v_mfma_f32_16x16x32_bf16 v[80:83], v[176:179], v[200:203], v[80:83]
	v_mfma_f32_16x16x32_bf16 v[68:71], v[168:171], v[208:211], v[68:71]
	v_mfma_f32_16x16x32_bf16 v[64:67], v[176:179], v[208:211], v[64:67]
	v_mfma_f32_16x16x32_bf16 v[116:119], v[172:175], v[188:191], v[116:119]
	v_mfma_f32_16x16x32_bf16 v[112:115], v[180:183], v[188:191], v[112:115]
	v_mfma_f32_16x16x32_bf16 v[100:103], v[172:175], v[196:199], v[100:103]
	v_mfma_f32_16x16x32_bf16 v[96:99], v[180:183], v[196:199], v[96:99]
	v_mfma_f32_16x16x32_bf16 v[84:87], v[172:175], v[204:207], v[84:87]
	v_mfma_f32_16x16x32_bf16 v[80:83], v[180:183], v[204:207], v[80:83]
	v_mfma_f32_16x16x32_bf16 v[68:71], v[172:175], v[212:215], v[68:71]
	v_mfma_f32_16x16x32_bf16 v[64:67], v[180:183], v[212:215], v[64:67]
	s_setprio 0
	s_barrier
	s_add_i32 s28, s50, s30
	v_lshl_add_u64 v[144:145], v[144:145], 0, s[12:13]
	s_mov_b32 m0, s28
	ds_read_b128 v[184:187], v151 offset:49152
	ds_read_b128 v[188:191], v151 offset:50176
	ds_read_b128 v[192:195], v151 offset:51200
	ds_read_b128 v[196:199], v151 offset:52224
	ds_read_b128 v[200:203], v151 offset:53248
	ds_read_b128 v[204:207], v151 offset:54272
	ds_read_b128 v[208:211], v151 offset:55296
	ds_read_b128 v[212:215], v151 offset:56320
	global_load_lds_dwordx4 v[144:145], off
	s_add_i32 m0, s28, 0x2000
	s_add_u32 s26, s26, 0x40080
	v_lshl_add_u64 v[144:145], v[216:217], 0, s[12:13]
	s_addc_u32 s27, s27, 0
	s_add_i32 s28, s51, s30
	global_load_lds_dwordx4 v[144:145], off
	v_lshl_add_u64 v[144:145], s[26:27], 0, v[132:133]
	s_mov_b32 m0, s28
	s_nop 0
	global_load_lds_dwordx4 v[144:145], off
	v_lshl_add_u64 v[144:145], s[26:27], 0, v[128:129]
	s_add_i32 m0, s28, 0x2000
	s_nop 0
	global_load_lds_dwordx4 v[144:145], off
	v_lshl_add_u64 v[144:145], v[218:219], 0, s[12:13]
	s_mov_b32 m0, s37
	s_nop 0
	global_load_lds_dwordx4 v[144:145], off
	v_lshl_add_u64 v[144:145], v[220:221], 0, s[12:13]
	s_mov_b32 m0, s38
	s_nop 0
	global_load_lds_dwordx4 v[144:145], off
	s_waitcnt vmcnt(8)
	s_waitcnt lgkmcnt(0)
	s_barrier
	s_setprio 1
	s_waitcnt lgkmcnt(0)
	v_mfma_f32_16x16x32_bf16 v[60:63], v[152:155], v[184:187], v[60:63]
	v_mfma_f32_16x16x32_bf16 v[56:59], v[160:163], v[184:187], v[56:59]
	v_mfma_f32_16x16x32_bf16 v[44:47], v[152:155], v[192:195], v[44:47]
	v_mfma_f32_16x16x32_bf16 v[40:43], v[160:163], v[192:195], v[40:43]
	v_mfma_f32_16x16x32_bf16 v[28:31], v[152:155], v[200:203], v[28:31]
	v_mfma_f32_16x16x32_bf16 v[24:27], v[160:163], v[200:203], v[24:27]
	v_mfma_f32_16x16x32_bf16 v[12:15], v[152:155], v[208:211], v[12:15]
	v_mfma_f32_16x16x32_bf16 v[8:11], v[160:163], v[208:211], v[8:11]
	v_mfma_f32_16x16x32_bf16 v[60:63], v[156:159], v[188:191], v[60:63]
	v_mfma_f32_16x16x32_bf16 v[56:59], v[164:167], v[188:191], v[56:59]
	v_mfma_f32_16x16x32_bf16 v[44:47], v[156:159], v[196:199], v[44:47]
	v_mfma_f32_16x16x32_bf16 v[40:43], v[164:167], v[196:199], v[40:43]
	v_mfma_f32_16x16x32_bf16 v[28:31], v[156:159], v[204:207], v[28:31]
	v_mfma_f32_16x16x32_bf16 v[24:27], v[164:167], v[204:207], v[24:27]
	v_mfma_f32_16x16x32_bf16 v[12:15], v[156:159], v[212:215], v[12:15]
	v_mfma_f32_16x16x32_bf16 v[8:11], v[164:167], v[212:215], v[8:11]
	v_mfma_f32_16x16x32_bf16 v[52:55], v[168:171], v[184:187], v[52:55]
	v_mfma_f32_16x16x32_bf16 v[48:51], v[176:179], v[184:187], v[48:51]
	v_mfma_f32_16x16x32_bf16 v[36:39], v[168:171], v[192:195], v[36:39]
	v_mfma_f32_16x16x32_bf16 v[32:35], v[176:179], v[192:195], v[32:35]
	v_mfma_f32_16x16x32_bf16 v[20:23], v[168:171], v[200:203], v[20:23]
	v_mfma_f32_16x16x32_bf16 v[16:19], v[176:179], v[200:203], v[16:19]
	v_mfma_f32_16x16x32_bf16 v[4:7], v[168:171], v[208:211], v[4:7]
	v_mfma_f32_16x16x32_bf16 v[0:3], v[176:179], v[208:211], v[0:3]
	v_mfma_f32_16x16x32_bf16 v[52:55], v[172:175], v[188:191], v[52:55]
	v_mfma_f32_16x16x32_bf16 v[48:51], v[180:183], v[188:191], v[48:51]
	v_mfma_f32_16x16x32_bf16 v[36:39], v[172:175], v[196:199], v[36:39]
	v_mfma_f32_16x16x32_bf16 v[32:35], v[180:183], v[196:199], v[32:35]
	v_mfma_f32_16x16x32_bf16 v[20:23], v[172:175], v[204:207], v[20:23]
	v_mfma_f32_16x16x32_bf16 v[16:19], v[180:183], v[204:207], v[16:19]
	v_mfma_f32_16x16x32_bf16 v[4:7], v[172:175], v[212:215], v[4:7]
	v_mfma_f32_16x16x32_bf16 v[0:3], v[180:183], v[212:215], v[0:3]
	s_setprio 0
	s_barrier
	s_add_i32 s49, s49, 2
	s_add_u32 s47, s47, 0x100
	s_addc_u32 s48, s48, 0
	s_add_u32 s24, s24, 0x100
	s_addc_u32 s25, s25, 0
	s_cmp_gt_u32 s49, 13
	s_cbranch_scc0 .LBB0_877
	s_and_b64 vcc, exec, s[14:15]
	s_cbranch_vccz .LBB0_880
	s_barrier

.LBB0_949:
	ds_read_b128 v[150:153], v147
	ds_read_b128 v[154:157], v147 offset:1024
	ds_read_b128 v[158:161], v147 offset:2048
	ds_read_b128 v[162:165], v147 offset:3072
	ds_read_b128 v[166:169], v148
	ds_read_b128 v[170:173], v148 offset:1024
	ds_read_b128 v[174:177], v148 offset:2048
	ds_read_b128 v[178:181], v148 offset:3072
	s_add_u32 s34, s30, 0x100
	s_addc_u32 s35, s31, 0
	s_cmp_eq_u32 s59, 40
	s_cselect_b32 s39, s11, s35
	s_cselect_b32 s38, s10, s34
	s_cselect_b32 s37, s29, s58
	s_cselect_b32 s36, s28, s57
	v_lshl_add_u64 v[214:215], s[30:31], 0, v[138:139]
	s_add_i32 m0, s40, 0xc000
	ds_read_b128 v[182:185], v149
	ds_read_b128 v[186:189], v149 offset:1024
	ds_read_b128 v[190:193], v149 offset:2048
	ds_read_b128 v[194:197], v149 offset:3072
	ds_read_b128 v[198:201], v149 offset:4096
	ds_read_b128 v[202:205], v149 offset:5120
	ds_read_b128 v[206:209], v149 offset:6144
	ds_read_b128 v[210:213], v149 offset:7168
	global_load_lds_dwordx4 v[214:215], off
	v_lshl_add_u64 v[214:215], s[30:31], 0, v[136:137]
	s_add_i32 m0, s40, 0xe000
	s_nop 0
	global_load_lds_dwordx4 v[214:215], off
	s_waitcnt vmcnt(8)
	s_waitcnt lgkmcnt(0)
	s_barrier
	s_setprio 1
	s_waitcnt lgkmcnt(0)
	v_mfma_f32_16x16x32_bf16 v[124:127], v[150:153], v[182:185], v[124:127]
	v_mfma_f32_16x16x32_bf16 v[120:123], v[158:161], v[182:185], v[120:123]
	v_mfma_f32_16x16x32_bf16 v[116:119], v[150:153], v[190:193], v[116:119]
	v_mfma_f32_16x16x32_bf16 v[112:115], v[158:161], v[190:193], v[112:115]
	v_mfma_f32_16x16x32_bf16 v[100:103], v[150:153], v[198:201], v[100:103]
	v_mfma_f32_16x16x32_bf16 v[96:99], v[158:161], v[198:201], v[96:99]
	v_mfma_f32_16x16x32_bf16 v[84:87], v[150:153], v[206:209], v[84:87]
	v_mfma_f32_16x16x32_bf16 v[80:83], v[158:161], v[206:209], v[80:83]
	v_mfma_f32_16x16x32_bf16 v[124:127], v[154:157], v[186:189], v[124:127]
	v_mfma_f32_16x16x32_bf16 v[120:123], v[162:165], v[186:189], v[120:123]
	v_mfma_f32_16x16x32_bf16 v[116:119], v[154:157], v[194:197], v[116:119]
	v_mfma_f32_16x16x32_bf16 v[112:115], v[162:165], v[194:197], v[112:115]
	v_mfma_f32_16x16x32_bf16 v[100:103], v[154:157], v[202:205], v[100:103]
	v_mfma_f32_16x16x32_bf16 v[96:99], v[162:165], v[202:205], v[96:99]
	v_mfma_f32_16x16x32_bf16 v[84:87], v[154:157], v[210:213], v[84:87]
	v_mfma_f32_16x16x32_bf16 v[80:83], v[162:165], v[210:213], v[80:83]
	v_mfma_f32_16x16x32_bf16 v[108:111], v[166:169], v[182:185], v[108:111]
	v_mfma_f32_16x16x32_bf16 v[104:107], v[174:177], v[182:185], v[104:107]
	v_mfma_f32_16x16x32_bf16 v[92:95], v[166:169], v[190:193], v[92:95]
	v_mfma_f32_16x16x32_bf16 v[88:91], v[174:177], v[190:193], v[88:91]
	v_mfma_f32_16x16x32_bf16 v[76:79], v[166:169], v[198:201], v[76:79]
	v_mfma_f32_16x16x32_bf16 v[72:75], v[174:177], v[198:201], v[72:75]
	v_mfma_f32_16x16x32_bf16 v[68:71], v[166:169], v[206:209], v[68:71]
	v_mfma_f32_16x16x32_bf16 v[64:67], v[174:177], v[206:209], v[64:67]
	v_mfma_f32_16x16x32_bf16 v[108:111], v[170:173], v[186:189], v[108:111]
	v_mfma_f32_16x16x32_bf16 v[104:107], v[178:181], v[186:189], v[104:107]
	v_mfma_f32_16x16x32_bf16 v[92:95], v[170:173], v[194:197], v[92:95]
	v_mfma_f32_16x16x32_bf16 v[88:91], v[178:181], v[194:197], v[88:91]
	v_mfma_f32_16x16x32_bf16 v[76:79], v[170:173], v[202:205], v[76:79]
	v_mfma_f32_16x16x32_bf16 v[72:75], v[178:181], v[202:205], v[72:75]
	v_mfma_f32_16x16x32_bf16 v[68:71], v[170:173], v[210:213], v[68:71]
	v_mfma_f32_16x16x32_bf16 v[64:67], v[178:181], v[210:213], v[64:67]
	s_setprio 0
	s_barrier
	s_add_i32 s30, s47, s33
	v_lshl_add_u64 v[214:215], s[36:37], 0, v[132:133]
	s_mov_b32 m0, s30
	ds_read_b128 v[182:185], v149 offset:16384
	ds_read_b128 v[186:189], v149 offset:17408
	ds_read_b128 v[190:193], v149 offset:18432
	ds_read_b128 v[194:197], v149 offset:19456
	ds_read_b128 v[198:201], v149 offset:20480
	ds_read_b128 v[202:205], v149 offset:21504
	ds_read_b128 v[206:209], v149 offset:22528
	ds_read_b128 v[210:213], v149 offset:23552
	global_load_lds_dwordx4 v[214:215], off
	s_add_i32 m0, s30, 0x2000
	s_add_u32 s30, s36, 0xb0000
	v_lshl_add_u64 v[216:217], s[36:37], 0, v[128:129]
	s_addc_u32 s31, s37, 0
	s_add_i32 s60, s48, s33
	global_load_lds_dwordx4 v[216:217], off
	v_lshl_add_u64 v[218:219], s[30:31], 0, v[132:133]
	s_mov_b32 m0, s60
	v_lshl_add_u64 v[220:221], s[38:39], 0, v[130:131]
	global_load_lds_dwordx4 v[218:219], off
	v_lshl_add_u64 v[218:219], s[30:31], 0, v[128:129]
	s_add_i32 m0, s60, 0x2000
	s_nop 0
	global_load_lds_dwordx4 v[218:219], off
	v_lshl_add_u64 v[218:219], s[38:39], 0, v[134:135]
	s_mov_b32 m0, s40
	s_nop 0
	global_load_lds_dwordx4 v[218:219], off
	s_mov_b32 m0, s41
	s_nop 0
	global_load_lds_dwordx4 v[220:221], off
	s_waitcnt vmcnt(8)
	s_waitcnt lgkmcnt(0)
	s_barrier
	s_setprio 1
	s_waitcnt lgkmcnt(0)
	v_mfma_f32_16x16x32_bf16 v[60:63], v[150:153], v[182:185], v[60:63]
	v_mfma_f32_16x16x32_bf16 v[56:59], v[158:161], v[182:185], v[56:59]
	v_mfma_f32_16x16x32_bf16 v[52:55], v[150:153], v[190:193], v[52:55]
	v_mfma_f32_16x16x32_bf16 v[48:51], v[158:161], v[190:193], v[48:51]
	v_mfma_f32_16x16x32_bf16 v[36:39], v[150:153], v[198:201], v[36:39]
	v_mfma_f32_16x16x32_bf16 v[32:35], v[158:161], v[198:201], v[32:35]
	v_mfma_f32_16x16x32_bf16 v[20:23], v[150:153], v[206:209], v[20:23]
	v_mfma_f32_16x16x32_bf16 v[16:19], v[158:161], v[206:209], v[16:19]
	v_mfma_f32_16x16x32_bf16 v[60:63], v[154:157], v[186:189], v[60:63]
	v_mfma_f32_16x16x32_bf16 v[56:59], v[162:165], v[186:189], v[56:59]
	v_mfma_f32_16x16x32_bf16 v[52:55], v[154:157], v[194:197], v[52:55]
	v_mfma_f32_16x16x32_bf16 v[48:51], v[162:165], v[194:197], v[48:51]
	v_mfma_f32_16x16x32_bf16 v[36:39], v[154:157], v[202:205], v[36:39]
	v_mfma_f32_16x16x32_bf16 v[32:35], v[162:165], v[202:205], v[32:35]
	v_mfma_f32_16x16x32_bf16 v[20:23], v[154:157], v[210:213], v[20:23]
	v_mfma_f32_16x16x32_bf16 v[16:19], v[162:165], v[210:213], v[16:19]
	v_mfma_f32_16x16x32_bf16 v[44:47], v[166:169], v[182:185], v[44:47]
	v_mfma_f32_16x16x32_bf16 v[40:43], v[174:177], v[182:185], v[40:43]
	v_mfma_f32_16x16x32_bf16 v[28:31], v[166:169], v[190:193], v[28:31]
	v_mfma_f32_16x16x32_bf16 v[24:27], v[174:177], v[190:193], v[24:27]
	v_mfma_f32_16x16x32_bf16 v[12:15], v[166:169], v[198:201], v[12:15]
	v_mfma_f32_16x16x32_bf16 v[8:11], v[174:177], v[198:201], v[8:11]
	v_mfma_f32_16x16x32_bf16 v[4:7], v[166:169], v[206:209], v[4:7]
	v_mfma_f32_16x16x32_bf16 v[0:3], v[174:177], v[206:209], v[0:3]
	v_mfma_f32_16x16x32_bf16 v[44:47], v[170:173], v[186:189], v[44:47]
	v_mfma_f32_16x16x32_bf16 v[40:43], v[178:181], v[186:189], v[40:43]
	v_mfma_f32_16x16x32_bf16 v[28:31], v[170:173], v[194:197], v[28:31]
	v_mfma_f32_16x16x32_bf16 v[24:27], v[178:181], v[194:197], v[24:27]
	v_mfma_f32_16x16x32_bf16 v[12:15], v[170:173], v[202:205], v[12:15]
	v_mfma_f32_16x16x32_bf16 v[8:11], v[178:181], v[202:205], v[8:11]
	v_mfma_f32_16x16x32_bf16 v[4:7], v[170:173], v[210:213], v[4:7]
	v_mfma_f32_16x16x32_bf16 v[0:3], v[178:181], v[210:213], v[0:3]
	s_setprio 0
	s_barrier
	s_add_i32 s60, 0, 0x18000
	s_add_i32 s61, 0, 0x1c000
	v_add_u32_e32 v162, s60, v145
	v_add_u32_e32 v178, s61, v145
	ds_read_b128 v[150:153], v162
	ds_read_b128 v[154:157], v162 offset:1024
	ds_read_b128 v[158:161], v162 offset:2048
	ds_read_b128 v[162:165], v162 offset:3072
	ds_read_b128 v[166:169], v178
	ds_read_b128 v[170:173], v178 offset:1024
	ds_read_b128 v[174:177], v178 offset:2048
	ds_read_b128 v[178:181], v178 offset:3072
	s_add_u32 s30, s38, 0xb0000
	s_addc_u32 s31, s39, 0
	s_mov_b32 m0, s42
	v_lshl_add_u64 v[222:223], s[30:31], 0, v[134:135]
	ds_read_b128 v[182:185], v149 offset:32768
	ds_read_b128 v[186:189], v149 offset:33792
	ds_read_b128 v[190:193], v149 offset:34816
	ds_read_b128 v[194:197], v149 offset:35840
	ds_read_b128 v[198:201], v149 offset:36864
	ds_read_b128 v[202:205], v149 offset:37888
	ds_read_b128 v[206:209], v149 offset:38912
	ds_read_b128 v[210:213], v149 offset:39936
	global_load_lds_dwordx4 v[222:223], off
	v_lshl_add_u64 v[222:223], s[30:31], 0, v[130:131]
	s_mov_b32 m0, s43
	s_nop 0
	global_load_lds_dwordx4 v[222:223], off
	s_waitcnt vmcnt(8)
	s_waitcnt lgkmcnt(0)
	s_barrier
	s_setprio 1
	s_waitcnt lgkmcnt(0)
	v_mfma_f32_16x16x32_bf16 v[124:127], v[150:153], v[182:185], v[124:127]
	v_mfma_f32_16x16x32_bf16 v[120:123], v[158:161], v[182:185], v[120:123]
	v_mfma_f32_16x16x32_bf16 v[116:119], v[150:153], v[190:193], v[116:119]
	v_mfma_f32_16x16x32_bf16 v[112:115], v[158:161], v[190:193], v[112:115]
	v_mfma_f32_16x16x32_bf16 v[100:103], v[150:153], v[198:201], v[100:103]
	v_mfma_f32_16x16x32_bf16 v[96:99], v[158:161], v[198:201], v[96:99]
	v_mfma_f32_16x16x32_bf16 v[84:87], v[150:153], v[206:209], v[84:87]
	v_mfma_f32_16x16x32_bf16 v[80:83], v[158:161], v[206:209], v[80:83]
	v_mfma_f32_16x16x32_bf16 v[124:127], v[154:157], v[186:189], v[124:127]
	v_mfma_f32_16x16x32_bf16 v[120:123], v[162:165], v[186:189], v[120:123]
	v_mfma_f32_16x16x32_bf16 v[116:119], v[154:157], v[194:197], v[116:119]
	v_mfma_f32_16x16x32_bf16 v[112:115], v[162:165], v[194:197], v[112:115]
	v_mfma_f32_16x16x32_bf16 v[100:103], v[154:157], v[202:205], v[100:103]
	v_mfma_f32_16x16x32_bf16 v[96:99], v[162:165], v[202:205], v[96:99]
	v_mfma_f32_16x16x32_bf16 v[84:87], v[154:157], v[210:213], v[84:87]
	v_mfma_f32_16x16x32_bf16 v[80:83], v[162:165], v[210:213], v[80:83]
	v_mfma_f32_16x16x32_bf16 v[108:111], v[166:169], v[182:185], v[108:111]
	v_mfma_f32_16x16x32_bf16 v[104:107], v[174:177], v[182:185], v[104:107]
	v_mfma_f32_16x16x32_bf16 v[92:95], v[166:169], v[190:193], v[92:95]
	v_mfma_f32_16x16x32_bf16 v[88:91], v[174:177], v[190:193], v[88:91]
	v_mfma_f32_16x16x32_bf16 v[76:79], v[166:169], v[198:201], v[76:79]
	v_mfma_f32_16x16x32_bf16 v[72:75], v[174:177], v[198:201], v[72:75]
	v_mfma_f32_16x16x32_bf16 v[68:71], v[166:169], v[206:209], v[68:71]
	v_mfma_f32_16x16x32_bf16 v[64:67], v[174:177], v[206:209], v[64:67]
	v_mfma_f32_16x16x32_bf16 v[108:111], v[170:173], v[186:189], v[108:111]
	v_mfma_f32_16x16x32_bf16 v[104:107], v[178:181], v[186:189], v[104:107]
	v_mfma_f32_16x16x32_bf16 v[92:95], v[170:173], v[194:197], v[92:95]
	v_mfma_f32_16x16x32_bf16 v[88:91], v[178:181], v[194:197], v[88:91]
	v_mfma_f32_16x16x32_bf16 v[76:79], v[170:173], v[202:205], v[76:79]
	v_mfma_f32_16x16x32_bf16 v[72:75], v[178:181], v[202:205], v[72:75]
	v_mfma_f32_16x16x32_bf16 v[68:71], v[170:173], v[210:213], v[68:71]
	v_mfma_f32_16x16x32_bf16 v[64:67], v[178:181], v[210:213], v[64:67]
	s_setprio 0
	s_barrier
	s_add_i32 s30, s60, s33
	v_lshl_add_u64 v[214:215], v[214:215], 0, s[16:17]
	s_mov_b32 m0, s30
	ds_read_b128 v[182:185], v149 offset:49152
	ds_read_b128 v[186:189], v149 offset:50176
	ds_read_b128 v[190:193], v149 offset:51200
	ds_read_b128 v[194:197], v149 offset:52224
	ds_read_b128 v[198:201], v149 offset:53248
	ds_read_b128 v[202:205], v149 offset:54272
	ds_read_b128 v[206:209], v149 offset:55296
	ds_read_b128 v[210:213], v149 offset:56320
	global_load_lds_dwordx4 v[214:215], off
	s_add_i32 m0, s30, 0x2000
	s_add_u32 s30, s36, 0xb0080
	v_lshl_add_u64 v[214:215], v[216:217], 0, s[16:17]
	s_addc_u32 s31, s37, 0
	s_add_i32 s36, s61, s33
	global_load_lds_dwordx4 v[214:215], off
	v_lshl_add_u64 v[214:215], s[30:31], 0, v[132:133]
	s_mov_b32 m0, s36
	s_nop 0
	global_load_lds_dwordx4 v[214:215], off
	v_lshl_add_u64 v[214:215], s[30:31], 0, v[128:129]
	s_add_i32 m0, s36, 0x2000
	s_nop 0
	global_load_lds_dwordx4 v[214:215], off
	v_lshl_add_u64 v[214:215], v[218:219], 0, s[16:17]
	s_mov_b32 m0, s45
	s_nop 0
	global_load_lds_dwordx4 v[214:215], off
	v_lshl_add_u64 v[214:215], v[220:221], 0, s[16:17]
	s_mov_b32 m0, s46
	s_nop 0
	global_load_lds_dwordx4 v[214:215], off
	s_waitcnt vmcnt(8)
	s_waitcnt lgkmcnt(0)
	s_barrier
	s_setprio 1
	s_waitcnt lgkmcnt(0)
	v_mfma_f32_16x16x32_bf16 v[60:63], v[150:153], v[182:185], v[60:63]
	v_mfma_f32_16x16x32_bf16 v[56:59], v[158:161], v[182:185], v[56:59]
	v_mfma_f32_16x16x32_bf16 v[52:55], v[150:153], v[190:193], v[52:55]
	v_mfma_f32_16x16x32_bf16 v[48:51], v[158:161], v[190:193], v[48:51]
	v_mfma_f32_16x16x32_bf16 v[36:39], v[150:153], v[198:201], v[36:39]
	v_mfma_f32_16x16x32_bf16 v[32:35], v[158:161], v[198:201], v[32:35]
	v_mfma_f32_16x16x32_bf16 v[20:23], v[150:153], v[206:209], v[20:23]
	v_mfma_f32_16x16x32_bf16 v[16:19], v[158:161], v[206:209], v[16:19]
	v_mfma_f32_16x16x32_bf16 v[60:63], v[154:157], v[186:189], v[60:63]
	v_mfma_f32_16x16x32_bf16 v[56:59], v[162:165], v[186:189], v[56:59]
	v_mfma_f32_16x16x32_bf16 v[52:55], v[154:157], v[194:197], v[52:55]
	v_mfma_f32_16x16x32_bf16 v[48:51], v[162:165], v[194:197], v[48:51]
	v_mfma_f32_16x16x32_bf16 v[36:39], v[154:157], v[202:205], v[36:39]
	v_mfma_f32_16x16x32_bf16 v[32:35], v[162:165], v[202:205], v[32:35]
	v_mfma_f32_16x16x32_bf16 v[20:23], v[154:157], v[210:213], v[20:23]
	v_mfma_f32_16x16x32_bf16 v[16:19], v[162:165], v[210:213], v[16:19]
	v_mfma_f32_16x16x32_bf16 v[44:47], v[166:169], v[182:185], v[44:47]
	v_mfma_f32_16x16x32_bf16 v[40:43], v[174:177], v[182:185], v[40:43]
	v_mfma_f32_16x16x32_bf16 v[28:31], v[166:169], v[190:193], v[28:31]
	v_mfma_f32_16x16x32_bf16 v[24:27], v[174:177], v[190:193], v[24:27]
	v_mfma_f32_16x16x32_bf16 v[12:15], v[166:169], v[198:201], v[12:15]
	v_mfma_f32_16x16x32_bf16 v[8:11], v[174:177], v[198:201], v[8:11]
	v_mfma_f32_16x16x32_bf16 v[4:7], v[166:169], v[206:209], v[4:7]
	v_mfma_f32_16x16x32_bf16 v[0:3], v[174:177], v[206:209], v[0:3]
	v_mfma_f32_16x16x32_bf16 v[44:47], v[170:173], v[186:189], v[44:47]
	v_mfma_f32_16x16x32_bf16 v[40:43], v[178:181], v[186:189], v[40:43]
	v_mfma_f32_16x16x32_bf16 v[28:31], v[170:173], v[194:197], v[28:31]
	v_mfma_f32_16x16x32_bf16 v[24:27], v[178:181], v[194:197], v[24:27]
	v_mfma_f32_16x16x32_bf16 v[12:15], v[170:173], v[202:205], v[12:15]
	v_mfma_f32_16x16x32_bf16 v[8:11], v[178:181], v[202:205], v[8:11]
	v_mfma_f32_16x16x32_bf16 v[4:7], v[170:173], v[210:213], v[4:7]
	v_mfma_f32_16x16x32_bf16 v[0:3], v[178:181], v[210:213], v[0:3]
	s_setprio 0
	s_barrier
	s_add_i32 s59, s59, 2
	s_add_u32 s57, s57, 0x100
	s_addc_u32 s58, s58, 0
	s_cmp_gt_u32 s59, 41
	s_mov_b64 s[30:31], s[34:35]
	s_cbranch_scc0 .LBB0_949
	s_and_b64 vcc, exec, s[18:19]
	s_cbranch_vccz .LBB0_952
	s_barrier

.LBB0_1111:
	ds_read_b128 v[144:147], v153
	ds_read_b128 v[156:159], v153 offset:1024
	ds_read_b128 v[160:163], v153 offset:2048
	ds_read_b128 v[164:167], v153 offset:3072
	ds_read_b128 v[168:171], v154
	ds_read_b128 v[172:175], v154 offset:1024
	ds_read_b128 v[176:179], v154 offset:2048
	ds_read_b128 v[180:183], v154 offset:3072
	s_add_u32 s42, s40, 0xfffc0080
	s_addc_u32 s43, s41, -1
	s_cmp_eq_u32 s63, 12
	s_cselect_b32 s45, s31, s43
	s_cselect_b32 s44, s59, s42
	s_cselect_b32 s43, s29, s62
	s_cselect_b32 s42, s60, s61
	v_lshl_add_u64 v[148:149], s[40:41], 0, v[138:139]
	s_add_i32 m0, s39, 0xc000
	ds_read_b128 v[184:187], v155
	ds_read_b128 v[188:191], v155 offset:1024
	ds_read_b128 v[192:195], v155 offset:2048
	ds_read_b128 v[196:199], v155 offset:3072
	ds_read_b128 v[200:203], v155 offset:4096
	ds_read_b128 v[204:207], v155 offset:5120
	ds_read_b128 v[208:211], v155 offset:6144
	ds_read_b128 v[212:215], v155 offset:7168
	global_load_lds_dwordx4 v[148:149], off
	v_lshl_add_u64 v[148:149], s[40:41], 0, v[136:137]
	s_add_i32 m0, s39, 0xe000
	s_nop 0
	global_load_lds_dwordx4 v[148:149], off
	s_waitcnt vmcnt(8)
	s_waitcnt lgkmcnt(0)
	s_barrier
	s_setprio 1
	s_waitcnt lgkmcnt(0)
	v_mfma_f32_16x16x32_bf16 v[124:127], v[144:147], v[184:187], v[124:127]
	v_mfma_f32_16x16x32_bf16 v[120:123], v[160:163], v[184:187], v[120:123]
	v_mfma_f32_16x16x32_bf16 v[108:111], v[144:147], v[192:195], v[108:111]
	v_mfma_f32_16x16x32_bf16 v[104:107], v[160:163], v[192:195], v[104:107]
	v_mfma_f32_16x16x32_bf16 v[92:95], v[144:147], v[200:203], v[92:95]
	v_mfma_f32_16x16x32_bf16 v[88:91], v[160:163], v[200:203], v[88:91]
	v_mfma_f32_16x16x32_bf16 v[76:79], v[144:147], v[208:211], v[76:79]
	v_mfma_f32_16x16x32_bf16 v[72:75], v[160:163], v[208:211], v[72:75]
	v_mfma_f32_16x16x32_bf16 v[124:127], v[156:159], v[188:191], v[124:127]
	v_mfma_f32_16x16x32_bf16 v[120:123], v[164:167], v[188:191], v[120:123]
	v_mfma_f32_16x16x32_bf16 v[108:111], v[156:159], v[196:199], v[108:111]
	v_mfma_f32_16x16x32_bf16 v[104:107], v[164:167], v[196:199], v[104:107]
	v_mfma_f32_16x16x32_bf16 v[92:95], v[156:159], v[204:207], v[92:95]
	v_mfma_f32_16x16x32_bf16 v[88:91], v[164:167], v[204:207], v[88:91]
	v_mfma_f32_16x16x32_bf16 v[76:79], v[156:159], v[212:215], v[76:79]
	v_mfma_f32_16x16x32_bf16 v[72:75], v[164:167], v[212:215], v[72:75]
	v_mfma_f32_16x16x32_bf16 v[116:119], v[168:171], v[184:187], v[116:119]
	v_mfma_f32_16x16x32_bf16 v[112:115], v[176:179], v[184:187], v[112:115]
	v_mfma_f32_16x16x32_bf16 v[100:103], v[168:171], v[192:195], v[100:103]
	v_mfma_f32_16x16x32_bf16 v[96:99], v[176:179], v[192:195], v[96:99]
	v_mfma_f32_16x16x32_bf16 v[84:87], v[168:171], v[200:203], v[84:87]
	v_mfma_f32_16x16x32_bf16 v[80:83], v[176:179], v[200:203], v[80:83]
	v_mfma_f32_16x16x32_bf16 v[68:71], v[168:171], v[208:211], v[68:71]
	v_mfma_f32_16x16x32_bf16 v[64:67], v[176:179], v[208:211], v[64:67]
	v_mfma_f32_16x16x32_bf16 v[116:119], v[172:175], v[188:191], v[116:119]
	v_mfma_f32_16x16x32_bf16 v[112:115], v[180:183], v[188:191], v[112:115]
	v_mfma_f32_16x16x32_bf16 v[100:103], v[172:175], v[196:199], v[100:103]
	v_mfma_f32_16x16x32_bf16 v[96:99], v[180:183], v[196:199], v[96:99]
	v_mfma_f32_16x16x32_bf16 v[84:87], v[172:175], v[204:207], v[84:87]
	v_mfma_f32_16x16x32_bf16 v[80:83], v[180:183], v[204:207], v[80:83]
	v_mfma_f32_16x16x32_bf16 v[68:71], v[172:175], v[212:215], v[68:71]
	v_mfma_f32_16x16x32_bf16 v[64:67], v[180:183], v[212:215], v[64:67]
	s_setprio 0
	s_barrier
	s_add_i32 s64, s52, s33
	v_lshl_add_u64 v[148:149], s[42:43], 0, v[130:131]
	s_mov_b32 m0, s64
	ds_read_b128 v[184:187], v155 offset:16384
	ds_read_b128 v[188:191], v155 offset:17408
	ds_read_b128 v[192:195], v155 offset:18432
	ds_read_b128 v[196:199], v155 offset:19456
	ds_read_b128 v[200:203], v155 offset:20480
	ds_read_b128 v[204:207], v155 offset:21504
	ds_read_b128 v[208:211], v155 offset:22528
	ds_read_b128 v[212:215], v155 offset:23552
	global_load_lds_dwordx4 v[148:149], off
	s_add_i32 m0, s64, 0x2000
	s_add_u32 s64, s42, 0x40000
	v_lshl_add_u64 v[216:217], s[42:43], 0, v[134:135]
	s_addc_u32 s65, s43, 0
	s_add_i32 s66, s53, s33
	global_load_lds_dwordx4 v[216:217], off
	v_lshl_add_u64 v[218:219], s[64:65], 0, v[130:131]
	s_mov_b32 m0, s66
	v_lshl_add_u64 v[220:221], s[44:45], 0, v[132:133]
	global_load_lds_dwordx4 v[218:219], off
	v_lshl_add_u64 v[218:219], s[64:65], 0, v[134:135]
	s_add_i32 m0, s66, 0x2000
	s_nop 0
	global_load_lds_dwordx4 v[218:219], off
	v_lshl_add_u64 v[218:219], s[44:45], 0, v[128:129]
	s_mov_b32 m0, s39
	s_nop 0
	global_load_lds_dwordx4 v[218:219], off
	s_mov_b32 m0, s46
	s_nop 0
	global_load_lds_dwordx4 v[220:221], off
	s_waitcnt vmcnt(8)
	s_waitcnt lgkmcnt(0)
	s_barrier
	s_setprio 1
	s_waitcnt lgkmcnt(0)
	v_mfma_f32_16x16x32_bf16 v[60:63], v[144:147], v[184:187], v[60:63]
	v_mfma_f32_16x16x32_bf16 v[56:59], v[160:163], v[184:187], v[56:59]
	v_mfma_f32_16x16x32_bf16 v[44:47], v[144:147], v[192:195], v[44:47]
	v_mfma_f32_16x16x32_bf16 v[40:43], v[160:163], v[192:195], v[40:43]
	v_mfma_f32_16x16x32_bf16 v[28:31], v[144:147], v[200:203], v[28:31]
	v_mfma_f32_16x16x32_bf16 v[24:27], v[160:163], v[200:203], v[24:27]
	v_mfma_f32_16x16x32_bf16 v[12:15], v[144:147], v[208:211], v[12:15]
	v_mfma_f32_16x16x32_bf16 v[8:11], v[160:163], v[208:211], v[8:11]
	v_mfma_f32_16x16x32_bf16 v[60:63], v[156:159], v[188:191], v[60:63]
	v_mfma_f32_16x16x32_bf16 v[56:59], v[164:167], v[188:191], v[56:59]
	v_mfma_f32_16x16x32_bf16 v[44:47], v[156:159], v[196:199], v[44:47]
	v_mfma_f32_16x16x32_bf16 v[40:43], v[164:167], v[196:199], v[40:43]
	v_mfma_f32_16x16x32_bf16 v[28:31], v[156:159], v[204:207], v[28:31]
	v_mfma_f32_16x16x32_bf16 v[24:27], v[164:167], v[204:207], v[24:27]
	v_mfma_f32_16x16x32_bf16 v[12:15], v[156:159], v[212:215], v[12:15]
	v_mfma_f32_16x16x32_bf16 v[8:11], v[164:167], v[212:215], v[8:11]
	v_mfma_f32_16x16x32_bf16 v[52:55], v[168:171], v[184:187], v[52:55]
	v_mfma_f32_16x16x32_bf16 v[48:51], v[176:179], v[184:187], v[48:51]
	v_mfma_f32_16x16x32_bf16 v[36:39], v[168:171], v[192:195], v[36:39]
	v_mfma_f32_16x16x32_bf16 v[32:35], v[176:179], v[192:195], v[32:35]
	v_mfma_f32_16x16x32_bf16 v[20:23], v[168:171], v[200:203], v[20:23]
	v_mfma_f32_16x16x32_bf16 v[16:19], v[176:179], v[200:203], v[16:19]
	v_mfma_f32_16x16x32_bf16 v[4:7], v[168:171], v[208:211], v[4:7]
	v_mfma_f32_16x16x32_bf16 v[0:3], v[176:179], v[208:211], v[0:3]
	v_mfma_f32_16x16x32_bf16 v[52:55], v[172:175], v[188:191], v[52:55]
	v_mfma_f32_16x16x32_bf16 v[48:51], v[180:183], v[188:191], v[48:51]
	v_mfma_f32_16x16x32_bf16 v[36:39], v[172:175], v[196:199], v[36:39]
	v_mfma_f32_16x16x32_bf16 v[32:35], v[180:183], v[196:199], v[32:35]
	v_mfma_f32_16x16x32_bf16 v[20:23], v[172:175], v[204:207], v[20:23]
	v_mfma_f32_16x16x32_bf16 v[16:19], v[180:183], v[204:207], v[16:19]
	v_mfma_f32_16x16x32_bf16 v[4:7], v[172:175], v[212:215], v[4:7]
	v_mfma_f32_16x16x32_bf16 v[0:3], v[180:183], v[212:215], v[0:3]
	s_setprio 0
	s_barrier
	s_add_i32 s64, 0, 0x18000
	s_add_i32 s65, 0, 0x1c000
	v_add_u32_e32 v164, s64, v151
	v_add_u32_e32 v180, s65, v151
	ds_read_b128 v[144:147], v164
	ds_read_b128 v[156:159], v164 offset:1024
	ds_read_b128 v[160:163], v164 offset:2048
	ds_read_b128 v[164:167], v164 offset:3072
	ds_read_b128 v[168:171], v180
	ds_read_b128 v[172:175], v180 offset:1024
	ds_read_b128 v[176:179], v180 offset:2048
	ds_read_b128 v[180:183], v180 offset:3072
	s_add_u32 s44, s44, 0x40000
	s_addc_u32 s45, s45, 0
	s_mov_b32 m0, s47
	v_lshl_add_u64 v[222:223], s[44:45], 0, v[128:129]
	ds_read_b128 v[184:187], v155 offset:32768
	ds_read_b128 v[188:191], v155 offset:33792
	ds_read_b128 v[192:195], v155 offset:34816
	ds_read_b128 v[196:199], v155 offset:35840
	ds_read_b128 v[200:203], v155 offset:36864
	ds_read_b128 v[204:207], v155 offset:37888
	ds_read_b128 v[208:211], v155 offset:38912
	ds_read_b128 v[212:215], v155 offset:39936
	global_load_lds_dwordx4 v[222:223], off
	v_lshl_add_u64 v[222:223], s[44:45], 0, v[132:133]
	s_mov_b32 m0, s48
	s_nop 0
	global_load_lds_dwordx4 v[222:223], off
	s_waitcnt vmcnt(8)
	s_waitcnt lgkmcnt(0)
	s_barrier
	s_setprio 1
	s_waitcnt lgkmcnt(0)
	v_mfma_f32_16x16x32_bf16 v[124:127], v[144:147], v[184:187], v[124:127]
	v_mfma_f32_16x16x32_bf16 v[120:123], v[160:163], v[184:187], v[120:123]
	v_mfma_f32_16x16x32_bf16 v[108:111], v[144:147], v[192:195], v[108:111]
	v_mfma_f32_16x16x32_bf16 v[104:107], v[160:163], v[192:195], v[104:107]
	v_mfma_f32_16x16x32_bf16 v[92:95], v[144:147], v[200:203], v[92:95]
	v_mfma_f32_16x16x32_bf16 v[88:91], v[160:163], v[200:203], v[88:91]
	v_mfma_f32_16x16x32_bf16 v[76:79], v[144:147], v[208:211], v[76:79]
	v_mfma_f32_16x16x32_bf16 v[72:75], v[160:163], v[208:211], v[72:75]
	v_mfma_f32_16x16x32_bf16 v[124:127], v[156:159], v[188:191], v[124:127]
	v_mfma_f32_16x16x32_bf16 v[120:123], v[164:167], v[188:191], v[120:123]
	v_mfma_f32_16x16x32_bf16 v[108:111], v[156:159], v[196:199], v[108:111]
	v_mfma_f32_16x16x32_bf16 v[104:107], v[164:167], v[196:199], v[104:107]
	v_mfma_f32_16x16x32_bf16 v[92:95], v[156:159], v[204:207], v[92:95]
	v_mfma_f32_16x16x32_bf16 v[88:91], v[164:167], v[204:207], v[88:91]
	v_mfma_f32_16x16x32_bf16 v[76:79], v[156:159], v[212:215], v[76:79]
	v_mfma_f32_16x16x32_bf16 v[72:75], v[164:167], v[212:215], v[72:75]
	v_mfma_f32_16x16x32_bf16 v[116:119], v[168:171], v[184:187], v[116:119]
	v_mfma_f32_16x16x32_bf16 v[112:115], v[176:179], v[184:187], v[112:115]
	v_mfma_f32_16x16x32_bf16 v[100:103], v[168:171], v[192:195], v[100:103]
	v_mfma_f32_16x16x32_bf16 v[96:99], v[176:179], v[192:195], v[96:99]
	v_mfma_f32_16x16x32_bf16 v[84:87], v[168:171], v[200:203], v[84:87]
	v_mfma_f32_16x16x32_bf16 v[80:83], v[176:179], v[200:203], v[80:83]
	v_mfma_f32_16x16x32_bf16 v[68:71], v[168:171], v[208:211], v[68:71]
	v_mfma_f32_16x16x32_bf16 v[64:67], v[176:179], v[208:211], v[64:67]
	v_mfma_f32_16x16x32_bf16 v[116:119], v[172:175], v[188:191], v[116:119]
	v_mfma_f32_16x16x32_bf16 v[112:115], v[180:183], v[188:191], v[112:115]
	v_mfma_f32_16x16x32_bf16 v[100:103], v[172:175], v[196:199], v[100:103]
	v_mfma_f32_16x16x32_bf16 v[96:99], v[180:183], v[196:199], v[96:99]
	v_mfma_f32_16x16x32_bf16 v[84:87], v[172:175], v[204:207], v[84:87]
	v_mfma_f32_16x16x32_bf16 v[80:83], v[180:183], v[204:207], v[80:83]
	v_mfma_f32_16x16x32_bf16 v[68:71], v[172:175], v[212:215], v[68:71]
	v_mfma_f32_16x16x32_bf16 v[64:67], v[180:183], v[212:215], v[64:67]
	s_setprio 0
	s_barrier
	s_add_i32 s44, s64, s33
	v_lshl_add_u64 v[148:149], v[148:149], 0, s[18:19]
	s_mov_b32 m0, s44
	ds_read_b128 v[184:187], v155 offset:49152
	ds_read_b128 v[188:191], v155 offset:50176
	ds_read_b128 v[192:195], v155 offset:51200
	ds_read_b128 v[196:199], v155 offset:52224
	ds_read_b128 v[200:203], v155 offset:53248
	ds_read_b128 v[204:207], v155 offset:54272
	ds_read_b128 v[208:211], v155 offset:55296
	ds_read_b128 v[212:215], v155 offset:56320
	global_load_lds_dwordx4 v[148:149], off
	s_add_i32 m0, s44, 0x2000
	s_add_u32 s42, s42, 0x40080
	v_lshl_add_u64 v[148:149], v[216:217], 0, s[18:19]
	s_addc_u32 s43, s43, 0
	s_add_i32 s44, s65, s33
	global_load_lds_dwordx4 v[148:149], off
	v_lshl_add_u64 v[148:149], s[42:43], 0, v[130:131]
	s_mov_b32 m0, s44
	s_nop 0
	global_load_lds_dwordx4 v[148:149], off
	v_lshl_add_u64 v[148:149], s[42:43], 0, v[134:135]
	s_add_i32 m0, s44, 0x2000
	s_nop 0
	global_load_lds_dwordx4 v[148:149], off
	v_lshl_add_u64 v[148:149], v[218:219], 0, s[18:19]
	s_mov_b32 m0, s50
	s_nop 0
	global_load_lds_dwordx4 v[148:149], off
	v_lshl_add_u64 v[148:149], v[220:221], 0, s[18:19]
	s_mov_b32 m0, s51
	s_nop 0
	global_load_lds_dwordx4 v[148:149], off
	s_waitcnt vmcnt(8)
	s_waitcnt lgkmcnt(0)
	s_barrier
	s_setprio 1
	s_waitcnt lgkmcnt(0)
	v_mfma_f32_16x16x32_bf16 v[60:63], v[144:147], v[184:187], v[60:63]
	v_mfma_f32_16x16x32_bf16 v[56:59], v[160:163], v[184:187], v[56:59]
	v_mfma_f32_16x16x32_bf16 v[44:47], v[144:147], v[192:195], v[44:47]
	v_mfma_f32_16x16x32_bf16 v[40:43], v[160:163], v[192:195], v[40:43]
	v_mfma_f32_16x16x32_bf16 v[28:31], v[144:147], v[200:203], v[28:31]
	v_mfma_f32_16x16x32_bf16 v[24:27], v[160:163], v[200:203], v[24:27]
	v_mfma_f32_16x16x32_bf16 v[12:15], v[144:147], v[208:211], v[12:15]
	v_mfma_f32_16x16x32_bf16 v[8:11], v[160:163], v[208:211], v[8:11]
	v_mfma_f32_16x16x32_bf16 v[60:63], v[156:159], v[188:191], v[60:63]
	v_mfma_f32_16x16x32_bf16 v[56:59], v[164:167], v[188:191], v[56:59]
	v_mfma_f32_16x16x32_bf16 v[44:47], v[156:159], v[196:199], v[44:47]
	v_mfma_f32_16x16x32_bf16 v[40:43], v[164:167], v[196:199], v[40:43]
	v_mfma_f32_16x16x32_bf16 v[28:31], v[156:159], v[204:207], v[28:31]
	v_mfma_f32_16x16x32_bf16 v[24:27], v[164:167], v[204:207], v[24:27]
	v_mfma_f32_16x16x32_bf16 v[12:15], v[156:159], v[212:215], v[12:15]
	v_mfma_f32_16x16x32_bf16 v[8:11], v[164:167], v[212:215], v[8:11]
	v_mfma_f32_16x16x32_bf16 v[52:55], v[168:171], v[184:187], v[52:55]
	v_mfma_f32_16x16x32_bf16 v[48:51], v[176:179], v[184:187], v[48:51]
	v_mfma_f32_16x16x32_bf16 v[36:39], v[168:171], v[192:195], v[36:39]
	v_mfma_f32_16x16x32_bf16 v[32:35], v[176:179], v[192:195], v[32:35]
	v_mfma_f32_16x16x32_bf16 v[20:23], v[168:171], v[200:203], v[20:23]
	v_mfma_f32_16x16x32_bf16 v[16:19], v[176:179], v[200:203], v[16:19]
	v_mfma_f32_16x16x32_bf16 v[4:7], v[168:171], v[208:211], v[4:7]
	v_mfma_f32_16x16x32_bf16 v[0:3], v[176:179], v[208:211], v[0:3]
	v_mfma_f32_16x16x32_bf16 v[52:55], v[172:175], v[188:191], v[52:55]
	v_mfma_f32_16x16x32_bf16 v[48:51], v[180:183], v[188:191], v[48:51]
	v_mfma_f32_16x16x32_bf16 v[36:39], v[172:175], v[196:199], v[36:39]
	v_mfma_f32_16x16x32_bf16 v[32:35], v[180:183], v[196:199], v[32:35]
	v_mfma_f32_16x16x32_bf16 v[20:23], v[172:175], v[204:207], v[20:23]
	v_mfma_f32_16x16x32_bf16 v[16:19], v[180:183], v[204:207], v[16:19]
	v_mfma_f32_16x16x32_bf16 v[4:7], v[172:175], v[212:215], v[4:7]
	v_mfma_f32_16x16x32_bf16 v[0:3], v[180:183], v[212:215], v[0:3]
	s_setprio 0
	s_barrier
	s_add_i32 s63, s63, 2
	s_add_u32 s61, s61, 0x100
	s_addc_u32 s62, s62, 0
	s_add_u32 s40, s40, 0x100
	s_addc_u32 s41, s41, 0
	s_cmp_gt_u32 s63, 13
	s_cbranch_scc0 .LBB0_1111
	s_and_b64 vcc, exec, s[20:21]
	s_cbranch_vccz .LBB0_1114
	s_barrier

.LBB0_1134:
	ds_read_b128 v[0:3], v161
	ds_read_b128 v[4:7], v161 offset:1024
	ds_read_b128 v[8:11], v161 offset:2048
	ds_read_b128 v[12:15], v161 offset:3072
	ds_read_b128 v[16:19], v162
	ds_read_b128 v[20:23], v162 offset:1024
	ds_read_b128 v[24:27], v162 offset:2048
	ds_read_b128 v[28:31], v162 offset:3072
	s_ashr_i32 s37, s36, 31
	s_lshl_b64 s[38:39], s[36:37], 17
	s_add_u32 s38, s10, s38
	s_addc_u32 s39, s11, s39
	s_and_b64 s[40:41], s[8:9], exec
	s_cselect_b32 s51, s39, s45
	s_cselect_b32 s50, s38, s44
	s_ashr_i32 s35, s34, 31
	s_lshl_b64 s[40:41], s[34:35], 17
	s_add_u32 s40, s4, s40
	s_addc_u32 s41, s5, s41
	s_and_b64 s[48:49], s[8:9], exec
	s_cselect_b32 s49, s41, s47
	s_cselect_b32 s48, s40, s46
	s_add_u32 s66, s44, 0x10080
	s_addc_u32 s67, s45, 0
	s_mov_b32 m0, s59
	v_lshl_add_u64 v[64:65], s[66:67], 0, v[140:141]
	ds_read_b128 v[32:35], v163
	ds_read_b128 v[36:39], v163 offset:1024
	ds_read_b128 v[40:43], v163 offset:2048
	ds_read_b128 v[44:47], v163 offset:3072
	ds_read_b128 v[48:51], v163 offset:4096
	ds_read_b128 v[52:55], v163 offset:5120
	ds_read_b128 v[56:59], v163 offset:6144
	ds_read_b128 v[60:63], v163 offset:7168
	global_load_lds_dwordx4 v[64:65], off
	v_lshl_add_u64 v[64:65], s[66:67], 0, v[144:145]
	s_mov_b32 m0, s60
	s_nop 0
	global_load_lds_dwordx4 v[64:65], off
	s_waitcnt vmcnt(8)
	s_waitcnt lgkmcnt(0)
	s_barrier
	s_setprio 1
	s_waitcnt lgkmcnt(0)
	v_mfma_f32_16x16x32_bf16 v[64:67], v[0:3], v[32:35], 0
	v_mfma_f32_16x16x32_bf16 v[68:71], v[8:11], v[32:35], 0
	v_mfma_f32_16x16x32_bf16 v[72:75], v[0:3], v[40:43], 0
	v_mfma_f32_16x16x32_bf16 v[76:79], v[8:11], v[40:43], 0
	v_mfma_f32_16x16x32_bf16 v[80:83], v[0:3], v[48:51], 0
	v_mfma_f32_16x16x32_bf16 v[84:87], v[8:11], v[48:51], 0
	v_mfma_f32_16x16x32_bf16 v[88:91], v[0:3], v[56:59], 0
	v_mfma_f32_16x16x32_bf16 v[92:95], v[8:11], v[56:59], 0
	v_mfma_f32_16x16x32_bf16 v[64:67], v[4:7], v[36:39], v[64:67]
	v_mfma_f32_16x16x32_bf16 v[68:71], v[12:15], v[36:39], v[68:71]
	v_mfma_f32_16x16x32_bf16 v[72:75], v[4:7], v[44:47], v[72:75]
	v_mfma_f32_16x16x32_bf16 v[76:79], v[12:15], v[44:47], v[76:79]
	v_mfma_f32_16x16x32_bf16 v[80:83], v[4:7], v[52:55], v[80:83]
	v_mfma_f32_16x16x32_bf16 v[84:87], v[12:15], v[52:55], v[84:87]
	v_mfma_f32_16x16x32_bf16 v[88:91], v[4:7], v[60:63], v[88:91]
	v_mfma_f32_16x16x32_bf16 v[92:95], v[12:15], v[60:63], v[92:95]
	v_mfma_f32_16x16x32_bf16 v[96:99], v[16:19], v[32:35], 0
	v_mfma_f32_16x16x32_bf16 v[32:35], v[24:27], v[32:35], 0
	v_mfma_f32_16x16x32_bf16 v[96:99], v[20:23], v[36:39], v[96:99]
	v_mfma_f32_16x16x32_bf16 v[32:35], v[28:31], v[36:39], v[32:35]
	v_mfma_f32_16x16x32_bf16 v[36:39], v[16:19], v[40:43], 0
	v_mfma_f32_16x16x32_bf16 v[40:43], v[24:27], v[40:43], 0
	v_mfma_f32_16x16x32_bf16 v[36:39], v[20:23], v[44:47], v[36:39]
	v_mfma_f32_16x16x32_bf16 v[40:43], v[28:31], v[44:47], v[40:43]
	v_mfma_f32_16x16x32_bf16 v[44:47], v[16:19], v[48:51], 0
	v_mfma_f32_16x16x32_bf16 v[48:51], v[24:27], v[48:51], 0
	v_mfma_f32_16x16x32_bf16 v[44:47], v[20:23], v[52:55], v[44:47]
	v_mfma_f32_16x16x32_bf16 v[48:51], v[28:31], v[52:55], v[48:51]
	v_mfma_f32_16x16x32_bf16 v[52:55], v[16:19], v[56:59], 0
	v_mfma_f32_16x16x32_bf16 v[56:59], v[24:27], v[56:59], 0
	v_mfma_f32_16x16x32_bf16 v[52:55], v[20:23], v[60:63], v[52:55]
	v_mfma_f32_16x16x32_bf16 v[56:59], v[28:31], v[60:63], v[56:59]
	s_setprio 0
	s_barrier
	s_add_i32 s67, s57, s33
	v_lshl_add_u64 v[156:157], s[46:47], 0, v[142:143]
	s_add_i32 s35, s67, 0x2000
	v_lshl_add_u64 v[128:129], v[156:157], 0, s[20:21]
	s_mov_b32 m0, s67
	v_lshl_add_u64 v[212:213], s[46:47], 0, v[146:147]
	s_add_u32 s68, s46, 0x10100
	ds_read_b128 v[60:63], v163 offset:16384
	ds_read_b128 v[100:103], v163 offset:17408
	ds_read_b128 v[104:107], v163 offset:18432
	ds_read_b128 v[108:111], v163 offset:19456
	ds_read_b128 v[112:115], v163 offset:20480
	ds_read_b128 v[116:119], v163 offset:21504
	ds_read_b128 v[120:123], v163 offset:22528
	ds_read_b128 v[124:127], v163 offset:23552
	global_load_lds_dwordx4 v[128:129], off
	v_lshl_add_u64 v[128:129], v[212:213], 0, s[20:21]
	s_mov_b32 m0, s35
	s_addc_u32 s69, s47, 0
	s_add_i32 s37, s58, s33
	global_load_lds_dwordx4 v[128:129], off
	v_lshl_add_u64 v[128:129], s[68:69], 0, v[142:143]
	s_mov_b32 m0, s37
	s_add_i32 s66, s37, 0x2000
	global_load_lds_dwordx4 v[128:129], off
	v_lshl_add_u64 v[128:129], s[68:69], 0, v[146:147]
	s_mov_b32 m0, s66
	v_lshl_add_u64 v[214:215], s[44:45], 0, v[140:141]
	global_load_lds_dwordx4 v[128:129], off
	v_lshl_add_u64 v[128:129], v[214:215], 0, s[20:21]
	s_mov_b32 m0, s43
	v_lshl_add_u64 v[216:217], s[44:45], 0, v[144:145]
	global_load_lds_dwordx4 v[128:129], off
	v_lshl_add_u64 v[128:129], v[216:217], 0, s[20:21]
	s_mov_b32 m0, s52
	s_nop 0
	global_load_lds_dwordx4 v[128:129], off
	s_waitcnt vmcnt(8)
	s_waitcnt lgkmcnt(0)
	s_barrier
	s_setprio 1
	s_waitcnt lgkmcnt(0)
	v_mfma_f32_16x16x32_bf16 v[128:131], v[0:3], v[60:63], 0
	v_mfma_f32_16x16x32_bf16 v[136:139], v[0:3], v[104:107], 0
	v_mfma_f32_16x16x32_bf16 v[164:167], v[0:3], v[112:115], 0
	v_mfma_f32_16x16x32_bf16 v[0:3], v[0:3], v[120:123], 0
	v_mfma_f32_16x16x32_bf16 v[128:131], v[4:7], v[100:103], v[128:131]
	v_mfma_f32_16x16x32_bf16 v[136:139], v[4:7], v[108:111], v[136:139]
	v_mfma_f32_16x16x32_bf16 v[164:167], v[4:7], v[116:119], v[164:167]
	v_mfma_f32_16x16x32_bf16 v[0:3], v[4:7], v[124:127], v[0:3]
	v_mfma_f32_16x16x32_bf16 v[4:7], v[8:11], v[120:123], 0
	v_mfma_f32_16x16x32_bf16 v[132:135], v[8:11], v[60:63], 0
	v_mfma_f32_16x16x32_bf16 v[152:155], v[8:11], v[104:107], 0
	v_mfma_f32_16x16x32_bf16 v[168:171], v[8:11], v[112:115], 0
	v_mfma_f32_16x16x32_bf16 v[4:7], v[12:15], v[124:127], v[4:7]
	v_mfma_f32_16x16x32_bf16 v[132:135], v[12:15], v[100:103], v[132:135]
	v_mfma_f32_16x16x32_bf16 v[152:155], v[12:15], v[108:111], v[152:155]
	v_mfma_f32_16x16x32_bf16 v[168:171], v[12:15], v[116:119], v[168:171]
	v_mfma_f32_16x16x32_bf16 v[8:11], v[16:19], v[60:63], 0
	v_mfma_f32_16x16x32_bf16 v[12:15], v[24:27], v[60:63], 0
	v_mfma_f32_16x16x32_bf16 v[8:11], v[20:23], v[100:103], v[8:11]
	v_mfma_f32_16x16x32_bf16 v[12:15], v[28:31], v[100:103], v[12:15]
	v_mfma_f32_16x16x32_bf16 v[60:63], v[16:19], v[104:107], 0
	v_mfma_f32_16x16x32_bf16 v[100:103], v[24:27], v[104:107], 0
	v_mfma_f32_16x16x32_bf16 v[104:107], v[16:19], v[112:115], 0
	v_mfma_f32_16x16x32_bf16 v[16:19], v[16:19], v[120:123], 0
	v_mfma_f32_16x16x32_bf16 v[60:63], v[20:23], v[108:111], v[60:63]
	v_mfma_f32_16x16x32_bf16 v[100:103], v[28:31], v[108:111], v[100:103]
	v_mfma_f32_16x16x32_bf16 v[104:107], v[20:23], v[116:119], v[104:107]
	v_mfma_f32_16x16x32_bf16 v[108:111], v[24:27], v[112:115], 0
	v_mfma_f32_16x16x32_bf16 v[16:19], v[20:23], v[124:127], v[16:19]
	v_mfma_f32_16x16x32_bf16 v[20:23], v[24:27], v[120:123], 0
	v_mfma_f32_16x16x32_bf16 v[108:111], v[28:31], v[116:119], v[108:111]
	v_mfma_f32_16x16x32_bf16 v[20:23], v[28:31], v[124:127], v[20:23]
	s_setprio 0
	s_barrier
	s_add_i32 s70, 0, 0x18000
	s_add_i32 s72, 0, 0x1c000
	v_add_u32_e32 v224, s70, v159
	v_add_u32_e32 v228, s72, v159
	ds_read_b128 v[24:27], v224
	ds_read_b128 v[28:31], v224 offset:1024
	ds_read_b128 v[112:115], v224 offset:2048
	ds_read_b128 v[116:119], v224 offset:3072
	ds_read_b128 v[120:123], v228
	ds_read_b128 v[124:127], v228 offset:1024
	ds_read_b128 v[172:175], v228 offset:2048
	ds_read_b128 v[176:179], v228 offset:3072
	s_add_u32 s68, s44, 0x10100
	s_addc_u32 s69, s45, 0
	s_mov_b32 m0, s53
	v_lshl_add_u64 v[218:219], s[68:69], 0, v[140:141]
	ds_read_b128 v[180:183], v163 offset:32768
	ds_read_b128 v[184:187], v163 offset:33792
	ds_read_b128 v[188:191], v163 offset:34816
	ds_read_b128 v[192:195], v163 offset:35840
	ds_read_b128 v[196:199], v163 offset:36864
	ds_read_b128 v[200:203], v163 offset:37888
	ds_read_b128 v[204:207], v163 offset:38912
	ds_read_b128 v[208:211], v163 offset:39936
	global_load_lds_dwordx4 v[218:219], off
	v_lshl_add_u64 v[218:219], s[68:69], 0, v[144:145]
	s_mov_b32 m0, s54
	s_nop 0
	global_load_lds_dwordx4 v[218:219], off
	s_waitcnt vmcnt(8)
	s_waitcnt lgkmcnt(0)
	s_barrier
	s_setprio 1
	s_waitcnt lgkmcnt(0)
	v_mfma_f32_16x16x32_bf16 v[64:67], v[24:27], v[180:183], v[64:67]
	v_mfma_f32_16x16x32_bf16 v[68:71], v[112:115], v[180:183], v[68:71]
	v_mfma_f32_16x16x32_bf16 v[72:75], v[24:27], v[188:191], v[72:75]
	v_mfma_f32_16x16x32_bf16 v[76:79], v[112:115], v[188:191], v[76:79]
	v_mfma_f32_16x16x32_bf16 v[80:83], v[24:27], v[196:199], v[80:83]
	v_mfma_f32_16x16x32_bf16 v[84:87], v[112:115], v[196:199], v[84:87]
	v_mfma_f32_16x16x32_bf16 v[88:91], v[24:27], v[204:207], v[88:91]
	v_mfma_f32_16x16x32_bf16 v[92:95], v[112:115], v[204:207], v[92:95]
	v_mfma_f32_16x16x32_bf16 v[64:67], v[28:31], v[184:187], v[64:67]
	v_mfma_f32_16x16x32_bf16 v[68:71], v[116:119], v[184:187], v[68:71]
	v_mfma_f32_16x16x32_bf16 v[72:75], v[28:31], v[192:195], v[72:75]
	v_mfma_f32_16x16x32_bf16 v[76:79], v[116:119], v[192:195], v[76:79]
	v_mfma_f32_16x16x32_bf16 v[80:83], v[28:31], v[200:203], v[80:83]
	v_mfma_f32_16x16x32_bf16 v[84:87], v[116:119], v[200:203], v[84:87]
	v_mfma_f32_16x16x32_bf16 v[88:91], v[28:31], v[208:211], v[88:91]
	v_mfma_f32_16x16x32_bf16 v[92:95], v[116:119], v[208:211], v[92:95]
	v_mfma_f32_16x16x32_bf16 v[96:99], v[120:123], v[180:183], v[96:99]
	v_mfma_f32_16x16x32_bf16 v[32:35], v[172:175], v[180:183], v[32:35]
	v_mfma_f32_16x16x32_bf16 v[36:39], v[120:123], v[188:191], v[36:39]
	v_mfma_f32_16x16x32_bf16 v[40:43], v[172:175], v[188:191], v[40:43]
	v_mfma_f32_16x16x32_bf16 v[44:47], v[120:123], v[196:199], v[44:47]
	v_mfma_f32_16x16x32_bf16 v[48:51], v[172:175], v[196:199], v[48:51]
	v_mfma_f32_16x16x32_bf16 v[52:55], v[120:123], v[204:207], v[52:55]
	v_mfma_f32_16x16x32_bf16 v[56:59], v[172:175], v[204:207], v[56:59]
	v_mfma_f32_16x16x32_bf16 v[96:99], v[124:127], v[184:187], v[96:99]
	v_mfma_f32_16x16x32_bf16 v[32:35], v[176:179], v[184:187], v[32:35]
	v_mfma_f32_16x16x32_bf16 v[36:39], v[124:127], v[192:195], v[36:39]
	v_mfma_f32_16x16x32_bf16 v[40:43], v[176:179], v[192:195], v[40:43]
	v_mfma_f32_16x16x32_bf16 v[44:47], v[124:127], v[200:203], v[44:47]
	v_mfma_f32_16x16x32_bf16 v[48:51], v[176:179], v[200:203], v[48:51]
	v_mfma_f32_16x16x32_bf16 v[52:55], v[124:127], v[208:211], v[52:55]
	v_mfma_f32_16x16x32_bf16 v[56:59], v[176:179], v[208:211], v[56:59]
	s_setprio 0
	s_barrier
	s_add_i32 s69, s70, s33
	s_add_i32 s68, s69, 0x2000
	v_lshl_add_u64 v[156:157], v[156:157], 0, s[22:23]
	s_mov_b32 m0, s69
	s_add_u32 s70, s46, 0x10180
	ds_read_b128 v[180:183], v163 offset:49152
	ds_read_b128 v[184:187], v163 offset:50176
	ds_read_b128 v[188:191], v163 offset:51200
	ds_read_b128 v[192:195], v163 offset:52224
	ds_read_b128 v[196:199], v163 offset:53248
	ds_read_b128 v[200:203], v163 offset:54272
	ds_read_b128 v[204:207], v163 offset:55296
	ds_read_b128 v[208:211], v163 offset:56320
	global_load_lds_dwordx4 v[156:157], off
	v_lshl_add_u64 v[156:157], v[212:213], 0, s[22:23]
	s_mov_b32 m0, s68
	s_addc_u32 s71, s47, 0
	s_add_i32 s46, s72, s33
	global_load_lds_dwordx4 v[156:157], off
	v_lshl_add_u64 v[156:157], s[70:71], 0, v[142:143]
	s_mov_b32 m0, s46
	s_add_i32 s47, s46, 0x2000
	global_load_lds_dwordx4 v[156:157], off
	v_lshl_add_u64 v[156:157], s[70:71], 0, v[146:147]
	s_mov_b32 m0, s47
	s_nop 0
	global_load_lds_dwordx4 v[156:157], off
	v_lshl_add_u64 v[156:157], v[214:215], 0, s[22:23]
	s_mov_b32 m0, s55
	s_nop 0
	global_load_lds_dwordx4 v[156:157], off
	v_lshl_add_u64 v[156:157], v[216:217], 0, s[22:23]
	s_mov_b32 m0, s56
	s_nop 0
	global_load_lds_dwordx4 v[156:157], off
	s_waitcnt vmcnt(8)
	s_waitcnt lgkmcnt(0)
	s_barrier
	s_setprio 1
	s_waitcnt lgkmcnt(0)
	v_mfma_f32_16x16x32_bf16 v[0:3], v[24:27], v[204:207], v[0:3]
	v_mfma_f32_16x16x32_bf16 v[4:7], v[112:115], v[204:207], v[4:7]
	v_mfma_f32_16x16x32_bf16 v[128:131], v[24:27], v[180:183], v[128:131]
	v_mfma_f32_16x16x32_bf16 v[132:135], v[112:115], v[180:183], v[132:135]
	v_mfma_f32_16x16x32_bf16 v[136:139], v[24:27], v[188:191], v[136:139]
	v_mfma_f32_16x16x32_bf16 v[152:155], v[112:115], v[188:191], v[152:155]
	v_mfma_f32_16x16x32_bf16 v[164:167], v[24:27], v[196:199], v[164:167]
	v_mfma_f32_16x16x32_bf16 v[168:171], v[112:115], v[196:199], v[168:171]
	v_mfma_f32_16x16x32_bf16 v[0:3], v[28:31], v[208:211], v[0:3]
	v_mfma_f32_16x16x32_bf16 v[4:7], v[116:119], v[208:211], v[4:7]
	v_mfma_f32_16x16x32_bf16 v[128:131], v[28:31], v[184:187], v[128:131]
	v_mfma_f32_16x16x32_bf16 v[132:135], v[116:119], v[184:187], v[132:135]
	v_mfma_f32_16x16x32_bf16 v[136:139], v[28:31], v[192:195], v[136:139]
	v_mfma_f32_16x16x32_bf16 v[152:155], v[116:119], v[192:195], v[152:155]
	v_mfma_f32_16x16x32_bf16 v[164:167], v[28:31], v[200:203], v[164:167]
	v_mfma_f32_16x16x32_bf16 v[168:171], v[116:119], v[200:203], v[168:171]
	v_mfma_f32_16x16x32_bf16 v[8:11], v[120:123], v[180:183], v[8:11]
	v_mfma_f32_16x16x32_bf16 v[12:15], v[172:175], v[180:183], v[12:15]
	v_mfma_f32_16x16x32_bf16 v[24:27], v[120:123], v[188:191], v[60:63]
	v_mfma_f32_16x16x32_bf16 v[28:31], v[172:175], v[188:191], v[100:103]
	v_mfma_f32_16x16x32_bf16 v[60:63], v[120:123], v[196:199], v[104:107]
	v_mfma_f32_16x16x32_bf16 v[100:103], v[172:175], v[196:199], v[108:111]
	v_mfma_f32_16x16x32_bf16 v[16:19], v[120:123], v[204:207], v[16:19]
	v_mfma_f32_16x16x32_bf16 v[20:23], v[172:175], v[204:207], v[20:23]
	v_mfma_f32_16x16x32_bf16 v[8:11], v[124:127], v[184:187], v[8:11]
	v_mfma_f32_16x16x32_bf16 v[12:15], v[176:179], v[184:187], v[12:15]
	v_mfma_f32_16x16x32_bf16 v[24:27], v[124:127], v[192:195], v[24:27]
	v_mfma_f32_16x16x32_bf16 v[28:31], v[176:179], v[192:195], v[28:31]
	v_mfma_f32_16x16x32_bf16 v[60:63], v[124:127], v[200:203], v[60:63]
	v_mfma_f32_16x16x32_bf16 v[100:103], v[176:179], v[200:203], v[100:103]
	v_mfma_f32_16x16x32_bf16 v[16:19], v[124:127], v[208:211], v[16:19]
	v_mfma_f32_16x16x32_bf16 v[20:23], v[176:179], v[208:211], v[20:23]
	s_setprio 0
	s_barrier
	ds_read_b128 v[104:107], v161
	ds_read_b128 v[108:111], v161 offset:1024
	ds_read_b128 v[112:115], v161 offset:2048
	ds_read_b128 v[116:119], v161 offset:3072
	ds_read_b128 v[120:123], v162
	ds_read_b128 v[124:127], v162 offset:1024
	ds_read_b128 v[172:175], v162 offset:2048
	ds_read_b128 v[176:179], v162 offset:3072
	s_add_u32 s44, s44, 0x10180
	s_addc_u32 s45, s45, 0
	s_mov_b32 m0, s59
	v_lshl_add_u64 v[156:157], s[44:45], 0, v[140:141]
	ds_read_b128 v[180:183], v163
	ds_read_b128 v[184:187], v163 offset:1024
	ds_read_b128 v[188:191], v163 offset:2048
	ds_read_b128 v[192:195], v163 offset:3072
	ds_read_b128 v[196:199], v163 offset:4096
	ds_read_b128 v[200:203], v163 offset:5120
	ds_read_b128 v[204:207], v163 offset:6144
	ds_read_b128 v[208:211], v163 offset:7168
	global_load_lds_dwordx4 v[156:157], off
	v_lshl_add_u64 v[156:157], s[44:45], 0, v[144:145]
	s_mov_b32 m0, s60
	s_nop 0
	global_load_lds_dwordx4 v[156:157], off
	s_waitcnt vmcnt(8)
	s_waitcnt lgkmcnt(0)
	s_barrier
	s_setprio 1
	s_waitcnt lgkmcnt(0)
	v_mfma_f32_16x16x32_bf16 v[64:67], v[104:107], v[180:183], v[64:67]
	v_mfma_f32_16x16x32_bf16 v[68:71], v[112:115], v[180:183], v[68:71]
	v_mfma_f32_16x16x32_bf16 v[72:75], v[104:107], v[188:191], v[72:75]
	v_mfma_f32_16x16x32_bf16 v[76:79], v[112:115], v[188:191], v[76:79]
	v_mfma_f32_16x16x32_bf16 v[80:83], v[104:107], v[196:199], v[80:83]
	v_mfma_f32_16x16x32_bf16 v[84:87], v[112:115], v[196:199], v[84:87]
	v_mfma_f32_16x16x32_bf16 v[88:91], v[104:107], v[204:207], v[88:91]
	v_mfma_f32_16x16x32_bf16 v[64:67], v[108:111], v[184:187], v[64:67]
	v_mfma_f32_16x16x32_bf16 v[68:71], v[116:119], v[184:187], v[68:71]
	v_mfma_f32_16x16x32_bf16 v[72:75], v[108:111], v[192:195], v[72:75]
	v_mfma_f32_16x16x32_bf16 v[76:79], v[116:119], v[192:195], v[76:79]
	v_mfma_f32_16x16x32_bf16 v[80:83], v[108:111], v[200:203], v[80:83]
	v_mfma_f32_16x16x32_bf16 v[84:87], v[116:119], v[200:203], v[84:87]
	v_mfma_f32_16x16x32_bf16 v[212:215], v[108:111], v[208:211], v[88:91]
	v_mfma_f32_16x16x32_bf16 v[88:91], v[112:115], v[204:207], v[92:95]
	v_mfma_f32_16x16x32_bf16 v[216:219], v[116:119], v[208:211], v[88:91]
	v_mfma_f32_16x16x32_bf16 v[32:35], v[172:175], v[180:183], v[32:35]
	v_mfma_f32_16x16x32_bf16 v[36:39], v[120:123], v[188:191], v[36:39]
	v_mfma_f32_16x16x32_bf16 v[40:43], v[172:175], v[188:191], v[40:43]
	v_mfma_f32_16x16x32_bf16 v[44:47], v[120:123], v[196:199], v[44:47]
	v_mfma_f32_16x16x32_bf16 v[48:51], v[172:175], v[196:199], v[48:51]
	v_mfma_f32_16x16x32_bf16 v[52:55], v[120:123], v[204:207], v[52:55]
	v_mfma_f32_16x16x32_bf16 v[56:59], v[172:175], v[204:207], v[56:59]
	v_mfma_f32_16x16x32_bf16 v[88:91], v[120:123], v[180:183], v[96:99]
	v_mfma_f32_16x16x32_bf16 v[32:35], v[176:179], v[184:187], v[32:35]
	v_mfma_f32_16x16x32_bf16 v[36:39], v[124:127], v[192:195], v[36:39]
	v_mfma_f32_16x16x32_bf16 v[40:43], v[176:179], v[192:195], v[40:43]
	v_mfma_f32_16x16x32_bf16 v[44:47], v[124:127], v[200:203], v[44:47]
	v_mfma_f32_16x16x32_bf16 v[48:51], v[176:179], v[200:203], v[48:51]
	v_mfma_f32_16x16x32_bf16 v[52:55], v[124:127], v[208:211], v[52:55]
	v_mfma_f32_16x16x32_bf16 v[56:59], v[176:179], v[208:211], v[56:59]
	v_mfma_f32_16x16x32_bf16 v[220:223], v[124:127], v[184:187], v[88:91]
	s_setprio 0
	s_barrier
	s_mov_b32 m0, s67
	v_lshl_add_u64 v[156:157], s[48:49], 0, v[142:143]
	s_add_u32 s44, s48, 0x10000
	ds_read_b128 v[88:91], v163 offset:16384
	ds_read_b128 v[92:95], v163 offset:17408
	ds_read_b128 v[96:99], v163 offset:18432
	ds_read_b128 v[180:183], v163 offset:19456
	ds_read_b128 v[184:187], v163 offset:20480
	ds_read_b128 v[188:191], v163 offset:21504
	ds_read_b128 v[192:195], v163 offset:22528
	ds_read_b128 v[196:199], v163 offset:23552
	global_load_lds_dwordx4 v[156:157], off
	v_lshl_add_u64 v[250:251], s[48:49], 0, v[146:147]
	s_mov_b32 m0, s35
	s_addc_u32 s45, s49, 0
	global_load_lds_dwordx4 v[250:251], off
	v_lshl_add_u64 v[200:201], s[44:45], 0, v[142:143]
	s_mov_b32 m0, s37
	v_lshl_add_u64 v[252:253], s[50:51], 0, v[140:141]
	global_load_lds_dwordx4 v[200:201], off
	v_lshl_add_u64 v[200:201], s[44:45], 0, v[146:147]
	s_mov_b32 m0, s66
	v_lshl_add_u64 v[148:149], s[50:51], 0, v[144:145]
	global_load_lds_dwordx4 v[200:201], off
	s_mov_b32 m0, s43
	s_nop 0
	global_load_lds_dwordx4 v[252:253], off
	s_mov_b32 m0, s52
	s_nop 0
	global_load_lds_dwordx4 v[148:149], off
	s_waitcnt vmcnt(8)
	s_waitcnt lgkmcnt(0)
	s_barrier
	s_setprio 1
	s_waitcnt lgkmcnt(0)
	v_mfma_f32_16x16x32_bf16 v[0:3], v[104:107], v[192:195], v[0:3]
	v_mfma_f32_16x16x32_bf16 v[4:7], v[112:115], v[192:195], v[4:7]
	v_mfma_f32_16x16x32_bf16 v[128:131], v[104:107], v[88:91], v[128:131]
	v_mfma_f32_16x16x32_bf16 v[132:135], v[112:115], v[88:91], v[132:135]
	v_mfma_f32_16x16x32_bf16 v[136:139], v[104:107], v[96:99], v[136:139]
	v_mfma_f32_16x16x32_bf16 v[152:155], v[112:115], v[96:99], v[152:155]
	v_mfma_f32_16x16x32_bf16 v[164:167], v[104:107], v[184:187], v[164:167]
	v_mfma_f32_16x16x32_bf16 v[168:171], v[112:115], v[184:187], v[168:171]
	v_mfma_f32_16x16x32_bf16 v[0:3], v[108:111], v[196:199], v[0:3]
	v_mfma_f32_16x16x32_bf16 v[4:7], v[116:119], v[196:199], v[4:7]
	v_mfma_f32_16x16x32_bf16 v[128:131], v[108:111], v[92:95], v[128:131]
	v_mfma_f32_16x16x32_bf16 v[132:135], v[116:119], v[92:95], v[132:135]
	v_mfma_f32_16x16x32_bf16 v[136:139], v[108:111], v[180:183], v[136:139]
	v_mfma_f32_16x16x32_bf16 v[152:155], v[116:119], v[180:183], v[152:155]
	v_mfma_f32_16x16x32_bf16 v[164:167], v[108:111], v[188:191], v[164:167]
	v_mfma_f32_16x16x32_bf16 v[168:171], v[116:119], v[188:191], v[168:171]
	v_mfma_f32_16x16x32_bf16 v[8:11], v[120:123], v[88:91], v[8:11]
	v_mfma_f32_16x16x32_bf16 v[200:203], v[124:127], v[92:95], v[8:11]
	v_mfma_f32_16x16x32_bf16 v[8:11], v[172:175], v[88:91], v[12:15]
	v_mfma_f32_16x16x32_bf16 v[204:207], v[176:179], v[92:95], v[8:11]
	v_mfma_f32_16x16x32_bf16 v[8:11], v[120:123], v[96:99], v[24:27]
	v_mfma_f32_16x16x32_bf16 v[208:211], v[124:127], v[180:183], v[8:11]
	v_mfma_f32_16x16x32_bf16 v[8:11], v[172:175], v[96:99], v[28:31]
	v_mfma_f32_16x16x32_bf16 v[28:31], v[176:179], v[180:183], v[8:11]
	v_mfma_f32_16x16x32_bf16 v[8:11], v[120:123], v[184:187], v[60:63]
	v_mfma_f32_16x16x32_bf16 v[180:183], v[124:127], v[188:191], v[8:11]
	v_mfma_f32_16x16x32_bf16 v[8:11], v[172:175], v[184:187], v[100:103]
	v_mfma_f32_16x16x32_bf16 v[184:187], v[176:179], v[188:191], v[8:11]
	v_mfma_f32_16x16x32_bf16 v[8:11], v[120:123], v[192:195], v[16:19]
	v_mfma_f32_16x16x32_bf16 v[188:191], v[124:127], v[196:199], v[8:11]
	v_mfma_f32_16x16x32_bf16 v[8:11], v[172:175], v[192:195], v[20:23]
	v_mfma_f32_16x16x32_bf16 v[172:175], v[176:179], v[196:199], v[8:11]
	s_setprio 0
	s_barrier
	s_nop 4
	ds_read_b128 v[8:11], v224
	ds_read_b128 v[12:15], v224 offset:1024
	ds_read_b128 v[20:23], v224 offset:2048
	ds_read_b128 v[176:179], v224 offset:3072
	ds_read_b128 v[192:195], v228
	ds_read_b128 v[196:199], v228 offset:1024
	ds_read_b128 v[224:227], v228 offset:2048
	ds_read_b128 v[230:233], v228 offset:3072
	s_add_u32 s44, s50, 0x10000
	s_addc_u32 s45, s51, 0
	s_mov_b32 m0, s53
	v_lshl_add_u64 v[88:89], s[44:45], 0, v[140:141]
	ds_read_b128 v[16:19], v163 offset:32768
	ds_read_b128 v[24:27], v163 offset:33792
	ds_read_b128 v[60:63], v163 offset:34816
	ds_read_b128 v[104:107], v163 offset:35840
	ds_read_b128 v[234:237], v163 offset:36864
	ds_read_b128 v[238:241], v163 offset:37888
	ds_read_b128 v[242:245], v163 offset:38912
	ds_read_b128 v[246:249], v163 offset:39936
	global_load_lds_dwordx4 v[88:89], off
	v_lshl_add_u64 v[88:89], s[44:45], 0, v[144:145]
	s_mov_b32 m0, s54
	s_nop 0
	global_load_lds_dwordx4 v[88:89], off
	s_waitcnt vmcnt(8)
	s_waitcnt lgkmcnt(0)
	s_barrier
	s_setprio 1
	s_waitcnt lgkmcnt(0)
	v_mfma_f32_16x16x32_bf16 v[64:67], v[8:11], v[16:19], v[64:67]
	v_mfma_f32_16x16x32_bf16 v[112:115], v[12:15], v[24:27], v[64:67]
	v_mfma_f32_16x16x32_bf16 v[64:67], v[20:23], v[16:19], v[68:71]
	v_mfma_f32_16x16x32_bf16 v[116:119], v[176:179], v[24:27], v[64:67]
	v_mfma_f32_16x16x32_bf16 v[64:67], v[8:11], v[60:63], v[72:75]
	v_mfma_f32_16x16x32_bf16 v[96:99], v[12:15], v[104:107], v[64:67]
	v_mfma_f32_16x16x32_bf16 v[64:67], v[20:23], v[60:63], v[76:79]
	v_mfma_f32_16x16x32_bf16 v[100:103], v[176:179], v[104:107], v[64:67]
	v_mfma_f32_16x16x32_bf16 v[64:67], v[8:11], v[234:237], v[80:83]
	v_mfma_f32_16x16x32_bf16 v[92:95], v[12:15], v[238:241], v[64:67]
	v_mfma_f32_16x16x32_bf16 v[64:67], v[20:23], v[234:237], v[84:87]
	v_mfma_f32_16x16x32_bf16 v[88:91], v[176:179], v[238:241], v[64:67]
	v_mfma_f32_16x16x32_bf16 v[64:67], v[8:11], v[242:245], v[212:215]
	v_mfma_f32_16x16x32_bf16 v[76:79], v[12:15], v[246:249], v[64:67]
	v_mfma_f32_16x16x32_bf16 v[64:67], v[20:23], v[242:245], v[216:219]
	v_mfma_f32_16x16x32_bf16 v[72:75], v[176:179], v[246:249], v[64:67]
	v_mfma_f32_16x16x32_bf16 v[64:67], v[192:195], v[16:19], v[220:223]
	v_mfma_f32_16x16x32_bf16 v[16:19], v[224:227], v[16:19], v[32:35]
	v_mfma_f32_16x16x32_bf16 v[124:127], v[230:233], v[24:27], v[16:19]
	v_mfma_f32_16x16x32_bf16 v[16:19], v[192:195], v[60:63], v[36:39]
	v_mfma_f32_16x16x32_bf16 v[108:111], v[196:199], v[104:107], v[16:19]
	v_mfma_f32_16x16x32_bf16 v[16:19], v[224:227], v[60:63], v[40:43]
	v_mfma_f32_16x16x32_bf16 v[104:107], v[230:233], v[104:107], v[16:19]
	v_mfma_f32_16x16x32_bf16 v[16:19], v[192:195], v[234:237], v[44:47]
	v_mfma_f32_16x16x32_bf16 v[84:87], v[196:199], v[238:241], v[16:19]
	v_mfma_f32_16x16x32_bf16 v[16:19], v[224:227], v[234:237], v[48:51]
	v_mfma_f32_16x16x32_bf16 v[80:83], v[230:233], v[238:241], v[16:19]
	v_mfma_f32_16x16x32_bf16 v[16:19], v[192:195], v[242:245], v[52:55]
	v_mfma_f32_16x16x32_bf16 v[68:71], v[196:199], v[246:249], v[16:19]
	v_mfma_f32_16x16x32_bf16 v[16:19], v[224:227], v[242:245], v[56:59]
	v_mfma_f32_16x16x32_bf16 v[120:123], v[196:199], v[24:27], v[64:67]
	v_mfma_f32_16x16x32_bf16 v[64:67], v[230:233], v[246:249], v[16:19]
	s_setprio 0
	s_barrier
	s_mov_b32 m0, s69
	s_nop 2
	v_lshl_add_u64 v[16:17], v[156:157], 0, s[14:15]
	s_add_u32 s44, s48, 0x10080
	ds_read_b128 v[36:39], v163 offset:49152
	ds_read_b128 v[40:43], v163 offset:50176
	ds_read_b128 v[212:215], v163 offset:51200
	ds_read_b128 v[216:219], v163 offset:52224
	ds_read_b128 v[220:223], v163 offset:53248
	ds_read_b128 v[234:237], v163 offset:54272
	ds_read_b128 v[238:241], v163 offset:55296
	ds_read_b128 v[242:245], v163 offset:56320
	global_load_lds_dwordx4 v[16:17], off
	v_lshl_add_u64 v[16:17], v[250:251], 0, s[14:15]
	s_mov_b32 m0, s68
	s_addc_u32 s45, s49, 0
	global_load_lds_dwordx4 v[16:17], off
	v_lshl_add_u64 v[16:17], s[44:45], 0, v[142:143]
	s_mov_b32 m0, s46
	s_nop 0
	global_load_lds_dwordx4 v[16:17], off
	v_lshl_add_u64 v[16:17], s[44:45], 0, v[146:147]
	s_mov_b32 m0, s47
	s_nop 0
	global_load_lds_dwordx4 v[16:17], off
	v_lshl_add_u64 v[16:17], v[252:253], 0, s[14:15]
	s_mov_b32 m0, s55
	s_nop 0
	global_load_lds_dwordx4 v[16:17], off
	v_lshl_add_u64 v[16:17], v[148:149], 0, s[14:15]
	s_mov_b32 m0, s56
	s_nop 0
	global_load_lds_dwordx4 v[16:17], off
	s_waitcnt vmcnt(8)
	s_waitcnt lgkmcnt(0)
	s_barrier
	s_setprio 1
	s_waitcnt lgkmcnt(0)
	v_mfma_f32_16x16x32_bf16 v[16:19], v[8:11], v[36:39], v[128:131]
	v_mfma_f32_16x16x32_bf16 v[60:63], v[12:15], v[40:43], v[16:19]
	v_mfma_f32_16x16x32_bf16 v[16:19], v[20:23], v[36:39], v[132:135]
	v_mfma_f32_16x16x32_bf16 v[56:59], v[176:179], v[40:43], v[16:19]
	v_mfma_f32_16x16x32_bf16 v[16:19], v[8:11], v[212:215], v[136:139]
	v_mfma_f32_16x16x32_bf16 v[44:47], v[12:15], v[216:219], v[16:19]
	v_mfma_f32_16x16x32_bf16 v[16:19], v[20:23], v[212:215], v[152:155]
	v_mfma_f32_16x16x32_bf16 v[32:35], v[176:179], v[216:219], v[16:19]
	v_mfma_f32_16x16x32_bf16 v[16:19], v[8:11], v[220:223], v[164:167]
	v_mfma_f32_16x16x32_bf16 v[0:3], v[8:11], v[238:241], v[0:3]
	v_mfma_f32_16x16x32_bf16 v[24:27], v[12:15], v[234:237], v[16:19]
	v_mfma_f32_16x16x32_bf16 v[16:19], v[20:23], v[220:223], v[168:171]
	v_mfma_f32_16x16x32_bf16 v[12:15], v[12:15], v[242:245], v[0:3]
	v_mfma_f32_16x16x32_bf16 v[0:3], v[20:23], v[238:241], v[4:7]
	v_mfma_f32_16x16x32_bf16 v[16:19], v[176:179], v[234:237], v[16:19]
	v_mfma_f32_16x16x32_bf16 v[8:11], v[176:179], v[242:245], v[0:3]
	v_mfma_f32_16x16x32_bf16 v[0:3], v[192:195], v[36:39], v[200:203]
	v_mfma_f32_16x16x32_bf16 v[52:55], v[196:199], v[40:43], v[0:3]
	v_mfma_f32_16x16x32_bf16 v[0:3], v[224:227], v[36:39], v[204:207]
	v_mfma_f32_16x16x32_bf16 v[48:51], v[230:233], v[40:43], v[0:3]
	v_mfma_f32_16x16x32_bf16 v[0:3], v[192:195], v[212:215], v[208:211]
	v_mfma_f32_16x16x32_bf16 v[40:43], v[196:199], v[216:219], v[0:3]
	v_mfma_f32_16x16x32_bf16 v[0:3], v[224:227], v[212:215], v[28:31]
	v_mfma_f32_16x16x32_bf16 v[36:39], v[230:233], v[216:219], v[0:3]
	v_mfma_f32_16x16x32_bf16 v[0:3], v[192:195], v[220:223], v[180:183]
	v_mfma_f32_16x16x32_bf16 v[28:31], v[196:199], v[234:237], v[0:3]
	v_mfma_f32_16x16x32_bf16 v[0:3], v[224:227], v[220:223], v[184:187]
	v_mfma_f32_16x16x32_bf16 v[20:23], v[230:233], v[234:237], v[0:3]
	v_mfma_f32_16x16x32_bf16 v[0:3], v[192:195], v[238:241], v[188:191]
	v_mfma_f32_16x16x32_bf16 v[4:7], v[196:199], v[242:245], v[0:3]
	v_mfma_f32_16x16x32_bf16 v[0:3], v[224:227], v[238:241], v[172:175]
	v_mfma_f32_16x16x32_bf16 v[0:3], v[230:233], v[242:245], v[0:3]
	s_setprio 0
	s_barrier
	s_andn2_b64 vcc, exec, s[16:17]
	s_cbranch_vccnz .LBB0_1136
	s_barrier

.LBB0_1281:
	ds_read_b128 v[152:155], v149
	ds_read_b128 v[156:159], v149 offset:1024
	ds_read_b128 v[160:163], v149 offset:2048
	ds_read_b128 v[164:167], v149 offset:3072
	ds_read_b128 v[168:171], v150
	ds_read_b128 v[172:175], v150 offset:1024
	ds_read_b128 v[176:179], v150 offset:2048
	ds_read_b128 v[180:183], v150 offset:3072
	s_add_u32 s28, s26, 0xfffc0080
	s_addc_u32 s29, s27, -1
	s_cmp_eq_u32 s51, 12
	s_cselect_b32 s31, s21, s29
	s_cselect_b32 s30, s47, s28
	s_cselect_b32 s29, s19, s50
	s_cselect_b32 s28, s48, s49
	v_lshl_add_u64 v[144:145], s[26:27], 0, v[138:139]
	s_add_i32 m0, s34, 0xc000
	ds_read_b128 v[184:187], v151
	ds_read_b128 v[188:191], v151 offset:1024
	ds_read_b128 v[192:195], v151 offset:2048
	ds_read_b128 v[196:199], v151 offset:3072
	ds_read_b128 v[200:203], v151 offset:4096
	ds_read_b128 v[204:207], v151 offset:5120
	ds_read_b128 v[208:211], v151 offset:6144
	ds_read_b128 v[212:215], v151 offset:7168
	global_load_lds_dwordx4 v[144:145], off
	v_lshl_add_u64 v[144:145], s[26:27], 0, v[136:137]
	s_add_i32 m0, s34, 0xe000
	s_nop 0
	global_load_lds_dwordx4 v[144:145], off
	s_waitcnt vmcnt(8)
	s_waitcnt lgkmcnt(0)
	s_barrier
	s_setprio 1
	s_waitcnt lgkmcnt(0)
	v_mfma_f32_16x16x32_bf16 v[124:127], v[152:155], v[184:187], v[124:127]
	v_mfma_f32_16x16x32_bf16 v[120:123], v[160:163], v[184:187], v[120:123]
	v_mfma_f32_16x16x32_bf16 v[108:111], v[152:155], v[192:195], v[108:111]
	v_mfma_f32_16x16x32_bf16 v[104:107], v[160:163], v[192:195], v[104:107]
	v_mfma_f32_16x16x32_bf16 v[92:95], v[152:155], v[200:203], v[92:95]
	v_mfma_f32_16x16x32_bf16 v[88:91], v[160:163], v[200:203], v[88:91]
	v_mfma_f32_16x16x32_bf16 v[76:79], v[152:155], v[208:211], v[76:79]
	v_mfma_f32_16x16x32_bf16 v[72:75], v[160:163], v[208:211], v[72:75]
	v_mfma_f32_16x16x32_bf16 v[124:127], v[156:159], v[188:191], v[124:127]
	v_mfma_f32_16x16x32_bf16 v[120:123], v[164:167], v[188:191], v[120:123]
	v_mfma_f32_16x16x32_bf16 v[108:111], v[156:159], v[196:199], v[108:111]
	v_mfma_f32_16x16x32_bf16 v[104:107], v[164:167], v[196:199], v[104:107]
	v_mfma_f32_16x16x32_bf16 v[92:95], v[156:159], v[204:207], v[92:95]
	v_mfma_f32_16x16x32_bf16 v[88:91], v[164:167], v[204:207], v[88:91]
	v_mfma_f32_16x16x32_bf16 v[76:79], v[156:159], v[212:215], v[76:79]
	v_mfma_f32_16x16x32_bf16 v[72:75], v[164:167], v[212:215], v[72:75]
	v_mfma_f32_16x16x32_bf16 v[116:119], v[168:171], v[184:187], v[116:119]
	v_mfma_f32_16x16x32_bf16 v[112:115], v[176:179], v[184:187], v[112:115]
	v_mfma_f32_16x16x32_bf16 v[100:103], v[168:171], v[192:195], v[100:103]
	v_mfma_f32_16x16x32_bf16 v[96:99], v[176:179], v[192:195], v[96:99]
	v_mfma_f32_16x16x32_bf16 v[84:87], v[168:171], v[200:203], v[84:87]
	v_mfma_f32_16x16x32_bf16 v[80:83], v[176:179], v[200:203], v[80:83]
	v_mfma_f32_16x16x32_bf16 v[68:71], v[168:171], v[208:211], v[68:71]
	v_mfma_f32_16x16x32_bf16 v[64:67], v[176:179], v[208:211], v[64:67]
	v_mfma_f32_16x16x32_bf16 v[116:119], v[172:175], v[188:191], v[116:119]
	v_mfma_f32_16x16x32_bf16 v[112:115], v[180:183], v[188:191], v[112:115]
	v_mfma_f32_16x16x32_bf16 v[100:103], v[172:175], v[196:199], v[100:103]
	v_mfma_f32_16x16x32_bf16 v[96:99], v[180:183], v[196:199], v[96:99]
	v_mfma_f32_16x16x32_bf16 v[84:87], v[172:175], v[204:207], v[84:87]
	v_mfma_f32_16x16x32_bf16 v[80:83], v[180:183], v[204:207], v[80:83]
	v_mfma_f32_16x16x32_bf16 v[68:71], v[172:175], v[212:215], v[68:71]
	v_mfma_f32_16x16x32_bf16 v[64:67], v[180:183], v[212:215], v[64:67]
	s_setprio 0
	s_barrier
	s_add_i32 s52, s42, s33
	v_lshl_add_u64 v[144:145], s[28:29], 0, v[132:133]
	s_mov_b32 m0, s52
	ds_read_b128 v[184:187], v151 offset:16384
	ds_read_b128 v[188:191], v151 offset:17408
	ds_read_b128 v[192:195], v151 offset:18432
	ds_read_b128 v[196:199], v151 offset:19456
	ds_read_b128 v[200:203], v151 offset:20480
	ds_read_b128 v[204:207], v151 offset:21504
	ds_read_b128 v[208:211], v151 offset:22528
	ds_read_b128 v[212:215], v151 offset:23552
	global_load_lds_dwordx4 v[144:145], off
	s_add_i32 m0, s52, 0x2000
	s_add_u32 s52, s28, 0x40000
	v_lshl_add_u64 v[216:217], s[28:29], 0, v[128:129]
	s_addc_u32 s53, s29, 0
	s_add_i32 s54, s43, s33
	global_load_lds_dwordx4 v[216:217], off
	v_lshl_add_u64 v[218:219], s[52:53], 0, v[132:133]
	s_mov_b32 m0, s54
	v_lshl_add_u64 v[220:221], s[30:31], 0, v[130:131]
	global_load_lds_dwordx4 v[218:219], off
	v_lshl_add_u64 v[218:219], s[52:53], 0, v[128:129]
	s_add_i32 m0, s54, 0x2000
	s_nop 0
	global_load_lds_dwordx4 v[218:219], off
	v_lshl_add_u64 v[218:219], s[30:31], 0, v[134:135]
	s_mov_b32 m0, s34
	s_nop 0
	global_load_lds_dwordx4 v[218:219], off
	s_mov_b32 m0, s35
	s_nop 0
	global_load_lds_dwordx4 v[220:221], off
	s_waitcnt vmcnt(8)
	s_waitcnt lgkmcnt(0)
	s_barrier
	s_setprio 1
	s_waitcnt lgkmcnt(0)
	v_mfma_f32_16x16x32_bf16 v[60:63], v[152:155], v[184:187], v[60:63]
	v_mfma_f32_16x16x32_bf16 v[56:59], v[160:163], v[184:187], v[56:59]
	v_mfma_f32_16x16x32_bf16 v[44:47], v[152:155], v[192:195], v[44:47]
	v_mfma_f32_16x16x32_bf16 v[40:43], v[160:163], v[192:195], v[40:43]
	v_mfma_f32_16x16x32_bf16 v[28:31], v[152:155], v[200:203], v[28:31]
	v_mfma_f32_16x16x32_bf16 v[24:27], v[160:163], v[200:203], v[24:27]
	v_mfma_f32_16x16x32_bf16 v[12:15], v[152:155], v[208:211], v[12:15]
	v_mfma_f32_16x16x32_bf16 v[8:11], v[160:163], v[208:211], v[8:11]
	v_mfma_f32_16x16x32_bf16 v[60:63], v[156:159], v[188:191], v[60:63]
	v_mfma_f32_16x16x32_bf16 v[56:59], v[164:167], v[188:191], v[56:59]
	v_mfma_f32_16x16x32_bf16 v[44:47], v[156:159], v[196:199], v[44:47]
	v_mfma_f32_16x16x32_bf16 v[40:43], v[164:167], v[196:199], v[40:43]
	v_mfma_f32_16x16x32_bf16 v[28:31], v[156:159], v[204:207], v[28:31]
	v_mfma_f32_16x16x32_bf16 v[24:27], v[164:167], v[204:207], v[24:27]
	v_mfma_f32_16x16x32_bf16 v[12:15], v[156:159], v[212:215], v[12:15]
	v_mfma_f32_16x16x32_bf16 v[8:11], v[164:167], v[212:215], v[8:11]
	v_mfma_f32_16x16x32_bf16 v[52:55], v[168:171], v[184:187], v[52:55]
	v_mfma_f32_16x16x32_bf16 v[48:51], v[176:179], v[184:187], v[48:51]
	v_mfma_f32_16x16x32_bf16 v[36:39], v[168:171], v[192:195], v[36:39]
	v_mfma_f32_16x16x32_bf16 v[32:35], v[176:179], v[192:195], v[32:35]
	v_mfma_f32_16x16x32_bf16 v[20:23], v[168:171], v[200:203], v[20:23]
	v_mfma_f32_16x16x32_bf16 v[16:19], v[176:179], v[200:203], v[16:19]
	v_mfma_f32_16x16x32_bf16 v[4:7], v[168:171], v[208:211], v[4:7]
	v_mfma_f32_16x16x32_bf16 v[0:3], v[176:179], v[208:211], v[0:3]
	v_mfma_f32_16x16x32_bf16 v[52:55], v[172:175], v[188:191], v[52:55]
	v_mfma_f32_16x16x32_bf16 v[48:51], v[180:183], v[188:191], v[48:51]
	v_mfma_f32_16x16x32_bf16 v[36:39], v[172:175], v[196:199], v[36:39]
	v_mfma_f32_16x16x32_bf16 v[32:35], v[180:183], v[196:199], v[32:35]
	v_mfma_f32_16x16x32_bf16 v[20:23], v[172:175], v[204:207], v[20:23]
	v_mfma_f32_16x16x32_bf16 v[16:19], v[180:183], v[204:207], v[16:19]
	v_mfma_f32_16x16x32_bf16 v[4:7], v[172:175], v[212:215], v[4:7]
	v_mfma_f32_16x16x32_bf16 v[0:3], v[180:183], v[212:215], v[0:3]
	s_setprio 0
	s_barrier
	s_add_i32 s52, 0, 0x18000
	s_add_i32 s53, 0, 0x1c000
	v_add_u32_e32 v164, s52, v147
	v_add_u32_e32 v180, s53, v147
	ds_read_b128 v[152:155], v164
	ds_read_b128 v[156:159], v164 offset:1024
	ds_read_b128 v[160:163], v164 offset:2048
	ds_read_b128 v[164:167], v164 offset:3072
	ds_read_b128 v[168:171], v180
	ds_read_b128 v[172:175], v180 offset:1024
	ds_read_b128 v[176:179], v180 offset:2048
	ds_read_b128 v[180:183], v180 offset:3072
	s_add_u32 s30, s30, 0x40000
	s_addc_u32 s31, s31, 0
	s_mov_b32 m0, s36
	v_lshl_add_u64 v[222:223], s[30:31], 0, v[134:135]
	ds_read_b128 v[184:187], v151 offset:32768
	ds_read_b128 v[188:191], v151 offset:33792
	ds_read_b128 v[192:195], v151 offset:34816
	ds_read_b128 v[196:199], v151 offset:35840
	ds_read_b128 v[200:203], v151 offset:36864
	ds_read_b128 v[204:207], v151 offset:37888
	ds_read_b128 v[208:211], v151 offset:38912
	ds_read_b128 v[212:215], v151 offset:39936
	global_load_lds_dwordx4 v[222:223], off
	v_lshl_add_u64 v[222:223], s[30:31], 0, v[130:131]
	s_mov_b32 m0, s37
	s_nop 0
	global_load_lds_dwordx4 v[222:223], off
	s_waitcnt vmcnt(8)
	s_waitcnt lgkmcnt(0)
	s_barrier
	s_setprio 1
	s_waitcnt lgkmcnt(0)
	v_mfma_f32_16x16x32_bf16 v[124:127], v[152:155], v[184:187], v[124:127]
	v_mfma_f32_16x16x32_bf16 v[120:123], v[160:163], v[184:187], v[120:123]
	v_mfma_f32_16x16x32_bf16 v[108:111], v[152:155], v[192:195], v[108:111]
	v_mfma_f32_16x16x32_bf16 v[104:107], v[160:163], v[192:195], v[104:107]
	v_mfma_f32_16x16x32_bf16 v[92:95], v[152:155], v[200:203], v[92:95]
	v_mfma_f32_16x16x32_bf16 v[88:91], v[160:163], v[200:203], v[88:91]
	v_mfma_f32_16x16x32_bf16 v[76:79], v[152:155], v[208:211], v[76:79]
	v_mfma_f32_16x16x32_bf16 v[72:75], v[160:163], v[208:211], v[72:75]
	v_mfma_f32_16x16x32_bf16 v[124:127], v[156:159], v[188:191], v[124:127]
	v_mfma_f32_16x16x32_bf16 v[120:123], v[164:167], v[188:191], v[120:123]
	v_mfma_f32_16x16x32_bf16 v[108:111], v[156:159], v[196:199], v[108:111]
	v_mfma_f32_16x16x32_bf16 v[104:107], v[164:167], v[196:199], v[104:107]
	v_mfma_f32_16x16x32_bf16 v[92:95], v[156:159], v[204:207], v[92:95]
	v_mfma_f32_16x16x32_bf16 v[88:91], v[164:167], v[204:207], v[88:91]
	v_mfma_f32_16x16x32_bf16 v[76:79], v[156:159], v[212:215], v[76:79]
	v_mfma_f32_16x16x32_bf16 v[72:75], v[164:167], v[212:215], v[72:75]
	v_mfma_f32_16x16x32_bf16 v[116:119], v[168:171], v[184:187], v[116:119]
	v_mfma_f32_16x16x32_bf16 v[112:115], v[176:179], v[184:187], v[112:115]
	v_mfma_f32_16x16x32_bf16 v[100:103], v[168:171], v[192:195], v[100:103]
	v_mfma_f32_16x16x32_bf16 v[96:99], v[176:179], v[192:195], v[96:99]
	v_mfma_f32_16x16x32_bf16 v[84:87], v[168:171], v[200:203], v[84:87]
	v_mfma_f32_16x16x32_bf16 v[80:83], v[176:179], v[200:203], v[80:83]
	v_mfma_f32_16x16x32_bf16 v[68:71], v[168:171], v[208:211], v[68:71]
	v_mfma_f32_16x16x32_bf16 v[64:67], v[176:179], v[208:211], v[64:67]
	v_mfma_f32_16x16x32_bf16 v[116:119], v[172:175], v[188:191], v[116:119]
	v_mfma_f32_16x16x32_bf16 v[112:115], v[180:183], v[188:191], v[112:115]
	v_mfma_f32_16x16x32_bf16 v[100:103], v[172:175], v[196:199], v[100:103]
	v_mfma_f32_16x16x32_bf16 v[96:99], v[180:183], v[196:199], v[96:99]
	v_mfma_f32_16x16x32_bf16 v[84:87], v[172:175], v[204:207], v[84:87]
	v_mfma_f32_16x16x32_bf16 v[80:83], v[180:183], v[204:207], v[80:83]
	v_mfma_f32_16x16x32_bf16 v[68:71], v[172:175], v[212:215], v[68:71]
	v_mfma_f32_16x16x32_bf16 v[64:67], v[180:183], v[212:215], v[64:67]
	s_setprio 0
	s_barrier
	s_add_i32 s30, s52, s33
	v_lshl_add_u64 v[144:145], v[144:145], 0, s[14:15]
	s_mov_b32 m0, s30
	ds_read_b128 v[184:187], v151 offset:49152
	ds_read_b128 v[188:191], v151 offset:50176
	ds_read_b128 v[192:195], v151 offset:51200
	ds_read_b128 v[196:199], v151 offset:52224
	ds_read_b128 v[200:203], v151 offset:53248
	ds_read_b128 v[204:207], v151 offset:54272
	ds_read_b128 v[208:211], v151 offset:55296
	ds_read_b128 v[212:215], v151 offset:56320
	global_load_lds_dwordx4 v[144:145], off
	s_add_i32 m0, s30, 0x2000
	s_add_u32 s28, s28, 0x40080
	v_lshl_add_u64 v[144:145], v[216:217], 0, s[14:15]
	s_addc_u32 s29, s29, 0
	s_add_i32 s30, s53, s33
	global_load_lds_dwordx4 v[144:145], off
	v_lshl_add_u64 v[144:145], s[28:29], 0, v[132:133]
	s_mov_b32 m0, s30
	s_nop 0
	global_load_lds_dwordx4 v[144:145], off
	v_lshl_add_u64 v[144:145], s[28:29], 0, v[128:129]
	s_add_i32 m0, s30, 0x2000
	s_nop 0
	global_load_lds_dwordx4 v[144:145], off
	v_lshl_add_u64 v[144:145], v[218:219], 0, s[14:15]
	s_mov_b32 m0, s39
	s_nop 0
	global_load_lds_dwordx4 v[144:145], off
	v_lshl_add_u64 v[144:145], v[220:221], 0, s[14:15]
	s_mov_b32 m0, s40
	s_nop 0
	global_load_lds_dwordx4 v[144:145], off
	s_waitcnt vmcnt(8)
	s_waitcnt lgkmcnt(0)
	s_barrier
	s_setprio 1
	s_waitcnt lgkmcnt(0)
	v_mfma_f32_16x16x32_bf16 v[60:63], v[152:155], v[184:187], v[60:63]
	v_mfma_f32_16x16x32_bf16 v[56:59], v[160:163], v[184:187], v[56:59]
	v_mfma_f32_16x16x32_bf16 v[44:47], v[152:155], v[192:195], v[44:47]
	v_mfma_f32_16x16x32_bf16 v[40:43], v[160:163], v[192:195], v[40:43]
	v_mfma_f32_16x16x32_bf16 v[28:31], v[152:155], v[200:203], v[28:31]
	v_mfma_f32_16x16x32_bf16 v[24:27], v[160:163], v[200:203], v[24:27]
	v_mfma_f32_16x16x32_bf16 v[12:15], v[152:155], v[208:211], v[12:15]
	v_mfma_f32_16x16x32_bf16 v[8:11], v[160:163], v[208:211], v[8:11]
	v_mfma_f32_16x16x32_bf16 v[60:63], v[156:159], v[188:191], v[60:63]
	v_mfma_f32_16x16x32_bf16 v[56:59], v[164:167], v[188:191], v[56:59]
	v_mfma_f32_16x16x32_bf16 v[44:47], v[156:159], v[196:199], v[44:47]
	v_mfma_f32_16x16x32_bf16 v[40:43], v[164:167], v[196:199], v[40:43]
	v_mfma_f32_16x16x32_bf16 v[28:31], v[156:159], v[204:207], v[28:31]
	v_mfma_f32_16x16x32_bf16 v[24:27], v[164:167], v[204:207], v[24:27]
	v_mfma_f32_16x16x32_bf16 v[12:15], v[156:159], v[212:215], v[12:15]
	v_mfma_f32_16x16x32_bf16 v[8:11], v[164:167], v[212:215], v[8:11]
	v_mfma_f32_16x16x32_bf16 v[52:55], v[168:171], v[184:187], v[52:55]
	v_mfma_f32_16x16x32_bf16 v[48:51], v[176:179], v[184:187], v[48:51]
	v_mfma_f32_16x16x32_bf16 v[36:39], v[168:171], v[192:195], v[36:39]
	v_mfma_f32_16x16x32_bf16 v[32:35], v[176:179], v[192:195], v[32:35]
	v_mfma_f32_16x16x32_bf16 v[20:23], v[168:171], v[200:203], v[20:23]
	v_mfma_f32_16x16x32_bf16 v[16:19], v[176:179], v[200:203], v[16:19]
	v_mfma_f32_16x16x32_bf16 v[4:7], v[168:171], v[208:211], v[4:7]
	v_mfma_f32_16x16x32_bf16 v[0:3], v[176:179], v[208:211], v[0:3]
	v_mfma_f32_16x16x32_bf16 v[52:55], v[172:175], v[188:191], v[52:55]
	v_mfma_f32_16x16x32_bf16 v[48:51], v[180:183], v[188:191], v[48:51]
	v_mfma_f32_16x16x32_bf16 v[36:39], v[172:175], v[196:199], v[36:39]
	v_mfma_f32_16x16x32_bf16 v[32:35], v[180:183], v[196:199], v[32:35]
	v_mfma_f32_16x16x32_bf16 v[20:23], v[172:175], v[204:207], v[20:23]
	v_mfma_f32_16x16x32_bf16 v[16:19], v[180:183], v[204:207], v[16:19]
	v_mfma_f32_16x16x32_bf16 v[4:7], v[172:175], v[212:215], v[4:7]
	v_mfma_f32_16x16x32_bf16 v[0:3], v[180:183], v[212:215], v[0:3]
	s_setprio 0
	s_barrier
	s_add_i32 s51, s51, 2
	s_add_u32 s49, s49, 0x100
	s_addc_u32 s50, s50, 0
	s_add_u32 s26, s26, 0x100
	s_addc_u32 s27, s27, 0
	s_cmp_gt_u32 s51, 13
	s_cbranch_scc0 .LBB0_1281
	s_and_b64 vcc, exec, s[16:17]
	s_cbranch_vccz .LBB0_1284
	s_barrier

.LBB0_1513:
	ds_read_b128 v[154:157], v150
	ds_read_b128 v[158:161], v150 offset:1024
	ds_read_b128 v[162:165], v150 offset:2048
	ds_read_b128 v[166:169], v150 offset:3072
	ds_read_b128 v[170:173], v151
	ds_read_b128 v[174:177], v151 offset:1024
	ds_read_b128 v[178:181], v151 offset:2048
	ds_read_b128 v[182:185], v151 offset:3072
	s_add_u32 s40, s38, 0xfffc0080
	s_addc_u32 s41, s39, -1
	s_cmp_eq_u32 s63, 12
	s_cselect_b32 s43, s31, s41
	s_cselect_b32 s42, s59, s40
	s_cselect_b32 s41, s29, s62
	s_cselect_b32 s40, s60, s61
	v_lshl_add_u64 v[146:147], s[38:39], 0, v[138:139]
	s_add_i32 m0, s44, 0xc000
	ds_read_b128 v[186:189], v152
	ds_read_b128 v[190:193], v152 offset:1024
	ds_read_b128 v[194:197], v152 offset:2048
	ds_read_b128 v[198:201], v152 offset:3072
	ds_read_b128 v[202:205], v152 offset:4096
	ds_read_b128 v[206:209], v152 offset:5120
	ds_read_b128 v[210:213], v152 offset:6144
	ds_read_b128 v[214:217], v152 offset:7168
	global_load_lds_dwordx4 v[146:147], off
	v_lshl_add_u64 v[146:147], s[38:39], 0, v[136:137]
	s_add_i32 m0, s44, 0xe000
	s_nop 0
	global_load_lds_dwordx4 v[146:147], off
	s_waitcnt vmcnt(8)
	s_waitcnt lgkmcnt(0)
	s_barrier
	s_setprio 1
	s_waitcnt lgkmcnt(0)
	v_mfma_f32_16x16x32_bf16 v[124:127], v[154:157], v[186:189], v[124:127]
	v_mfma_f32_16x16x32_bf16 v[120:123], v[162:165], v[186:189], v[120:123]
	v_mfma_f32_16x16x32_bf16 v[116:119], v[154:157], v[194:197], v[116:119]
	v_mfma_f32_16x16x32_bf16 v[108:111], v[162:165], v[194:197], v[108:111]
	v_mfma_f32_16x16x32_bf16 v[100:103], v[154:157], v[202:205], v[100:103]
	v_mfma_f32_16x16x32_bf16 v[92:95], v[162:165], v[202:205], v[92:95]
	v_mfma_f32_16x16x32_bf16 v[84:87], v[154:157], v[210:213], v[84:87]
	v_mfma_f32_16x16x32_bf16 v[76:79], v[162:165], v[210:213], v[76:79]
	v_mfma_f32_16x16x32_bf16 v[124:127], v[158:161], v[190:193], v[124:127]
	v_mfma_f32_16x16x32_bf16 v[120:123], v[166:169], v[190:193], v[120:123]
	v_mfma_f32_16x16x32_bf16 v[116:119], v[158:161], v[198:201], v[116:119]
	v_mfma_f32_16x16x32_bf16 v[108:111], v[166:169], v[198:201], v[108:111]
	v_mfma_f32_16x16x32_bf16 v[100:103], v[158:161], v[206:209], v[100:103]
	v_mfma_f32_16x16x32_bf16 v[92:95], v[166:169], v[206:209], v[92:95]
	v_mfma_f32_16x16x32_bf16 v[84:87], v[158:161], v[214:217], v[84:87]
	v_mfma_f32_16x16x32_bf16 v[76:79], v[166:169], v[214:217], v[76:79]
	v_mfma_f32_16x16x32_bf16 v[112:115], v[170:173], v[186:189], v[112:115]
	v_mfma_f32_16x16x32_bf16 v[104:107], v[178:181], v[186:189], v[104:107]
	v_mfma_f32_16x16x32_bf16 v[96:99], v[170:173], v[194:197], v[96:99]
	v_mfma_f32_16x16x32_bf16 v[88:91], v[178:181], v[194:197], v[88:91]
	v_mfma_f32_16x16x32_bf16 v[80:83], v[170:173], v[202:205], v[80:83]
	v_mfma_f32_16x16x32_bf16 v[72:75], v[178:181], v[202:205], v[72:75]
	v_mfma_f32_16x16x32_bf16 v[68:71], v[170:173], v[210:213], v[68:71]
	v_mfma_f32_16x16x32_bf16 v[64:67], v[178:181], v[210:213], v[64:67]
	v_mfma_f32_16x16x32_bf16 v[112:115], v[174:177], v[190:193], v[112:115]
	v_mfma_f32_16x16x32_bf16 v[104:107], v[182:185], v[190:193], v[104:107]
	v_mfma_f32_16x16x32_bf16 v[96:99], v[174:177], v[198:201], v[96:99]
	v_mfma_f32_16x16x32_bf16 v[88:91], v[182:185], v[198:201], v[88:91]
	v_mfma_f32_16x16x32_bf16 v[80:83], v[174:177], v[206:209], v[80:83]
	v_mfma_f32_16x16x32_bf16 v[72:75], v[182:185], v[206:209], v[72:75]
	v_mfma_f32_16x16x32_bf16 v[68:71], v[174:177], v[214:217], v[68:71]
	v_mfma_f32_16x16x32_bf16 v[64:67], v[182:185], v[214:217], v[64:67]
	s_setprio 0
	s_barrier
	s_add_i32 s64, s51, s33
	v_lshl_add_u64 v[146:147], s[40:41], 0, v[132:133]
	s_mov_b32 m0, s64
	ds_read_b128 v[186:189], v152 offset:16384
	ds_read_b128 v[190:193], v152 offset:17408
	ds_read_b128 v[194:197], v152 offset:18432
	ds_read_b128 v[198:201], v152 offset:19456
	ds_read_b128 v[202:205], v152 offset:20480
	ds_read_b128 v[206:209], v152 offset:21504
	ds_read_b128 v[210:213], v152 offset:22528
	ds_read_b128 v[214:217], v152 offset:23552
	global_load_lds_dwordx4 v[146:147], off
	s_add_i32 m0, s64, 0x2000
	s_add_u32 s64, s40, 0x40000
	v_lshl_add_u64 v[218:219], s[40:41], 0, v[128:129]
	s_addc_u32 s65, s41, 0
	s_add_i32 s66, s52, s33
	global_load_lds_dwordx4 v[218:219], off
	v_lshl_add_u64 v[220:221], s[64:65], 0, v[132:133]
	s_mov_b32 m0, s66
	v_lshl_add_u64 v[222:223], s[42:43], 0, v[130:131]
	global_load_lds_dwordx4 v[220:221], off
	v_lshl_add_u64 v[220:221], s[64:65], 0, v[128:129]
	s_add_i32 m0, s66, 0x2000
	s_nop 0
	global_load_lds_dwordx4 v[220:221], off
	v_lshl_add_u64 v[220:221], s[42:43], 0, v[134:135]
	s_mov_b32 m0, s44
	s_nop 0
	global_load_lds_dwordx4 v[220:221], off
	s_mov_b32 m0, s45
	s_nop 0
	global_load_lds_dwordx4 v[222:223], off
	s_waitcnt vmcnt(8)
	s_waitcnt lgkmcnt(0)
	s_barrier
	s_setprio 1
	s_waitcnt lgkmcnt(0)
	v_mfma_f32_16x16x32_bf16 v[60:63], v[154:157], v[186:189], v[60:63]
	v_mfma_f32_16x16x32_bf16 v[56:59], v[162:165], v[186:189], v[56:59]
	v_mfma_f32_16x16x32_bf16 v[52:55], v[154:157], v[194:197], v[52:55]
	v_mfma_f32_16x16x32_bf16 v[44:47], v[162:165], v[194:197], v[44:47]
	v_mfma_f32_16x16x32_bf16 v[36:39], v[154:157], v[202:205], v[36:39]
	v_mfma_f32_16x16x32_bf16 v[28:31], v[162:165], v[202:205], v[28:31]
	v_mfma_f32_16x16x32_bf16 v[20:23], v[154:157], v[210:213], v[20:23]
	v_mfma_f32_16x16x32_bf16 v[12:15], v[162:165], v[210:213], v[12:15]
	v_mfma_f32_16x16x32_bf16 v[60:63], v[158:161], v[190:193], v[60:63]
	v_mfma_f32_16x16x32_bf16 v[56:59], v[166:169], v[190:193], v[56:59]
	v_mfma_f32_16x16x32_bf16 v[52:55], v[158:161], v[198:201], v[52:55]
	v_mfma_f32_16x16x32_bf16 v[44:47], v[166:169], v[198:201], v[44:47]
	v_mfma_f32_16x16x32_bf16 v[36:39], v[158:161], v[206:209], v[36:39]
	v_mfma_f32_16x16x32_bf16 v[28:31], v[166:169], v[206:209], v[28:31]
	v_mfma_f32_16x16x32_bf16 v[20:23], v[158:161], v[214:217], v[20:23]
	v_mfma_f32_16x16x32_bf16 v[12:15], v[166:169], v[214:217], v[12:15]
	v_mfma_f32_16x16x32_bf16 v[48:51], v[170:173], v[186:189], v[48:51]
	v_mfma_f32_16x16x32_bf16 v[40:43], v[178:181], v[186:189], v[40:43]
	v_mfma_f32_16x16x32_bf16 v[32:35], v[170:173], v[194:197], v[32:35]
	v_mfma_f32_16x16x32_bf16 v[24:27], v[178:181], v[194:197], v[24:27]
	v_mfma_f32_16x16x32_bf16 v[16:19], v[170:173], v[202:205], v[16:19]
	v_mfma_f32_16x16x32_bf16 v[8:11], v[178:181], v[202:205], v[8:11]
	v_mfma_f32_16x16x32_bf16 v[4:7], v[170:173], v[210:213], v[4:7]
	v_mfma_f32_16x16x32_bf16 v[0:3], v[178:181], v[210:213], v[0:3]
	v_mfma_f32_16x16x32_bf16 v[48:51], v[174:177], v[190:193], v[48:51]
	v_mfma_f32_16x16x32_bf16 v[40:43], v[182:185], v[190:193], v[40:43]
	v_mfma_f32_16x16x32_bf16 v[32:35], v[174:177], v[198:201], v[32:35]
	v_mfma_f32_16x16x32_bf16 v[24:27], v[182:185], v[198:201], v[24:27]
	v_mfma_f32_16x16x32_bf16 v[16:19], v[174:177], v[206:209], v[16:19]
	v_mfma_f32_16x16x32_bf16 v[8:11], v[182:185], v[206:209], v[8:11]
	v_mfma_f32_16x16x32_bf16 v[4:7], v[174:177], v[214:217], v[4:7]
	v_mfma_f32_16x16x32_bf16 v[0:3], v[182:185], v[214:217], v[0:3]
	s_setprio 0
	s_barrier
	s_add_i32 s64, 0, 0x18000
	v_add_u32_e32 v144, s64, v148
	s_add_i32 s65, 0, 0x1c000
	ds_read_b128 v[154:157], v144
	ds_read_b128 v[158:161], v144 offset:1024
	ds_read_b128 v[162:165], v144 offset:2048
	ds_read_b128 v[166:169], v144 offset:3072
	v_add_u32_e32 v144, s65, v148
	ds_read_b128 v[170:173], v144
	ds_read_b128 v[174:177], v144 offset:1024
	ds_read_b128 v[178:181], v144 offset:2048
	ds_read_b128 v[182:185], v144 offset:3072
	s_add_u32 s42, s42, 0x40000
	s_addc_u32 s43, s43, 0
	s_mov_b32 m0, s46
	v_lshl_add_u64 v[224:225], s[42:43], 0, v[134:135]
	ds_read_b128 v[186:189], v152 offset:32768
	ds_read_b128 v[190:193], v152 offset:33792
	ds_read_b128 v[194:197], v152 offset:34816
	ds_read_b128 v[198:201], v152 offset:35840
	ds_read_b128 v[202:205], v152 offset:36864
	ds_read_b128 v[206:209], v152 offset:37888
	ds_read_b128 v[210:213], v152 offset:38912
	ds_read_b128 v[214:217], v152 offset:39936
	global_load_lds_dwordx4 v[224:225], off
	v_lshl_add_u64 v[224:225], s[42:43], 0, v[130:131]
	s_mov_b32 m0, s47
	s_nop 0
	global_load_lds_dwordx4 v[224:225], off
	s_waitcnt vmcnt(8)
	s_waitcnt lgkmcnt(0)
	s_barrier
	s_setprio 1
	s_waitcnt lgkmcnt(0)
	v_mfma_f32_16x16x32_bf16 v[124:127], v[154:157], v[186:189], v[124:127]
	v_mfma_f32_16x16x32_bf16 v[120:123], v[162:165], v[186:189], v[120:123]
	v_mfma_f32_16x16x32_bf16 v[116:119], v[154:157], v[194:197], v[116:119]
	v_mfma_f32_16x16x32_bf16 v[108:111], v[162:165], v[194:197], v[108:111]
	v_mfma_f32_16x16x32_bf16 v[100:103], v[154:157], v[202:205], v[100:103]
	v_mfma_f32_16x16x32_bf16 v[92:95], v[162:165], v[202:205], v[92:95]
	v_mfma_f32_16x16x32_bf16 v[84:87], v[154:157], v[210:213], v[84:87]
	v_mfma_f32_16x16x32_bf16 v[76:79], v[162:165], v[210:213], v[76:79]
	v_mfma_f32_16x16x32_bf16 v[124:127], v[158:161], v[190:193], v[124:127]
	v_mfma_f32_16x16x32_bf16 v[120:123], v[166:169], v[190:193], v[120:123]
	v_mfma_f32_16x16x32_bf16 v[116:119], v[158:161], v[198:201], v[116:119]
	v_mfma_f32_16x16x32_bf16 v[108:111], v[166:169], v[198:201], v[108:111]
	v_mfma_f32_16x16x32_bf16 v[100:103], v[158:161], v[206:209], v[100:103]
	v_mfma_f32_16x16x32_bf16 v[92:95], v[166:169], v[206:209], v[92:95]
	v_mfma_f32_16x16x32_bf16 v[84:87], v[158:161], v[214:217], v[84:87]
	v_mfma_f32_16x16x32_bf16 v[76:79], v[166:169], v[214:217], v[76:79]
	v_mfma_f32_16x16x32_bf16 v[112:115], v[170:173], v[186:189], v[112:115]
	v_mfma_f32_16x16x32_bf16 v[104:107], v[178:181], v[186:189], v[104:107]
	v_mfma_f32_16x16x32_bf16 v[96:99], v[170:173], v[194:197], v[96:99]
	v_mfma_f32_16x16x32_bf16 v[88:91], v[178:181], v[194:197], v[88:91]
	v_mfma_f32_16x16x32_bf16 v[80:83], v[170:173], v[202:205], v[80:83]
	v_mfma_f32_16x16x32_bf16 v[72:75], v[178:181], v[202:205], v[72:75]
	v_mfma_f32_16x16x32_bf16 v[68:71], v[170:173], v[210:213], v[68:71]
	v_mfma_f32_16x16x32_bf16 v[64:67], v[178:181], v[210:213], v[64:67]
	v_mfma_f32_16x16x32_bf16 v[112:115], v[174:177], v[190:193], v[112:115]
	v_mfma_f32_16x16x32_bf16 v[104:107], v[182:185], v[190:193], v[104:107]
	v_mfma_f32_16x16x32_bf16 v[96:99], v[174:177], v[198:201], v[96:99]
	v_mfma_f32_16x16x32_bf16 v[88:91], v[182:185], v[198:201], v[88:91]
	v_mfma_f32_16x16x32_bf16 v[80:83], v[174:177], v[206:209], v[80:83]
	v_mfma_f32_16x16x32_bf16 v[72:75], v[182:185], v[206:209], v[72:75]
	v_mfma_f32_16x16x32_bf16 v[68:71], v[174:177], v[214:217], v[68:71]
	v_mfma_f32_16x16x32_bf16 v[64:67], v[182:185], v[214:217], v[64:67]
	s_setprio 0
	s_barrier
	s_add_i32 s42, s64, s33
	v_lshl_add_u64 v[146:147], v[146:147], 0, s[18:19]
	s_mov_b32 m0, s42
	ds_read_b128 v[186:189], v152 offset:49152
	ds_read_b128 v[190:193], v152 offset:50176
	ds_read_b128 v[194:197], v152 offset:51200
	ds_read_b128 v[198:201], v152 offset:52224
	ds_read_b128 v[202:205], v152 offset:53248
	ds_read_b128 v[206:209], v152 offset:54272
	ds_read_b128 v[210:213], v152 offset:55296
	ds_read_b128 v[214:217], v152 offset:56320
	global_load_lds_dwordx4 v[146:147], off
	s_add_i32 m0, s42, 0x2000
	s_add_u32 s40, s40, 0x40080
	v_lshl_add_u64 v[146:147], v[218:219], 0, s[18:19]
	s_addc_u32 s41, s41, 0
	s_add_i32 s42, s65, s33
	global_load_lds_dwordx4 v[146:147], off
	v_lshl_add_u64 v[146:147], s[40:41], 0, v[132:133]
	s_mov_b32 m0, s42
	s_nop 0
	global_load_lds_dwordx4 v[146:147], off
	v_lshl_add_u64 v[146:147], s[40:41], 0, v[128:129]
	s_add_i32 m0, s42, 0x2000
	s_nop 0
	global_load_lds_dwordx4 v[146:147], off
	v_lshl_add_u64 v[146:147], v[220:221], 0, s[18:19]
	s_mov_b32 m0, s49
	s_nop 0
	global_load_lds_dwordx4 v[146:147], off
	v_lshl_add_u64 v[146:147], v[222:223], 0, s[18:19]
	s_mov_b32 m0, s50
	s_nop 0
	global_load_lds_dwordx4 v[146:147], off
	s_waitcnt vmcnt(8)
	s_waitcnt lgkmcnt(0)
	s_barrier
	s_setprio 1
	s_waitcnt lgkmcnt(0)
	v_mfma_f32_16x16x32_bf16 v[60:63], v[154:157], v[186:189], v[60:63]
	v_mfma_f32_16x16x32_bf16 v[56:59], v[162:165], v[186:189], v[56:59]
	v_mfma_f32_16x16x32_bf16 v[52:55], v[154:157], v[194:197], v[52:55]
	v_mfma_f32_16x16x32_bf16 v[44:47], v[162:165], v[194:197], v[44:47]
	v_mfma_f32_16x16x32_bf16 v[36:39], v[154:157], v[202:205], v[36:39]
	v_mfma_f32_16x16x32_bf16 v[28:31], v[162:165], v[202:205], v[28:31]
	v_mfma_f32_16x16x32_bf16 v[20:23], v[154:157], v[210:213], v[20:23]
	v_mfma_f32_16x16x32_bf16 v[12:15], v[162:165], v[210:213], v[12:15]
	v_mfma_f32_16x16x32_bf16 v[60:63], v[158:161], v[190:193], v[60:63]
	v_mfma_f32_16x16x32_bf16 v[56:59], v[166:169], v[190:193], v[56:59]
	v_mfma_f32_16x16x32_bf16 v[52:55], v[158:161], v[198:201], v[52:55]
	v_mfma_f32_16x16x32_bf16 v[44:47], v[166:169], v[198:201], v[44:47]
	v_mfma_f32_16x16x32_bf16 v[36:39], v[158:161], v[206:209], v[36:39]
	v_mfma_f32_16x16x32_bf16 v[28:31], v[166:169], v[206:209], v[28:31]
	v_mfma_f32_16x16x32_bf16 v[20:23], v[158:161], v[214:217], v[20:23]
	v_mfma_f32_16x16x32_bf16 v[12:15], v[166:169], v[214:217], v[12:15]
	v_mfma_f32_16x16x32_bf16 v[48:51], v[170:173], v[186:189], v[48:51]
	v_mfma_f32_16x16x32_bf16 v[40:43], v[178:181], v[186:189], v[40:43]
	v_mfma_f32_16x16x32_bf16 v[32:35], v[170:173], v[194:197], v[32:35]
	v_mfma_f32_16x16x32_bf16 v[24:27], v[178:181], v[194:197], v[24:27]
	v_mfma_f32_16x16x32_bf16 v[16:19], v[170:173], v[202:205], v[16:19]
	v_mfma_f32_16x16x32_bf16 v[8:11], v[178:181], v[202:205], v[8:11]
	v_mfma_f32_16x16x32_bf16 v[4:7], v[170:173], v[210:213], v[4:7]
	v_mfma_f32_16x16x32_bf16 v[0:3], v[178:181], v[210:213], v[0:3]
	v_mfma_f32_16x16x32_bf16 v[48:51], v[174:177], v[190:193], v[48:51]
	v_mfma_f32_16x16x32_bf16 v[40:43], v[182:185], v[190:193], v[40:43]
	v_mfma_f32_16x16x32_bf16 v[32:35], v[174:177], v[198:201], v[32:35]
	v_mfma_f32_16x16x32_bf16 v[24:27], v[182:185], v[198:201], v[24:27]
	v_mfma_f32_16x16x32_bf16 v[16:19], v[174:177], v[206:209], v[16:19]
	v_mfma_f32_16x16x32_bf16 v[8:11], v[182:185], v[206:209], v[8:11]
	v_mfma_f32_16x16x32_bf16 v[4:7], v[174:177], v[214:217], v[4:7]
	v_mfma_f32_16x16x32_bf16 v[0:3], v[182:185], v[214:217], v[0:3]
	s_setprio 0
	s_barrier
	s_add_i32 s63, s63, 2
	s_add_u32 s61, s61, 0x100
	s_addc_u32 s62, s62, 0
	s_add_u32 s38, s38, 0x100
	s_addc_u32 s39, s39, 0
	s_cmp_gt_u32 s63, 13
	s_cbranch_scc0 .LBB0_1513
	s_and_b64 vcc, exec, s[20:21]
	s_cbranch_vccz .LBB0_1516
	s_barrier

.LBB0_1529:
	ds_read_b128 v[150:153], v147
	ds_read_b128 v[154:157], v147 offset:1024
	ds_read_b128 v[158:161], v147 offset:2048
	ds_read_b128 v[162:165], v147 offset:3072
	ds_read_b128 v[166:169], v148
	ds_read_b128 v[170:173], v148 offset:1024
	ds_read_b128 v[174:177], v148 offset:2048
	ds_read_b128 v[178:181], v148 offset:3072
	s_add_u32 s40, s38, 0xfffc0080
	s_addc_u32 s41, s39, -1
	s_cmp_eq_u32 s62, 12
	s_cselect_b32 s43, s31, s41
	s_cselect_b32 s42, s58, s40
	s_cselect_b32 s41, s29, s61
	s_cselect_b32 s40, s59, s60
	v_lshl_add_u64 v[214:215], s[38:39], 0, v[138:139]
	s_add_i32 m0, s27, 0xc000
	ds_read_b128 v[182:185], v149
	ds_read_b128 v[186:189], v149 offset:1024
	ds_read_b128 v[190:193], v149 offset:2048
	ds_read_b128 v[194:197], v149 offset:3072
	ds_read_b128 v[198:201], v149 offset:4096
	ds_read_b128 v[202:205], v149 offset:5120
	ds_read_b128 v[206:209], v149 offset:6144
	ds_read_b128 v[210:213], v149 offset:7168
	global_load_lds_dwordx4 v[214:215], off
	v_lshl_add_u64 v[214:215], s[38:39], 0, v[136:137]
	s_add_i32 m0, s27, 0xe000
	s_nop 0
	global_load_lds_dwordx4 v[214:215], off
	s_waitcnt vmcnt(8)
	s_waitcnt lgkmcnt(0)
	s_barrier
	s_setprio 1
	s_waitcnt lgkmcnt(0)
	v_mfma_f32_16x16x32_bf16 v[124:127], v[150:153], v[182:185], v[124:127]
	v_mfma_f32_16x16x32_bf16 v[120:123], v[158:161], v[182:185], v[120:123]
	v_mfma_f32_16x16x32_bf16 v[116:119], v[150:153], v[190:193], v[116:119]
	v_mfma_f32_16x16x32_bf16 v[112:115], v[158:161], v[190:193], v[112:115]
	v_mfma_f32_16x16x32_bf16 v[100:103], v[150:153], v[198:201], v[100:103]
	v_mfma_f32_16x16x32_bf16 v[96:99], v[158:161], v[198:201], v[96:99]
	v_mfma_f32_16x16x32_bf16 v[84:87], v[150:153], v[206:209], v[84:87]
	v_mfma_f32_16x16x32_bf16 v[80:83], v[158:161], v[206:209], v[80:83]
	v_mfma_f32_16x16x32_bf16 v[124:127], v[154:157], v[186:189], v[124:127]
	v_mfma_f32_16x16x32_bf16 v[120:123], v[162:165], v[186:189], v[120:123]
	v_mfma_f32_16x16x32_bf16 v[116:119], v[154:157], v[194:197], v[116:119]
	v_mfma_f32_16x16x32_bf16 v[112:115], v[162:165], v[194:197], v[112:115]
	v_mfma_f32_16x16x32_bf16 v[100:103], v[154:157], v[202:205], v[100:103]
	v_mfma_f32_16x16x32_bf16 v[96:99], v[162:165], v[202:205], v[96:99]
	v_mfma_f32_16x16x32_bf16 v[84:87], v[154:157], v[210:213], v[84:87]
	v_mfma_f32_16x16x32_bf16 v[80:83], v[162:165], v[210:213], v[80:83]
	v_mfma_f32_16x16x32_bf16 v[108:111], v[166:169], v[182:185], v[108:111]
	v_mfma_f32_16x16x32_bf16 v[104:107], v[174:177], v[182:185], v[104:107]
	v_mfma_f32_16x16x32_bf16 v[92:95], v[166:169], v[190:193], v[92:95]
	v_mfma_f32_16x16x32_bf16 v[88:91], v[174:177], v[190:193], v[88:91]
	v_mfma_f32_16x16x32_bf16 v[76:79], v[166:169], v[198:201], v[76:79]
	v_mfma_f32_16x16x32_bf16 v[72:75], v[174:177], v[198:201], v[72:75]
	v_mfma_f32_16x16x32_bf16 v[68:71], v[166:169], v[206:209], v[68:71]
	v_mfma_f32_16x16x32_bf16 v[64:67], v[174:177], v[206:209], v[64:67]
	v_mfma_f32_16x16x32_bf16 v[108:111], v[170:173], v[186:189], v[108:111]
	v_mfma_f32_16x16x32_bf16 v[104:107], v[178:181], v[186:189], v[104:107]
	v_mfma_f32_16x16x32_bf16 v[92:95], v[170:173], v[194:197], v[92:95]
	v_mfma_f32_16x16x32_bf16 v[88:91], v[178:181], v[194:197], v[88:91]
	v_mfma_f32_16x16x32_bf16 v[76:79], v[170:173], v[202:205], v[76:79]
	v_mfma_f32_16x16x32_bf16 v[72:75], v[178:181], v[202:205], v[72:75]
	v_mfma_f32_16x16x32_bf16 v[68:71], v[170:173], v[210:213], v[68:71]
	v_mfma_f32_16x16x32_bf16 v[64:67], v[178:181], v[210:213], v[64:67]
	s_setprio 0
	s_barrier
	s_add_i32 s63, s51, s33
	v_lshl_add_u64 v[214:215], s[40:41], 0, v[132:133]
	s_mov_b32 m0, s63
	ds_read_b128 v[182:185], v149 offset:16384
	ds_read_b128 v[186:189], v149 offset:17408
	ds_read_b128 v[190:193], v149 offset:18432
	ds_read_b128 v[194:197], v149 offset:19456
	ds_read_b128 v[198:201], v149 offset:20480
	ds_read_b128 v[202:205], v149 offset:21504
	ds_read_b128 v[206:209], v149 offset:22528
	ds_read_b128 v[210:213], v149 offset:23552
	global_load_lds_dwordx4 v[214:215], off
	s_add_i32 m0, s63, 0x2000
	s_add_u32 s64, s40, 0x40000
	v_lshl_add_u64 v[216:217], s[40:41], 0, v[128:129]
	s_addc_u32 s65, s41, 0
	s_add_i32 s63, s52, s33
	global_load_lds_dwordx4 v[216:217], off
	v_lshl_add_u64 v[218:219], s[64:65], 0, v[132:133]
	s_mov_b32 m0, s63
	v_lshl_add_u64 v[220:221], s[42:43], 0, v[130:131]
	global_load_lds_dwordx4 v[218:219], off
	v_lshl_add_u64 v[218:219], s[64:65], 0, v[128:129]
	s_add_i32 m0, s63, 0x2000
	s_nop 0
	global_load_lds_dwordx4 v[218:219], off
	v_lshl_add_u64 v[218:219], s[42:43], 0, v[134:135]
	s_mov_b32 m0, s27
	s_nop 0
	global_load_lds_dwordx4 v[218:219], off
	s_mov_b32 m0, s45
	s_nop 0
	global_load_lds_dwordx4 v[220:221], off
	s_waitcnt vmcnt(8)
	s_waitcnt lgkmcnt(0)
	s_barrier
	s_setprio 1
	s_waitcnt lgkmcnt(0)
	v_mfma_f32_16x16x32_bf16 v[60:63], v[150:153], v[182:185], v[60:63]
	v_mfma_f32_16x16x32_bf16 v[56:59], v[158:161], v[182:185], v[56:59]
	v_mfma_f32_16x16x32_bf16 v[52:55], v[150:153], v[190:193], v[52:55]
	v_mfma_f32_16x16x32_bf16 v[48:51], v[158:161], v[190:193], v[48:51]
	v_mfma_f32_16x16x32_bf16 v[36:39], v[150:153], v[198:201], v[36:39]
	v_mfma_f32_16x16x32_bf16 v[32:35], v[158:161], v[198:201], v[32:35]
	v_mfma_f32_16x16x32_bf16 v[20:23], v[150:153], v[206:209], v[20:23]
	v_mfma_f32_16x16x32_bf16 v[16:19], v[158:161], v[206:209], v[16:19]
	v_mfma_f32_16x16x32_bf16 v[60:63], v[154:157], v[186:189], v[60:63]
	v_mfma_f32_16x16x32_bf16 v[56:59], v[162:165], v[186:189], v[56:59]
	v_mfma_f32_16x16x32_bf16 v[52:55], v[154:157], v[194:197], v[52:55]
	v_mfma_f32_16x16x32_bf16 v[48:51], v[162:165], v[194:197], v[48:51]
	v_mfma_f32_16x16x32_bf16 v[36:39], v[154:157], v[202:205], v[36:39]
	v_mfma_f32_16x16x32_bf16 v[32:35], v[162:165], v[202:205], v[32:35]
	v_mfma_f32_16x16x32_bf16 v[20:23], v[154:157], v[210:213], v[20:23]
	v_mfma_f32_16x16x32_bf16 v[16:19], v[162:165], v[210:213], v[16:19]
	v_mfma_f32_16x16x32_bf16 v[44:47], v[166:169], v[182:185], v[44:47]
	v_mfma_f32_16x16x32_bf16 v[40:43], v[174:177], v[182:185], v[40:43]
	v_mfma_f32_16x16x32_bf16 v[28:31], v[166:169], v[190:193], v[28:31]
	v_mfma_f32_16x16x32_bf16 v[24:27], v[174:177], v[190:193], v[24:27]
	v_mfma_f32_16x16x32_bf16 v[12:15], v[166:169], v[198:201], v[12:15]
	v_mfma_f32_16x16x32_bf16 v[8:11], v[174:177], v[198:201], v[8:11]
	v_mfma_f32_16x16x32_bf16 v[4:7], v[166:169], v[206:209], v[4:7]
	v_mfma_f32_16x16x32_bf16 v[0:3], v[174:177], v[206:209], v[0:3]
	v_mfma_f32_16x16x32_bf16 v[44:47], v[170:173], v[186:189], v[44:47]
	v_mfma_f32_16x16x32_bf16 v[40:43], v[178:181], v[186:189], v[40:43]
	v_mfma_f32_16x16x32_bf16 v[28:31], v[170:173], v[194:197], v[28:31]
	v_mfma_f32_16x16x32_bf16 v[24:27], v[178:181], v[194:197], v[24:27]
	v_mfma_f32_16x16x32_bf16 v[12:15], v[170:173], v[202:205], v[12:15]
	v_mfma_f32_16x16x32_bf16 v[8:11], v[178:181], v[202:205], v[8:11]
	v_mfma_f32_16x16x32_bf16 v[4:7], v[170:173], v[210:213], v[4:7]
	v_mfma_f32_16x16x32_bf16 v[0:3], v[178:181], v[210:213], v[0:3]
	s_setprio 0
	s_barrier
	s_add_i32 s63, 0, 0x18000
	s_add_i32 s64, 0, 0x1c000
	v_add_u32_e32 v162, s63, v145
	v_add_u32_e32 v178, s64, v145
	ds_read_b128 v[150:153], v162
	ds_read_b128 v[154:157], v162 offset:1024
	ds_read_b128 v[158:161], v162 offset:2048
	ds_read_b128 v[162:165], v162 offset:3072
	ds_read_b128 v[166:169], v178
	ds_read_b128 v[170:173], v178 offset:1024
	ds_read_b128 v[174:177], v178 offset:2048
	ds_read_b128 v[178:181], v178 offset:3072
	s_add_u32 s42, s42, 0x40000
	s_addc_u32 s43, s43, 0
	s_mov_b32 m0, s46
	v_lshl_add_u64 v[222:223], s[42:43], 0, v[134:135]
	ds_read_b128 v[182:185], v149 offset:32768
	ds_read_b128 v[186:189], v149 offset:33792
	ds_read_b128 v[190:193], v149 offset:34816
	ds_read_b128 v[194:197], v149 offset:35840
	ds_read_b128 v[198:201], v149 offset:36864
	ds_read_b128 v[202:205], v149 offset:37888
	ds_read_b128 v[206:209], v149 offset:38912
	ds_read_b128 v[210:213], v149 offset:39936
	global_load_lds_dwordx4 v[222:223], off
	v_lshl_add_u64 v[222:223], s[42:43], 0, v[130:131]
	s_mov_b32 m0, s47
	s_nop 0
	global_load_lds_dwordx4 v[222:223], off
	s_waitcnt vmcnt(8)
	s_waitcnt lgkmcnt(0)
	s_barrier
	s_setprio 1
	s_waitcnt lgkmcnt(0)
	v_mfma_f32_16x16x32_bf16 v[124:127], v[150:153], v[182:185], v[124:127]
	v_mfma_f32_16x16x32_bf16 v[120:123], v[158:161], v[182:185], v[120:123]
	v_mfma_f32_16x16x32_bf16 v[116:119], v[150:153], v[190:193], v[116:119]
	v_mfma_f32_16x16x32_bf16 v[112:115], v[158:161], v[190:193], v[112:115]
	v_mfma_f32_16x16x32_bf16 v[100:103], v[150:153], v[198:201], v[100:103]
	v_mfma_f32_16x16x32_bf16 v[96:99], v[158:161], v[198:201], v[96:99]
	v_mfma_f32_16x16x32_bf16 v[84:87], v[150:153], v[206:209], v[84:87]
	v_mfma_f32_16x16x32_bf16 v[80:83], v[158:161], v[206:209], v[80:83]
	v_mfma_f32_16x16x32_bf16 v[124:127], v[154:157], v[186:189], v[124:127]
	v_mfma_f32_16x16x32_bf16 v[120:123], v[162:165], v[186:189], v[120:123]
	v_mfma_f32_16x16x32_bf16 v[116:119], v[154:157], v[194:197], v[116:119]
	v_mfma_f32_16x16x32_bf16 v[112:115], v[162:165], v[194:197], v[112:115]
	v_mfma_f32_16x16x32_bf16 v[100:103], v[154:157], v[202:205], v[100:103]
	v_mfma_f32_16x16x32_bf16 v[96:99], v[162:165], v[202:205], v[96:99]
	v_mfma_f32_16x16x32_bf16 v[84:87], v[154:157], v[210:213], v[84:87]
	v_mfma_f32_16x16x32_bf16 v[80:83], v[162:165], v[210:213], v[80:83]
	v_mfma_f32_16x16x32_bf16 v[108:111], v[166:169], v[182:185], v[108:111]
	v_mfma_f32_16x16x32_bf16 v[104:107], v[174:177], v[182:185], v[104:107]
	v_mfma_f32_16x16x32_bf16 v[92:95], v[166:169], v[190:193], v[92:95]
	v_mfma_f32_16x16x32_bf16 v[88:91], v[174:177], v[190:193], v[88:91]
	v_mfma_f32_16x16x32_bf16 v[76:79], v[166:169], v[198:201], v[76:79]
	v_mfma_f32_16x16x32_bf16 v[72:75], v[174:177], v[198:201], v[72:75]
	v_mfma_f32_16x16x32_bf16 v[68:71], v[166:169], v[206:209], v[68:71]
	v_mfma_f32_16x16x32_bf16 v[64:67], v[174:177], v[206:209], v[64:67]
	v_mfma_f32_16x16x32_bf16 v[108:111], v[170:173], v[186:189], v[108:111]
	v_mfma_f32_16x16x32_bf16 v[104:107], v[178:181], v[186:189], v[104:107]
	v_mfma_f32_16x16x32_bf16 v[92:95], v[170:173], v[194:197], v[92:95]
	v_mfma_f32_16x16x32_bf16 v[88:91], v[178:181], v[194:197], v[88:91]
	v_mfma_f32_16x16x32_bf16 v[76:79], v[170:173], v[202:205], v[76:79]
	v_mfma_f32_16x16x32_bf16 v[72:75], v[178:181], v[202:205], v[72:75]
	v_mfma_f32_16x16x32_bf16 v[68:71], v[170:173], v[210:213], v[68:71]
	v_mfma_f32_16x16x32_bf16 v[64:67], v[178:181], v[210:213], v[64:67]
	s_setprio 0
	s_barrier
	s_add_i32 s42, s63, s33
	v_lshl_add_u64 v[214:215], v[214:215], 0, s[16:17]
	s_mov_b32 m0, s42
	ds_read_b128 v[182:185], v149 offset:49152
	ds_read_b128 v[186:189], v149 offset:50176
	ds_read_b128 v[190:193], v149 offset:51200
	ds_read_b128 v[194:197], v149 offset:52224
	ds_read_b128 v[198:201], v149 offset:53248
	ds_read_b128 v[202:205], v149 offset:54272
	ds_read_b128 v[206:209], v149 offset:55296
	ds_read_b128 v[210:213], v149 offset:56320
	global_load_lds_dwordx4 v[214:215], off
	s_add_i32 m0, s42, 0x2000
	s_add_u32 s40, s40, 0x40080
	v_lshl_add_u64 v[214:215], v[216:217], 0, s[16:17]
	s_addc_u32 s41, s41, 0
	s_add_i32 s42, s64, s33
	global_load_lds_dwordx4 v[214:215], off
	v_lshl_add_u64 v[214:215], s[40:41], 0, v[132:133]
	s_mov_b32 m0, s42
	s_nop 0
	global_load_lds_dwordx4 v[214:215], off
	v_lshl_add_u64 v[214:215], s[40:41], 0, v[128:129]
	s_add_i32 m0, s42, 0x2000
	s_nop 0
	global_load_lds_dwordx4 v[214:215], off
	v_lshl_add_u64 v[214:215], v[218:219], 0, s[16:17]
	s_mov_b32 m0, s49
	s_nop 0
	global_load_lds_dwordx4 v[214:215], off
	v_lshl_add_u64 v[214:215], v[220:221], 0, s[16:17]
	s_mov_b32 m0, s50
	s_nop 0
	global_load_lds_dwordx4 v[214:215], off
	s_waitcnt vmcnt(8)
	s_waitcnt lgkmcnt(0)
	s_barrier
	s_setprio 1
	s_waitcnt lgkmcnt(0)
	v_mfma_f32_16x16x32_bf16 v[60:63], v[150:153], v[182:185], v[60:63]
	v_mfma_f32_16x16x32_bf16 v[56:59], v[158:161], v[182:185], v[56:59]
	v_mfma_f32_16x16x32_bf16 v[52:55], v[150:153], v[190:193], v[52:55]
	v_mfma_f32_16x16x32_bf16 v[48:51], v[158:161], v[190:193], v[48:51]
	v_mfma_f32_16x16x32_bf16 v[36:39], v[150:153], v[198:201], v[36:39]
	v_mfma_f32_16x16x32_bf16 v[32:35], v[158:161], v[198:201], v[32:35]
	v_mfma_f32_16x16x32_bf16 v[20:23], v[150:153], v[206:209], v[20:23]
	v_mfma_f32_16x16x32_bf16 v[16:19], v[158:161], v[206:209], v[16:19]
	v_mfma_f32_16x16x32_bf16 v[60:63], v[154:157], v[186:189], v[60:63]
	v_mfma_f32_16x16x32_bf16 v[56:59], v[162:165], v[186:189], v[56:59]
	v_mfma_f32_16x16x32_bf16 v[52:55], v[154:157], v[194:197], v[52:55]
	v_mfma_f32_16x16x32_bf16 v[48:51], v[162:165], v[194:197], v[48:51]
	v_mfma_f32_16x16x32_bf16 v[36:39], v[154:157], v[202:205], v[36:39]
	v_mfma_f32_16x16x32_bf16 v[32:35], v[162:165], v[202:205], v[32:35]
	v_mfma_f32_16x16x32_bf16 v[20:23], v[154:157], v[210:213], v[20:23]
	v_mfma_f32_16x16x32_bf16 v[16:19], v[162:165], v[210:213], v[16:19]
	v_mfma_f32_16x16x32_bf16 v[44:47], v[166:169], v[182:185], v[44:47]
	v_mfma_f32_16x16x32_bf16 v[40:43], v[174:177], v[182:185], v[40:43]
	v_mfma_f32_16x16x32_bf16 v[28:31], v[166:169], v[190:193], v[28:31]
	v_mfma_f32_16x16x32_bf16 v[24:27], v[174:177], v[190:193], v[24:27]
	v_mfma_f32_16x16x32_bf16 v[12:15], v[166:169], v[198:201], v[12:15]
	v_mfma_f32_16x16x32_bf16 v[8:11], v[174:177], v[198:201], v[8:11]
	v_mfma_f32_16x16x32_bf16 v[4:7], v[166:169], v[206:209], v[4:7]
	v_mfma_f32_16x16x32_bf16 v[0:3], v[174:177], v[206:209], v[0:3]
	v_mfma_f32_16x16x32_bf16 v[44:47], v[170:173], v[186:189], v[44:47]
	v_mfma_f32_16x16x32_bf16 v[40:43], v[178:181], v[186:189], v[40:43]
	v_mfma_f32_16x16x32_bf16 v[28:31], v[170:173], v[194:197], v[28:31]
	v_mfma_f32_16x16x32_bf16 v[24:27], v[178:181], v[194:197], v[24:27]
	v_mfma_f32_16x16x32_bf16 v[12:15], v[170:173], v[202:205], v[12:15]
	v_mfma_f32_16x16x32_bf16 v[8:11], v[178:181], v[202:205], v[8:11]
	v_mfma_f32_16x16x32_bf16 v[4:7], v[170:173], v[210:213], v[4:7]
	v_mfma_f32_16x16x32_bf16 v[0:3], v[178:181], v[210:213], v[0:3]
	s_setprio 0
	s_barrier
	s_add_i32 s62, s62, 2
	s_add_u32 s60, s60, 0x100
	s_addc_u32 s61, s61, 0
	s_add_u32 s38, s38, 0x100
	s_addc_u32 s39, s39, 0
	s_cmp_gt_u32 s62, 13
	s_cbranch_scc0 .LBB0_1529
	s_and_b64 vcc, exec, s[18:19]
	s_cbranch_vccz .LBB0_1532
	s_barrier

.LBB0_1801:
	ds_read_b128 v[150:153], v147
	ds_read_b128 v[154:157], v147 offset:1024
	ds_read_b128 v[158:161], v147 offset:2048
	ds_read_b128 v[162:165], v147 offset:3072
	ds_read_b128 v[166:169], v148
	ds_read_b128 v[170:173], v148 offset:1024
	ds_read_b128 v[174:177], v148 offset:2048
	ds_read_b128 v[178:181], v148 offset:3072
	s_add_u32 s38, s36, 0xfffc0080
	s_addc_u32 s39, s37, -1
	s_cmp_eq_u32 s61, 12
	s_cselect_b32 s41, s29, s39
	s_cselect_b32 s40, s57, s38
	s_cselect_b32 s39, s27, s60
	s_cselect_b32 s38, s58, s59
	v_lshl_add_u64 v[214:215], s[36:37], 0, v[138:139]
	s_add_i32 m0, s42, 0xc000
	ds_read_b128 v[182:185], v149
	ds_read_b128 v[186:189], v149 offset:1024
	ds_read_b128 v[190:193], v149 offset:2048
	ds_read_b128 v[194:197], v149 offset:3072
	ds_read_b128 v[198:201], v149 offset:4096
	ds_read_b128 v[202:205], v149 offset:5120
	ds_read_b128 v[206:209], v149 offset:6144
	ds_read_b128 v[210:213], v149 offset:7168
	global_load_lds_dwordx4 v[214:215], off
	v_lshl_add_u64 v[214:215], s[36:37], 0, v[136:137]
	s_add_i32 m0, s42, 0xe000
	s_nop 0
	global_load_lds_dwordx4 v[214:215], off
	s_waitcnt vmcnt(8)
	s_waitcnt lgkmcnt(0)
	s_barrier
	s_setprio 1
	s_waitcnt lgkmcnt(0)
	v_mfma_f32_16x16x32_bf16 v[124:127], v[150:153], v[182:185], v[124:127]
	v_mfma_f32_16x16x32_bf16 v[120:123], v[158:161], v[182:185], v[120:123]
	v_mfma_f32_16x16x32_bf16 v[116:119], v[150:153], v[190:193], v[116:119]
	v_mfma_f32_16x16x32_bf16 v[112:115], v[158:161], v[190:193], v[112:115]
	v_mfma_f32_16x16x32_bf16 v[100:103], v[150:153], v[198:201], v[100:103]
	v_mfma_f32_16x16x32_bf16 v[96:99], v[158:161], v[198:201], v[96:99]
	v_mfma_f32_16x16x32_bf16 v[84:87], v[150:153], v[206:209], v[84:87]
	v_mfma_f32_16x16x32_bf16 v[80:83], v[158:161], v[206:209], v[80:83]
	v_mfma_f32_16x16x32_bf16 v[124:127], v[154:157], v[186:189], v[124:127]
	v_mfma_f32_16x16x32_bf16 v[120:123], v[162:165], v[186:189], v[120:123]
	v_mfma_f32_16x16x32_bf16 v[116:119], v[154:157], v[194:197], v[116:119]
	v_mfma_f32_16x16x32_bf16 v[112:115], v[162:165], v[194:197], v[112:115]
	v_mfma_f32_16x16x32_bf16 v[100:103], v[154:157], v[202:205], v[100:103]
	v_mfma_f32_16x16x32_bf16 v[96:99], v[162:165], v[202:205], v[96:99]
	v_mfma_f32_16x16x32_bf16 v[84:87], v[154:157], v[210:213], v[84:87]
	v_mfma_f32_16x16x32_bf16 v[80:83], v[162:165], v[210:213], v[80:83]
	v_mfma_f32_16x16x32_bf16 v[108:111], v[166:169], v[182:185], v[108:111]
	v_mfma_f32_16x16x32_bf16 v[104:107], v[174:177], v[182:185], v[104:107]
	v_mfma_f32_16x16x32_bf16 v[92:95], v[166:169], v[190:193], v[92:95]
	v_mfma_f32_16x16x32_bf16 v[88:91], v[174:177], v[190:193], v[88:91]
	v_mfma_f32_16x16x32_bf16 v[76:79], v[166:169], v[198:201], v[76:79]
	v_mfma_f32_16x16x32_bf16 v[72:75], v[174:177], v[198:201], v[72:75]
	v_mfma_f32_16x16x32_bf16 v[68:71], v[166:169], v[206:209], v[68:71]
	v_mfma_f32_16x16x32_bf16 v[64:67], v[174:177], v[206:209], v[64:67]
	v_mfma_f32_16x16x32_bf16 v[108:111], v[170:173], v[186:189], v[108:111]
	v_mfma_f32_16x16x32_bf16 v[104:107], v[178:181], v[186:189], v[104:107]
	v_mfma_f32_16x16x32_bf16 v[92:95], v[170:173], v[194:197], v[92:95]
	v_mfma_f32_16x16x32_bf16 v[88:91], v[178:181], v[194:197], v[88:91]
	v_mfma_f32_16x16x32_bf16 v[76:79], v[170:173], v[202:205], v[76:79]
	v_mfma_f32_16x16x32_bf16 v[72:75], v[178:181], v[202:205], v[72:75]
	v_mfma_f32_16x16x32_bf16 v[68:71], v[170:173], v[210:213], v[68:71]
	v_mfma_f32_16x16x32_bf16 v[64:67], v[178:181], v[210:213], v[64:67]
	s_setprio 0
	s_barrier
	s_add_i32 s62, s49, s33
	v_lshl_add_u64 v[214:215], s[38:39], 0, v[132:133]
	s_mov_b32 m0, s62
	ds_read_b128 v[182:185], v149 offset:16384
	ds_read_b128 v[186:189], v149 offset:17408
	ds_read_b128 v[190:193], v149 offset:18432
	ds_read_b128 v[194:197], v149 offset:19456
	ds_read_b128 v[198:201], v149 offset:20480
	ds_read_b128 v[202:205], v149 offset:21504
	ds_read_b128 v[206:209], v149 offset:22528
	ds_read_b128 v[210:213], v149 offset:23552
	global_load_lds_dwordx4 v[214:215], off
	s_add_i32 m0, s62, 0x2000
	s_add_u32 s62, s38, 0x40000
	v_lshl_add_u64 v[216:217], s[38:39], 0, v[128:129]
	s_addc_u32 s63, s39, 0
	s_add_i32 s64, s50, s33
	global_load_lds_dwordx4 v[216:217], off
	v_lshl_add_u64 v[218:219], s[62:63], 0, v[132:133]
	s_mov_b32 m0, s64
	v_lshl_add_u64 v[220:221], s[40:41], 0, v[130:131]
	global_load_lds_dwordx4 v[218:219], off
	v_lshl_add_u64 v[218:219], s[62:63], 0, v[128:129]
	s_add_i32 m0, s64, 0x2000
	s_nop 0
	global_load_lds_dwordx4 v[218:219], off
	v_lshl_add_u64 v[218:219], s[40:41], 0, v[134:135]
	s_mov_b32 m0, s42
	s_nop 0
	global_load_lds_dwordx4 v[218:219], off
	s_mov_b32 m0, s43
	s_nop 0
	global_load_lds_dwordx4 v[220:221], off
	s_waitcnt vmcnt(8)
	s_waitcnt lgkmcnt(0)
	s_barrier
	s_setprio 1
	s_waitcnt lgkmcnt(0)
	v_mfma_f32_16x16x32_bf16 v[60:63], v[150:153], v[182:185], v[60:63]
	v_mfma_f32_16x16x32_bf16 v[56:59], v[158:161], v[182:185], v[56:59]
	v_mfma_f32_16x16x32_bf16 v[52:55], v[150:153], v[190:193], v[52:55]
	v_mfma_f32_16x16x32_bf16 v[48:51], v[158:161], v[190:193], v[48:51]
	v_mfma_f32_16x16x32_bf16 v[36:39], v[150:153], v[198:201], v[36:39]
	v_mfma_f32_16x16x32_bf16 v[32:35], v[158:161], v[198:201], v[32:35]
	v_mfma_f32_16x16x32_bf16 v[20:23], v[150:153], v[206:209], v[20:23]
	v_mfma_f32_16x16x32_bf16 v[16:19], v[158:161], v[206:209], v[16:19]
	v_mfma_f32_16x16x32_bf16 v[60:63], v[154:157], v[186:189], v[60:63]
	v_mfma_f32_16x16x32_bf16 v[56:59], v[162:165], v[186:189], v[56:59]
	v_mfma_f32_16x16x32_bf16 v[52:55], v[154:157], v[194:197], v[52:55]
	v_mfma_f32_16x16x32_bf16 v[48:51], v[162:165], v[194:197], v[48:51]
	v_mfma_f32_16x16x32_bf16 v[36:39], v[154:157], v[202:205], v[36:39]
	v_mfma_f32_16x16x32_bf16 v[32:35], v[162:165], v[202:205], v[32:35]
	v_mfma_f32_16x16x32_bf16 v[20:23], v[154:157], v[210:213], v[20:23]
	v_mfma_f32_16x16x32_bf16 v[16:19], v[162:165], v[210:213], v[16:19]
	v_mfma_f32_16x16x32_bf16 v[44:47], v[166:169], v[182:185], v[44:47]
	v_mfma_f32_16x16x32_bf16 v[40:43], v[174:177], v[182:185], v[40:43]
	v_mfma_f32_16x16x32_bf16 v[28:31], v[166:169], v[190:193], v[28:31]
	v_mfma_f32_16x16x32_bf16 v[24:27], v[174:177], v[190:193], v[24:27]
	v_mfma_f32_16x16x32_bf16 v[12:15], v[166:169], v[198:201], v[12:15]
	v_mfma_f32_16x16x32_bf16 v[8:11], v[174:177], v[198:201], v[8:11]
	v_mfma_f32_16x16x32_bf16 v[4:7], v[166:169], v[206:209], v[4:7]
	v_mfma_f32_16x16x32_bf16 v[0:3], v[174:177], v[206:209], v[0:3]
	v_mfma_f32_16x16x32_bf16 v[44:47], v[170:173], v[186:189], v[44:47]
	v_mfma_f32_16x16x32_bf16 v[40:43], v[178:181], v[186:189], v[40:43]
	v_mfma_f32_16x16x32_bf16 v[28:31], v[170:173], v[194:197], v[28:31]
	v_mfma_f32_16x16x32_bf16 v[24:27], v[178:181], v[194:197], v[24:27]
	v_mfma_f32_16x16x32_bf16 v[12:15], v[170:173], v[202:205], v[12:15]
	v_mfma_f32_16x16x32_bf16 v[8:11], v[178:181], v[202:205], v[8:11]
	v_mfma_f32_16x16x32_bf16 v[4:7], v[170:173], v[210:213], v[4:7]
	v_mfma_f32_16x16x32_bf16 v[0:3], v[178:181], v[210:213], v[0:3]
	s_setprio 0
	s_barrier
	s_add_i32 s62, 0, 0x18000
	s_add_i32 s63, 0, 0x1c000
	v_add_u32_e32 v162, s62, v145
	v_add_u32_e32 v178, s63, v145
	ds_read_b128 v[150:153], v162
	ds_read_b128 v[154:157], v162 offset:1024
	ds_read_b128 v[158:161], v162 offset:2048
	ds_read_b128 v[162:165], v162 offset:3072
	ds_read_b128 v[166:169], v178
	ds_read_b128 v[170:173], v178 offset:1024
	ds_read_b128 v[174:177], v178 offset:2048
	ds_read_b128 v[178:181], v178 offset:3072
	s_add_u32 s40, s40, 0x40000
	s_addc_u32 s41, s41, 0
	s_mov_b32 m0, s44
	v_lshl_add_u64 v[222:223], s[40:41], 0, v[134:135]
	ds_read_b128 v[182:185], v149 offset:32768
	ds_read_b128 v[186:189], v149 offset:33792
	ds_read_b128 v[190:193], v149 offset:34816
	ds_read_b128 v[194:197], v149 offset:35840
	ds_read_b128 v[198:201], v149 offset:36864
	ds_read_b128 v[202:205], v149 offset:37888
	ds_read_b128 v[206:209], v149 offset:38912
	ds_read_b128 v[210:213], v149 offset:39936
	global_load_lds_dwordx4 v[222:223], off
	v_lshl_add_u64 v[222:223], s[40:41], 0, v[130:131]
	s_mov_b32 m0, s45
	s_nop 0
	global_load_lds_dwordx4 v[222:223], off
	s_waitcnt vmcnt(8)
	s_waitcnt lgkmcnt(0)
	s_barrier
	s_setprio 1
	s_waitcnt lgkmcnt(0)
	v_mfma_f32_16x16x32_bf16 v[124:127], v[150:153], v[182:185], v[124:127]
	v_mfma_f32_16x16x32_bf16 v[120:123], v[158:161], v[182:185], v[120:123]
	v_mfma_f32_16x16x32_bf16 v[116:119], v[150:153], v[190:193], v[116:119]
	v_mfma_f32_16x16x32_bf16 v[112:115], v[158:161], v[190:193], v[112:115]
	v_mfma_f32_16x16x32_bf16 v[100:103], v[150:153], v[198:201], v[100:103]
	v_mfma_f32_16x16x32_bf16 v[96:99], v[158:161], v[198:201], v[96:99]
	v_mfma_f32_16x16x32_bf16 v[84:87], v[150:153], v[206:209], v[84:87]
	v_mfma_f32_16x16x32_bf16 v[80:83], v[158:161], v[206:209], v[80:83]
	v_mfma_f32_16x16x32_bf16 v[124:127], v[154:157], v[186:189], v[124:127]
	v_mfma_f32_16x16x32_bf16 v[120:123], v[162:165], v[186:189], v[120:123]
	v_mfma_f32_16x16x32_bf16 v[116:119], v[154:157], v[194:197], v[116:119]
	v_mfma_f32_16x16x32_bf16 v[112:115], v[162:165], v[194:197], v[112:115]
	v_mfma_f32_16x16x32_bf16 v[100:103], v[154:157], v[202:205], v[100:103]
	v_mfma_f32_16x16x32_bf16 v[96:99], v[162:165], v[202:205], v[96:99]
	v_mfma_f32_16x16x32_bf16 v[84:87], v[154:157], v[210:213], v[84:87]
	v_mfma_f32_16x16x32_bf16 v[80:83], v[162:165], v[210:213], v[80:83]
	v_mfma_f32_16x16x32_bf16 v[108:111], v[166:169], v[182:185], v[108:111]
	v_mfma_f32_16x16x32_bf16 v[104:107], v[174:177], v[182:185], v[104:107]
	v_mfma_f32_16x16x32_bf16 v[92:95], v[166:169], v[190:193], v[92:95]
	v_mfma_f32_16x16x32_bf16 v[88:91], v[174:177], v[190:193], v[88:91]
	v_mfma_f32_16x16x32_bf16 v[76:79], v[166:169], v[198:201], v[76:79]
	v_mfma_f32_16x16x32_bf16 v[72:75], v[174:177], v[198:201], v[72:75]
	v_mfma_f32_16x16x32_bf16 v[68:71], v[166:169], v[206:209], v[68:71]
	v_mfma_f32_16x16x32_bf16 v[64:67], v[174:177], v[206:209], v[64:67]
	v_mfma_f32_16x16x32_bf16 v[108:111], v[170:173], v[186:189], v[108:111]
	v_mfma_f32_16x16x32_bf16 v[104:107], v[178:181], v[186:189], v[104:107]
	v_mfma_f32_16x16x32_bf16 v[92:95], v[170:173], v[194:197], v[92:95]
	v_mfma_f32_16x16x32_bf16 v[88:91], v[178:181], v[194:197], v[88:91]
	v_mfma_f32_16x16x32_bf16 v[76:79], v[170:173], v[202:205], v[76:79]
	v_mfma_f32_16x16x32_bf16 v[72:75], v[178:181], v[202:205], v[72:75]
	v_mfma_f32_16x16x32_bf16 v[68:71], v[170:173], v[210:213], v[68:71]
	v_mfma_f32_16x16x32_bf16 v[64:67], v[178:181], v[210:213], v[64:67]
	s_setprio 0
	s_barrier
	s_add_i32 s40, s62, s33
	v_lshl_add_u64 v[214:215], v[214:215], 0, s[16:17]
	s_mov_b32 m0, s40
	ds_read_b128 v[182:185], v149 offset:49152
	ds_read_b128 v[186:189], v149 offset:50176
	ds_read_b128 v[190:193], v149 offset:51200
	ds_read_b128 v[194:197], v149 offset:52224
	ds_read_b128 v[198:201], v149 offset:53248
	ds_read_b128 v[202:205], v149 offset:54272
	ds_read_b128 v[206:209], v149 offset:55296
	ds_read_b128 v[210:213], v149 offset:56320
	global_load_lds_dwordx4 v[214:215], off
	s_add_i32 m0, s40, 0x2000
	s_add_u32 s38, s38, 0x40080
	v_lshl_add_u64 v[214:215], v[216:217], 0, s[16:17]
	s_addc_u32 s39, s39, 0
	s_add_i32 s40, s63, s33
	global_load_lds_dwordx4 v[214:215], off
	v_lshl_add_u64 v[214:215], s[38:39], 0, v[132:133]
	s_mov_b32 m0, s40
	s_nop 0
	global_load_lds_dwordx4 v[214:215], off
	v_lshl_add_u64 v[214:215], s[38:39], 0, v[128:129]
	s_add_i32 m0, s40, 0x2000
	s_nop 0
	global_load_lds_dwordx4 v[214:215], off
	v_lshl_add_u64 v[214:215], v[218:219], 0, s[16:17]
	s_mov_b32 m0, s47
	s_nop 0
	global_load_lds_dwordx4 v[214:215], off
	v_lshl_add_u64 v[214:215], v[220:221], 0, s[16:17]
	s_mov_b32 m0, s48
	s_nop 0
	global_load_lds_dwordx4 v[214:215], off
	s_waitcnt vmcnt(8)
	s_waitcnt lgkmcnt(0)
	s_barrier
	s_setprio 1
	s_waitcnt lgkmcnt(0)
	v_mfma_f32_16x16x32_bf16 v[60:63], v[150:153], v[182:185], v[60:63]
	v_mfma_f32_16x16x32_bf16 v[56:59], v[158:161], v[182:185], v[56:59]
	v_mfma_f32_16x16x32_bf16 v[52:55], v[150:153], v[190:193], v[52:55]
	v_mfma_f32_16x16x32_bf16 v[48:51], v[158:161], v[190:193], v[48:51]
	v_mfma_f32_16x16x32_bf16 v[36:39], v[150:153], v[198:201], v[36:39]
	v_mfma_f32_16x16x32_bf16 v[32:35], v[158:161], v[198:201], v[32:35]
	v_mfma_f32_16x16x32_bf16 v[20:23], v[150:153], v[206:209], v[20:23]
	v_mfma_f32_16x16x32_bf16 v[16:19], v[158:161], v[206:209], v[16:19]
	v_mfma_f32_16x16x32_bf16 v[60:63], v[154:157], v[186:189], v[60:63]
	v_mfma_f32_16x16x32_bf16 v[56:59], v[162:165], v[186:189], v[56:59]
	v_mfma_f32_16x16x32_bf16 v[52:55], v[154:157], v[194:197], v[52:55]
	v_mfma_f32_16x16x32_bf16 v[48:51], v[162:165], v[194:197], v[48:51]
	v_mfma_f32_16x16x32_bf16 v[36:39], v[154:157], v[202:205], v[36:39]
	v_mfma_f32_16x16x32_bf16 v[32:35], v[162:165], v[202:205], v[32:35]
	v_mfma_f32_16x16x32_bf16 v[20:23], v[154:157], v[210:213], v[20:23]
	v_mfma_f32_16x16x32_bf16 v[16:19], v[162:165], v[210:213], v[16:19]
	v_mfma_f32_16x16x32_bf16 v[44:47], v[166:169], v[182:185], v[44:47]
	v_mfma_f32_16x16x32_bf16 v[40:43], v[174:177], v[182:185], v[40:43]
	v_mfma_f32_16x16x32_bf16 v[28:31], v[166:169], v[190:193], v[28:31]
	v_mfma_f32_16x16x32_bf16 v[24:27], v[174:177], v[190:193], v[24:27]
	v_mfma_f32_16x16x32_bf16 v[12:15], v[166:169], v[198:201], v[12:15]
	v_mfma_f32_16x16x32_bf16 v[8:11], v[174:177], v[198:201], v[8:11]
	v_mfma_f32_16x16x32_bf16 v[4:7], v[166:169], v[206:209], v[4:7]
	v_mfma_f32_16x16x32_bf16 v[0:3], v[174:177], v[206:209], v[0:3]
	v_mfma_f32_16x16x32_bf16 v[44:47], v[170:173], v[186:189], v[44:47]
	v_mfma_f32_16x16x32_bf16 v[40:43], v[178:181], v[186:189], v[40:43]
	v_mfma_f32_16x16x32_bf16 v[28:31], v[170:173], v[194:197], v[28:31]
	v_mfma_f32_16x16x32_bf16 v[24:27], v[178:181], v[194:197], v[24:27]
	v_mfma_f32_16x16x32_bf16 v[12:15], v[170:173], v[202:205], v[12:15]
	v_mfma_f32_16x16x32_bf16 v[8:11], v[178:181], v[202:205], v[8:11]
	v_mfma_f32_16x16x32_bf16 v[4:7], v[170:173], v[210:213], v[4:7]
	v_mfma_f32_16x16x32_bf16 v[0:3], v[178:181], v[210:213], v[0:3]
	s_setprio 0
	s_barrier
	s_add_i32 s61, s61, 2
	s_add_u32 s59, s59, 0x100
	s_addc_u32 s60, s60, 0
	s_add_u32 s36, s36, 0x100
	s_addc_u32 s37, s37, 0
	s_cmp_gt_u32 s61, 13
	s_cbranch_scc0 .LBB0_1801
	s_and_b64 vcc, exec, s[18:19]
	s_cbranch_vccz .LBB0_1804
	s_barrier

.LBB0_1949:
	ds_read_b128 v[152:155], v149
	ds_read_b128 v[156:159], v149 offset:1024
	ds_read_b128 v[160:163], v149 offset:2048
	ds_read_b128 v[164:167], v149 offset:3072
	ds_read_b128 v[168:171], v150
	ds_read_b128 v[172:175], v150 offset:1024
	ds_read_b128 v[176:179], v150 offset:2048
	ds_read_b128 v[180:183], v150 offset:3072
	s_add_u32 s28, s26, 0xfffc0080
	s_addc_u32 s29, s27, -1
	s_cmp_eq_u32 s49, 12
	s_cselect_b32 s31, s21, s29
	s_cselect_b32 s30, s45, s28
	s_cselect_b32 s29, s19, s48
	s_cselect_b32 s28, s46, s47
	v_lshl_add_u64 v[144:145], s[26:27], 0, v[138:139]
	s_add_i32 m0, s34, 0xc000
	ds_read_b128 v[184:187], v151
	ds_read_b128 v[188:191], v151 offset:1024
	ds_read_b128 v[192:195], v151 offset:2048
	ds_read_b128 v[196:199], v151 offset:3072
	ds_read_b128 v[200:203], v151 offset:4096
	ds_read_b128 v[204:207], v151 offset:5120
	ds_read_b128 v[208:211], v151 offset:6144
	ds_read_b128 v[212:215], v151 offset:7168
	global_load_lds_dwordx4 v[144:145], off
	v_lshl_add_u64 v[144:145], s[26:27], 0, v[136:137]
	s_add_i32 m0, s34, 0xe000
	s_nop 0
	global_load_lds_dwordx4 v[144:145], off
	s_waitcnt vmcnt(8)
	s_waitcnt lgkmcnt(0)
	s_barrier
	s_setprio 1
	s_waitcnt lgkmcnt(0)
	v_mfma_f32_16x16x32_bf16 v[124:127], v[152:155], v[184:187], v[124:127]
	v_mfma_f32_16x16x32_bf16 v[120:123], v[160:163], v[184:187], v[120:123]
	v_mfma_f32_16x16x32_bf16 v[108:111], v[152:155], v[192:195], v[108:111]
	v_mfma_f32_16x16x32_bf16 v[104:107], v[160:163], v[192:195], v[104:107]
	v_mfma_f32_16x16x32_bf16 v[92:95], v[152:155], v[200:203], v[92:95]
	v_mfma_f32_16x16x32_bf16 v[88:91], v[160:163], v[200:203], v[88:91]
	v_mfma_f32_16x16x32_bf16 v[76:79], v[152:155], v[208:211], v[76:79]
	v_mfma_f32_16x16x32_bf16 v[72:75], v[160:163], v[208:211], v[72:75]
	v_mfma_f32_16x16x32_bf16 v[124:127], v[156:159], v[188:191], v[124:127]
	v_mfma_f32_16x16x32_bf16 v[120:123], v[164:167], v[188:191], v[120:123]
	v_mfma_f32_16x16x32_bf16 v[108:111], v[156:159], v[196:199], v[108:111]
	v_mfma_f32_16x16x32_bf16 v[104:107], v[164:167], v[196:199], v[104:107]
	v_mfma_f32_16x16x32_bf16 v[92:95], v[156:159], v[204:207], v[92:95]
	v_mfma_f32_16x16x32_bf16 v[88:91], v[164:167], v[204:207], v[88:91]
	v_mfma_f32_16x16x32_bf16 v[76:79], v[156:159], v[212:215], v[76:79]
	v_mfma_f32_16x16x32_bf16 v[72:75], v[164:167], v[212:215], v[72:75]
	v_mfma_f32_16x16x32_bf16 v[116:119], v[168:171], v[184:187], v[116:119]
	v_mfma_f32_16x16x32_bf16 v[112:115], v[176:179], v[184:187], v[112:115]
	v_mfma_f32_16x16x32_bf16 v[100:103], v[168:171], v[192:195], v[100:103]
	v_mfma_f32_16x16x32_bf16 v[96:99], v[176:179], v[192:195], v[96:99]
	v_mfma_f32_16x16x32_bf16 v[84:87], v[168:171], v[200:203], v[84:87]
	v_mfma_f32_16x16x32_bf16 v[80:83], v[176:179], v[200:203], v[80:83]
	v_mfma_f32_16x16x32_bf16 v[68:71], v[168:171], v[208:211], v[68:71]
	v_mfma_f32_16x16x32_bf16 v[64:67], v[176:179], v[208:211], v[64:67]
	v_mfma_f32_16x16x32_bf16 v[116:119], v[172:175], v[188:191], v[116:119]
	v_mfma_f32_16x16x32_bf16 v[112:115], v[180:183], v[188:191], v[112:115]
	v_mfma_f32_16x16x32_bf16 v[100:103], v[172:175], v[196:199], v[100:103]
	v_mfma_f32_16x16x32_bf16 v[96:99], v[180:183], v[196:199], v[96:99]
	v_mfma_f32_16x16x32_bf16 v[84:87], v[172:175], v[204:207], v[84:87]
	v_mfma_f32_16x16x32_bf16 v[80:83], v[180:183], v[204:207], v[80:83]
	v_mfma_f32_16x16x32_bf16 v[68:71], v[172:175], v[212:215], v[68:71]
	v_mfma_f32_16x16x32_bf16 v[64:67], v[180:183], v[212:215], v[64:67]
	s_setprio 0
	s_barrier
	s_add_i32 s50, s42, s33
	v_lshl_add_u64 v[144:145], s[28:29], 0, v[132:133]
	s_mov_b32 m0, s50
	ds_read_b128 v[184:187], v151 offset:16384
	ds_read_b128 v[188:191], v151 offset:17408
	ds_read_b128 v[192:195], v151 offset:18432
	ds_read_b128 v[196:199], v151 offset:19456
	ds_read_b128 v[200:203], v151 offset:20480
	ds_read_b128 v[204:207], v151 offset:21504
	ds_read_b128 v[208:211], v151 offset:22528
	ds_read_b128 v[212:215], v151 offset:23552
	global_load_lds_dwordx4 v[144:145], off
	s_add_i32 m0, s50, 0x2000
	s_add_u32 s50, s28, 0x40000
	v_lshl_add_u64 v[216:217], s[28:29], 0, v[128:129]
	s_addc_u32 s51, s29, 0
	s_add_i32 s52, s43, s33
	global_load_lds_dwordx4 v[216:217], off
	v_lshl_add_u64 v[218:219], s[50:51], 0, v[132:133]
	s_mov_b32 m0, s52
	v_lshl_add_u64 v[220:221], s[30:31], 0, v[130:131]
	global_load_lds_dwordx4 v[218:219], off
	v_lshl_add_u64 v[218:219], s[50:51], 0, v[128:129]
	s_add_i32 m0, s52, 0x2000
	s_nop 0
	global_load_lds_dwordx4 v[218:219], off
	v_lshl_add_u64 v[218:219], s[30:31], 0, v[134:135]
	s_mov_b32 m0, s34
	s_nop 0
	global_load_lds_dwordx4 v[218:219], off
	s_mov_b32 m0, s35
	s_nop 0
	global_load_lds_dwordx4 v[220:221], off
	s_waitcnt vmcnt(8)
	s_waitcnt lgkmcnt(0)
	s_barrier
	s_setprio 1
	s_waitcnt lgkmcnt(0)
	v_mfma_f32_16x16x32_bf16 v[60:63], v[152:155], v[184:187], v[60:63]
	v_mfma_f32_16x16x32_bf16 v[56:59], v[160:163], v[184:187], v[56:59]
	v_mfma_f32_16x16x32_bf16 v[44:47], v[152:155], v[192:195], v[44:47]
	v_mfma_f32_16x16x32_bf16 v[40:43], v[160:163], v[192:195], v[40:43]
	v_mfma_f32_16x16x32_bf16 v[28:31], v[152:155], v[200:203], v[28:31]
	v_mfma_f32_16x16x32_bf16 v[24:27], v[160:163], v[200:203], v[24:27]
	v_mfma_f32_16x16x32_bf16 v[12:15], v[152:155], v[208:211], v[12:15]
	v_mfma_f32_16x16x32_bf16 v[8:11], v[160:163], v[208:211], v[8:11]
	v_mfma_f32_16x16x32_bf16 v[60:63], v[156:159], v[188:191], v[60:63]
	v_mfma_f32_16x16x32_bf16 v[56:59], v[164:167], v[188:191], v[56:59]
	v_mfma_f32_16x16x32_bf16 v[44:47], v[156:159], v[196:199], v[44:47]
	v_mfma_f32_16x16x32_bf16 v[40:43], v[164:167], v[196:199], v[40:43]
	v_mfma_f32_16x16x32_bf16 v[28:31], v[156:159], v[204:207], v[28:31]
	v_mfma_f32_16x16x32_bf16 v[24:27], v[164:167], v[204:207], v[24:27]
	v_mfma_f32_16x16x32_bf16 v[12:15], v[156:159], v[212:215], v[12:15]
	v_mfma_f32_16x16x32_bf16 v[8:11], v[164:167], v[212:215], v[8:11]
	v_mfma_f32_16x16x32_bf16 v[52:55], v[168:171], v[184:187], v[52:55]
	v_mfma_f32_16x16x32_bf16 v[48:51], v[176:179], v[184:187], v[48:51]
	v_mfma_f32_16x16x32_bf16 v[36:39], v[168:171], v[192:195], v[36:39]
	v_mfma_f32_16x16x32_bf16 v[32:35], v[176:179], v[192:195], v[32:35]
	v_mfma_f32_16x16x32_bf16 v[20:23], v[168:171], v[200:203], v[20:23]
	v_mfma_f32_16x16x32_bf16 v[16:19], v[176:179], v[200:203], v[16:19]
	v_mfma_f32_16x16x32_bf16 v[4:7], v[168:171], v[208:211], v[4:7]
	v_mfma_f32_16x16x32_bf16 v[0:3], v[176:179], v[208:211], v[0:3]
	v_mfma_f32_16x16x32_bf16 v[52:55], v[172:175], v[188:191], v[52:55]
	v_mfma_f32_16x16x32_bf16 v[48:51], v[180:183], v[188:191], v[48:51]
	v_mfma_f32_16x16x32_bf16 v[36:39], v[172:175], v[196:199], v[36:39]
	v_mfma_f32_16x16x32_bf16 v[32:35], v[180:183], v[196:199], v[32:35]
	v_mfma_f32_16x16x32_bf16 v[20:23], v[172:175], v[204:207], v[20:23]
	v_mfma_f32_16x16x32_bf16 v[16:19], v[180:183], v[204:207], v[16:19]
	v_mfma_f32_16x16x32_bf16 v[4:7], v[172:175], v[212:215], v[4:7]
	v_mfma_f32_16x16x32_bf16 v[0:3], v[180:183], v[212:215], v[0:3]
	s_setprio 0
	s_barrier
	s_add_i32 s50, 0, 0x18000
	s_add_i32 s51, 0, 0x1c000
	v_add_u32_e32 v164, s50, v147
	v_add_u32_e32 v180, s51, v147
	ds_read_b128 v[152:155], v164
	ds_read_b128 v[156:159], v164 offset:1024
	ds_read_b128 v[160:163], v164 offset:2048
	ds_read_b128 v[164:167], v164 offset:3072
	ds_read_b128 v[168:171], v180
	ds_read_b128 v[172:175], v180 offset:1024
	ds_read_b128 v[176:179], v180 offset:2048
	ds_read_b128 v[180:183], v180 offset:3072
	s_add_u32 s30, s30, 0x40000
	s_addc_u32 s31, s31, 0
	s_mov_b32 m0, s36
	v_lshl_add_u64 v[222:223], s[30:31], 0, v[134:135]
	ds_read_b128 v[184:187], v151 offset:32768
	ds_read_b128 v[188:191], v151 offset:33792
	ds_read_b128 v[192:195], v151 offset:34816
	ds_read_b128 v[196:199], v151 offset:35840
	ds_read_b128 v[200:203], v151 offset:36864
	ds_read_b128 v[204:207], v151 offset:37888
	ds_read_b128 v[208:211], v151 offset:38912
	ds_read_b128 v[212:215], v151 offset:39936
	global_load_lds_dwordx4 v[222:223], off
	v_lshl_add_u64 v[222:223], s[30:31], 0, v[130:131]
	s_mov_b32 m0, s37
	s_nop 0
	global_load_lds_dwordx4 v[222:223], off
	s_waitcnt vmcnt(8)
	s_waitcnt lgkmcnt(0)
	s_barrier
	s_setprio 1
	s_waitcnt lgkmcnt(0)
	v_mfma_f32_16x16x32_bf16 v[124:127], v[152:155], v[184:187], v[124:127]
	v_mfma_f32_16x16x32_bf16 v[120:123], v[160:163], v[184:187], v[120:123]
	v_mfma_f32_16x16x32_bf16 v[108:111], v[152:155], v[192:195], v[108:111]
	v_mfma_f32_16x16x32_bf16 v[104:107], v[160:163], v[192:195], v[104:107]
	v_mfma_f32_16x16x32_bf16 v[92:95], v[152:155], v[200:203], v[92:95]
	v_mfma_f32_16x16x32_bf16 v[88:91], v[160:163], v[200:203], v[88:91]
	v_mfma_f32_16x16x32_bf16 v[76:79], v[152:155], v[208:211], v[76:79]
	v_mfma_f32_16x16x32_bf16 v[72:75], v[160:163], v[208:211], v[72:75]
	v_mfma_f32_16x16x32_bf16 v[124:127], v[156:159], v[188:191], v[124:127]
	v_mfma_f32_16x16x32_bf16 v[120:123], v[164:167], v[188:191], v[120:123]
	v_mfma_f32_16x16x32_bf16 v[108:111], v[156:159], v[196:199], v[108:111]
	v_mfma_f32_16x16x32_bf16 v[104:107], v[164:167], v[196:199], v[104:107]
	v_mfma_f32_16x16x32_bf16 v[92:95], v[156:159], v[204:207], v[92:95]
	v_mfma_f32_16x16x32_bf16 v[88:91], v[164:167], v[204:207], v[88:91]
	v_mfma_f32_16x16x32_bf16 v[76:79], v[156:159], v[212:215], v[76:79]
	v_mfma_f32_16x16x32_bf16 v[72:75], v[164:167], v[212:215], v[72:75]
	v_mfma_f32_16x16x32_bf16 v[116:119], v[168:171], v[184:187], v[116:119]
	v_mfma_f32_16x16x32_bf16 v[112:115], v[176:179], v[184:187], v[112:115]
	v_mfma_f32_16x16x32_bf16 v[100:103], v[168:171], v[192:195], v[100:103]
	v_mfma_f32_16x16x32_bf16 v[96:99], v[176:179], v[192:195], v[96:99]
	v_mfma_f32_16x16x32_bf16 v[84:87], v[168:171], v[200:203], v[84:87]
	v_mfma_f32_16x16x32_bf16 v[80:83], v[176:179], v[200:203], v[80:83]
	v_mfma_f32_16x16x32_bf16 v[68:71], v[168:171], v[208:211], v[68:71]
	v_mfma_f32_16x16x32_bf16 v[64:67], v[176:179], v[208:211], v[64:67]
	v_mfma_f32_16x16x32_bf16 v[116:119], v[172:175], v[188:191], v[116:119]
	v_mfma_f32_16x16x32_bf16 v[112:115], v[180:183], v[188:191], v[112:115]
	v_mfma_f32_16x16x32_bf16 v[100:103], v[172:175], v[196:199], v[100:103]
	v_mfma_f32_16x16x32_bf16 v[96:99], v[180:183], v[196:199], v[96:99]
	v_mfma_f32_16x16x32_bf16 v[84:87], v[172:175], v[204:207], v[84:87]
	v_mfma_f32_16x16x32_bf16 v[80:83], v[180:183], v[204:207], v[80:83]
	v_mfma_f32_16x16x32_bf16 v[68:71], v[172:175], v[212:215], v[68:71]
	v_mfma_f32_16x16x32_bf16 v[64:67], v[180:183], v[212:215], v[64:67]
	s_setprio 0
	s_barrier
	s_add_i32 s30, s50, s33
	v_lshl_add_u64 v[144:145], v[144:145], 0, s[14:15]
	s_mov_b32 m0, s30
	ds_read_b128 v[184:187], v151 offset:49152
	ds_read_b128 v[188:191], v151 offset:50176
	ds_read_b128 v[192:195], v151 offset:51200
	ds_read_b128 v[196:199], v151 offset:52224
	ds_read_b128 v[200:203], v151 offset:53248
	ds_read_b128 v[204:207], v151 offset:54272
	ds_read_b128 v[208:211], v151 offset:55296
	ds_read_b128 v[212:215], v151 offset:56320
	global_load_lds_dwordx4 v[144:145], off
	s_add_i32 m0, s30, 0x2000
	s_add_u32 s28, s28, 0x40080
	v_lshl_add_u64 v[144:145], v[216:217], 0, s[14:15]
	s_addc_u32 s29, s29, 0
	s_add_i32 s30, s51, s33
	global_load_lds_dwordx4 v[144:145], off
	v_lshl_add_u64 v[144:145], s[28:29], 0, v[132:133]
	s_mov_b32 m0, s30
	s_nop 0
	global_load_lds_dwordx4 v[144:145], off
	v_lshl_add_u64 v[144:145], s[28:29], 0, v[128:129]
	s_add_i32 m0, s30, 0x2000
	s_nop 0
	global_load_lds_dwordx4 v[144:145], off
	v_lshl_add_u64 v[144:145], v[218:219], 0, s[14:15]
	s_mov_b32 m0, s39
	s_nop 0
	global_load_lds_dwordx4 v[144:145], off
	v_lshl_add_u64 v[144:145], v[220:221], 0, s[14:15]
	s_mov_b32 m0, s40
	s_nop 0
	global_load_lds_dwordx4 v[144:145], off
	s_waitcnt vmcnt(8)
	s_waitcnt lgkmcnt(0)
	s_barrier
	s_setprio 1
	s_waitcnt lgkmcnt(0)
	v_mfma_f32_16x16x32_bf16 v[60:63], v[152:155], v[184:187], v[60:63]
	v_mfma_f32_16x16x32_bf16 v[56:59], v[160:163], v[184:187], v[56:59]
	v_mfma_f32_16x16x32_bf16 v[44:47], v[152:155], v[192:195], v[44:47]
	v_mfma_f32_16x16x32_bf16 v[40:43], v[160:163], v[192:195], v[40:43]
	v_mfma_f32_16x16x32_bf16 v[28:31], v[152:155], v[200:203], v[28:31]
	v_mfma_f32_16x16x32_bf16 v[24:27], v[160:163], v[200:203], v[24:27]
	v_mfma_f32_16x16x32_bf16 v[12:15], v[152:155], v[208:211], v[12:15]
	v_mfma_f32_16x16x32_bf16 v[8:11], v[160:163], v[208:211], v[8:11]
	v_mfma_f32_16x16x32_bf16 v[60:63], v[156:159], v[188:191], v[60:63]
	v_mfma_f32_16x16x32_bf16 v[56:59], v[164:167], v[188:191], v[56:59]
	v_mfma_f32_16x16x32_bf16 v[44:47], v[156:159], v[196:199], v[44:47]
	v_mfma_f32_16x16x32_bf16 v[40:43], v[164:167], v[196:199], v[40:43]
	v_mfma_f32_16x16x32_bf16 v[28:31], v[156:159], v[204:207], v[28:31]
	v_mfma_f32_16x16x32_bf16 v[24:27], v[164:167], v[204:207], v[24:27]
	v_mfma_f32_16x16x32_bf16 v[12:15], v[156:159], v[212:215], v[12:15]
	v_mfma_f32_16x16x32_bf16 v[8:11], v[164:167], v[212:215], v[8:11]
	v_mfma_f32_16x16x32_bf16 v[52:55], v[168:171], v[184:187], v[52:55]
	v_mfma_f32_16x16x32_bf16 v[48:51], v[176:179], v[184:187], v[48:51]
	v_mfma_f32_16x16x32_bf16 v[36:39], v[168:171], v[192:195], v[36:39]
	v_mfma_f32_16x16x32_bf16 v[32:35], v[176:179], v[192:195], v[32:35]
	v_mfma_f32_16x16x32_bf16 v[20:23], v[168:171], v[200:203], v[20:23]
	v_mfma_f32_16x16x32_bf16 v[16:19], v[176:179], v[200:203], v[16:19]
	v_mfma_f32_16x16x32_bf16 v[4:7], v[168:171], v[208:211], v[4:7]
	v_mfma_f32_16x16x32_bf16 v[0:3], v[176:179], v[208:211], v[0:3]
	v_mfma_f32_16x16x32_bf16 v[52:55], v[172:175], v[188:191], v[52:55]
	v_mfma_f32_16x16x32_bf16 v[48:51], v[180:183], v[188:191], v[48:51]
	v_mfma_f32_16x16x32_bf16 v[36:39], v[172:175], v[196:199], v[36:39]
	v_mfma_f32_16x16x32_bf16 v[32:35], v[180:183], v[196:199], v[32:35]
	v_mfma_f32_16x16x32_bf16 v[20:23], v[172:175], v[204:207], v[20:23]
	v_mfma_f32_16x16x32_bf16 v[16:19], v[180:183], v[204:207], v[16:19]
	v_mfma_f32_16x16x32_bf16 v[4:7], v[172:175], v[212:215], v[4:7]
	v_mfma_f32_16x16x32_bf16 v[0:3], v[180:183], v[212:215], v[0:3]
	s_setprio 0
	s_barrier
	s_add_i32 s49, s49, 2
	s_add_u32 s47, s47, 0x100
	s_addc_u32 s48, s48, 0
	s_add_u32 s26, s26, 0x100
	s_addc_u32 s27, s27, 0
	s_cmp_gt_u32 s49, 13
	s_cbranch_scc0 .LBB0_1949
	s_and_b64 vcc, exec, s[16:17]
	s_cbranch_vccz .LBB0_1952
	s_barrier

.LBB0_2021:
	ds_read_b128 v[150:153], v147
	ds_read_b128 v[154:157], v147 offset:1024
	ds_read_b128 v[158:161], v147 offset:2048
	ds_read_b128 v[162:165], v147 offset:3072
	ds_read_b128 v[166:169], v148
	ds_read_b128 v[170:173], v148 offset:1024
	ds_read_b128 v[174:177], v148 offset:2048
	ds_read_b128 v[178:181], v148 offset:3072
	s_add_u32 s34, s30, 0x100
	s_addc_u32 s35, s31, 0
	s_cmp_eq_u32 s57, 40
	s_cselect_b32 s39, s11, s35
	s_cselect_b32 s38, s10, s34
	s_cselect_b32 s37, s29, s56
	s_cselect_b32 s36, s28, s55
	v_lshl_add_u64 v[214:215], s[30:31], 0, v[138:139]
	s_add_i32 m0, s40, 0xc000
	ds_read_b128 v[182:185], v149
	ds_read_b128 v[186:189], v149 offset:1024
	ds_read_b128 v[190:193], v149 offset:2048
	ds_read_b128 v[194:197], v149 offset:3072
	ds_read_b128 v[198:201], v149 offset:4096
	ds_read_b128 v[202:205], v149 offset:5120
	ds_read_b128 v[206:209], v149 offset:6144
	ds_read_b128 v[210:213], v149 offset:7168
	global_load_lds_dwordx4 v[214:215], off
	v_lshl_add_u64 v[214:215], s[30:31], 0, v[136:137]
	s_add_i32 m0, s40, 0xe000
	s_nop 0
	global_load_lds_dwordx4 v[214:215], off
	s_waitcnt vmcnt(8)
	s_waitcnt lgkmcnt(0)
	s_barrier
	s_setprio 1
	s_waitcnt lgkmcnt(0)
	v_mfma_f32_16x16x32_bf16 v[124:127], v[150:153], v[182:185], v[124:127]
	v_mfma_f32_16x16x32_bf16 v[120:123], v[158:161], v[182:185], v[120:123]
	v_mfma_f32_16x16x32_bf16 v[116:119], v[150:153], v[190:193], v[116:119]
	v_mfma_f32_16x16x32_bf16 v[112:115], v[158:161], v[190:193], v[112:115]
	v_mfma_f32_16x16x32_bf16 v[100:103], v[150:153], v[198:201], v[100:103]
	v_mfma_f32_16x16x32_bf16 v[96:99], v[158:161], v[198:201], v[96:99]
	v_mfma_f32_16x16x32_bf16 v[84:87], v[150:153], v[206:209], v[84:87]
	v_mfma_f32_16x16x32_bf16 v[80:83], v[158:161], v[206:209], v[80:83]
	v_mfma_f32_16x16x32_bf16 v[124:127], v[154:157], v[186:189], v[124:127]
	v_mfma_f32_16x16x32_bf16 v[120:123], v[162:165], v[186:189], v[120:123]
	v_mfma_f32_16x16x32_bf16 v[116:119], v[154:157], v[194:197], v[116:119]
	v_mfma_f32_16x16x32_bf16 v[112:115], v[162:165], v[194:197], v[112:115]
	v_mfma_f32_16x16x32_bf16 v[100:103], v[154:157], v[202:205], v[100:103]
	v_mfma_f32_16x16x32_bf16 v[96:99], v[162:165], v[202:205], v[96:99]
	v_mfma_f32_16x16x32_bf16 v[84:87], v[154:157], v[210:213], v[84:87]
	v_mfma_f32_16x16x32_bf16 v[80:83], v[162:165], v[210:213], v[80:83]
	v_mfma_f32_16x16x32_bf16 v[108:111], v[166:169], v[182:185], v[108:111]
	v_mfma_f32_16x16x32_bf16 v[104:107], v[174:177], v[182:185], v[104:107]
	v_mfma_f32_16x16x32_bf16 v[92:95], v[166:169], v[190:193], v[92:95]
	v_mfma_f32_16x16x32_bf16 v[88:91], v[174:177], v[190:193], v[88:91]
	v_mfma_f32_16x16x32_bf16 v[76:79], v[166:169], v[198:201], v[76:79]
	v_mfma_f32_16x16x32_bf16 v[72:75], v[174:177], v[198:201], v[72:75]
	v_mfma_f32_16x16x32_bf16 v[68:71], v[166:169], v[206:209], v[68:71]
	v_mfma_f32_16x16x32_bf16 v[64:67], v[174:177], v[206:209], v[64:67]
	v_mfma_f32_16x16x32_bf16 v[108:111], v[170:173], v[186:189], v[108:111]
	v_mfma_f32_16x16x32_bf16 v[104:107], v[178:181], v[186:189], v[104:107]
	v_mfma_f32_16x16x32_bf16 v[92:95], v[170:173], v[194:197], v[92:95]
	v_mfma_f32_16x16x32_bf16 v[88:91], v[178:181], v[194:197], v[88:91]
	v_mfma_f32_16x16x32_bf16 v[76:79], v[170:173], v[202:205], v[76:79]
	v_mfma_f32_16x16x32_bf16 v[72:75], v[178:181], v[202:205], v[72:75]
	v_mfma_f32_16x16x32_bf16 v[68:71], v[170:173], v[210:213], v[68:71]
	v_mfma_f32_16x16x32_bf16 v[64:67], v[178:181], v[210:213], v[64:67]
	s_setprio 0
	s_barrier
	s_add_i32 s30, s47, s33
	v_lshl_add_u64 v[214:215], s[36:37], 0, v[132:133]
	s_mov_b32 m0, s30
	ds_read_b128 v[182:185], v149 offset:16384
	ds_read_b128 v[186:189], v149 offset:17408
	ds_read_b128 v[190:193], v149 offset:18432
	ds_read_b128 v[194:197], v149 offset:19456
	ds_read_b128 v[198:201], v149 offset:20480
	ds_read_b128 v[202:205], v149 offset:21504
	ds_read_b128 v[206:209], v149 offset:22528
	ds_read_b128 v[210:213], v149 offset:23552
	global_load_lds_dwordx4 v[214:215], off
	s_add_i32 m0, s30, 0x2000
	s_add_u32 s30, s36, 0xb0000
	v_lshl_add_u64 v[216:217], s[36:37], 0, v[128:129]
	s_addc_u32 s31, s37, 0
	s_add_i32 s58, s48, s33
	global_load_lds_dwordx4 v[216:217], off
	v_lshl_add_u64 v[218:219], s[30:31], 0, v[132:133]
	s_mov_b32 m0, s58
	v_lshl_add_u64 v[220:221], s[38:39], 0, v[130:131]
	global_load_lds_dwordx4 v[218:219], off
	v_lshl_add_u64 v[218:219], s[30:31], 0, v[128:129]
	s_add_i32 m0, s58, 0x2000
	s_nop 0
	global_load_lds_dwordx4 v[218:219], off
	v_lshl_add_u64 v[218:219], s[38:39], 0, v[134:135]
	s_mov_b32 m0, s40
	s_nop 0
	global_load_lds_dwordx4 v[218:219], off
	s_mov_b32 m0, s41
	s_nop 0
	global_load_lds_dwordx4 v[220:221], off
	s_waitcnt vmcnt(8)
	s_waitcnt lgkmcnt(0)
	s_barrier
	s_setprio 1
	s_waitcnt lgkmcnt(0)
	v_mfma_f32_16x16x32_bf16 v[60:63], v[150:153], v[182:185], v[60:63]
	v_mfma_f32_16x16x32_bf16 v[56:59], v[158:161], v[182:185], v[56:59]
	v_mfma_f32_16x16x32_bf16 v[52:55], v[150:153], v[190:193], v[52:55]
	v_mfma_f32_16x16x32_bf16 v[48:51], v[158:161], v[190:193], v[48:51]
	v_mfma_f32_16x16x32_bf16 v[36:39], v[150:153], v[198:201], v[36:39]
	v_mfma_f32_16x16x32_bf16 v[32:35], v[158:161], v[198:201], v[32:35]
	v_mfma_f32_16x16x32_bf16 v[20:23], v[150:153], v[206:209], v[20:23]
	v_mfma_f32_16x16x32_bf16 v[16:19], v[158:161], v[206:209], v[16:19]
	v_mfma_f32_16x16x32_bf16 v[60:63], v[154:157], v[186:189], v[60:63]
	v_mfma_f32_16x16x32_bf16 v[56:59], v[162:165], v[186:189], v[56:59]
	v_mfma_f32_16x16x32_bf16 v[52:55], v[154:157], v[194:197], v[52:55]
	v_mfma_f32_16x16x32_bf16 v[48:51], v[162:165], v[194:197], v[48:51]
	v_mfma_f32_16x16x32_bf16 v[36:39], v[154:157], v[202:205], v[36:39]
	v_mfma_f32_16x16x32_bf16 v[32:35], v[162:165], v[202:205], v[32:35]
	v_mfma_f32_16x16x32_bf16 v[20:23], v[154:157], v[210:213], v[20:23]
	v_mfma_f32_16x16x32_bf16 v[16:19], v[162:165], v[210:213], v[16:19]
	v_mfma_f32_16x16x32_bf16 v[44:47], v[166:169], v[182:185], v[44:47]
	v_mfma_f32_16x16x32_bf16 v[40:43], v[174:177], v[182:185], v[40:43]
	v_mfma_f32_16x16x32_bf16 v[28:31], v[166:169], v[190:193], v[28:31]
	v_mfma_f32_16x16x32_bf16 v[24:27], v[174:177], v[190:193], v[24:27]
	v_mfma_f32_16x16x32_bf16 v[12:15], v[166:169], v[198:201], v[12:15]
	v_mfma_f32_16x16x32_bf16 v[8:11], v[174:177], v[198:201], v[8:11]
	v_mfma_f32_16x16x32_bf16 v[4:7], v[166:169], v[206:209], v[4:7]
	v_mfma_f32_16x16x32_bf16 v[0:3], v[174:177], v[206:209], v[0:3]
	v_mfma_f32_16x16x32_bf16 v[44:47], v[170:173], v[186:189], v[44:47]
	v_mfma_f32_16x16x32_bf16 v[40:43], v[178:181], v[186:189], v[40:43]
	v_mfma_f32_16x16x32_bf16 v[28:31], v[170:173], v[194:197], v[28:31]
	v_mfma_f32_16x16x32_bf16 v[24:27], v[178:181], v[194:197], v[24:27]
	v_mfma_f32_16x16x32_bf16 v[12:15], v[170:173], v[202:205], v[12:15]
	v_mfma_f32_16x16x32_bf16 v[8:11], v[178:181], v[202:205], v[8:11]
	v_mfma_f32_16x16x32_bf16 v[4:7], v[170:173], v[210:213], v[4:7]
	v_mfma_f32_16x16x32_bf16 v[0:3], v[178:181], v[210:213], v[0:3]
	s_setprio 0
	s_barrier
	s_add_i32 s58, 0, 0x18000
	s_add_i32 s59, 0, 0x1c000
	v_add_u32_e32 v162, s58, v145
	v_add_u32_e32 v178, s59, v145
	ds_read_b128 v[150:153], v162
	ds_read_b128 v[154:157], v162 offset:1024
	ds_read_b128 v[158:161], v162 offset:2048
	ds_read_b128 v[162:165], v162 offset:3072
	ds_read_b128 v[166:169], v178
	ds_read_b128 v[170:173], v178 offset:1024
	ds_read_b128 v[174:177], v178 offset:2048
	ds_read_b128 v[178:181], v178 offset:3072
	s_add_u32 s30, s38, 0xb0000
	s_addc_u32 s31, s39, 0
	s_mov_b32 m0, s42
	v_lshl_add_u64 v[222:223], s[30:31], 0, v[134:135]
	ds_read_b128 v[182:185], v149 offset:32768
	ds_read_b128 v[186:189], v149 offset:33792
	ds_read_b128 v[190:193], v149 offset:34816
	ds_read_b128 v[194:197], v149 offset:35840
	ds_read_b128 v[198:201], v149 offset:36864
	ds_read_b128 v[202:205], v149 offset:37888
	ds_read_b128 v[206:209], v149 offset:38912
	ds_read_b128 v[210:213], v149 offset:39936
	global_load_lds_dwordx4 v[222:223], off
	v_lshl_add_u64 v[222:223], s[30:31], 0, v[130:131]
	s_mov_b32 m0, s43
	s_nop 0
	global_load_lds_dwordx4 v[222:223], off
	s_waitcnt vmcnt(8)
	s_waitcnt lgkmcnt(0)
	s_barrier
	s_setprio 1
	s_waitcnt lgkmcnt(0)
	v_mfma_f32_16x16x32_bf16 v[124:127], v[150:153], v[182:185], v[124:127]
	v_mfma_f32_16x16x32_bf16 v[120:123], v[158:161], v[182:185], v[120:123]
	v_mfma_f32_16x16x32_bf16 v[116:119], v[150:153], v[190:193], v[116:119]
	v_mfma_f32_16x16x32_bf16 v[112:115], v[158:161], v[190:193], v[112:115]
	v_mfma_f32_16x16x32_bf16 v[100:103], v[150:153], v[198:201], v[100:103]
	v_mfma_f32_16x16x32_bf16 v[96:99], v[158:161], v[198:201], v[96:99]
	v_mfma_f32_16x16x32_bf16 v[84:87], v[150:153], v[206:209], v[84:87]
	v_mfma_f32_16x16x32_bf16 v[80:83], v[158:161], v[206:209], v[80:83]
	v_mfma_f32_16x16x32_bf16 v[124:127], v[154:157], v[186:189], v[124:127]
	v_mfma_f32_16x16x32_bf16 v[120:123], v[162:165], v[186:189], v[120:123]
	v_mfma_f32_16x16x32_bf16 v[116:119], v[154:157], v[194:197], v[116:119]
	v_mfma_f32_16x16x32_bf16 v[112:115], v[162:165], v[194:197], v[112:115]
	v_mfma_f32_16x16x32_bf16 v[100:103], v[154:157], v[202:205], v[100:103]
	v_mfma_f32_16x16x32_bf16 v[96:99], v[162:165], v[202:205], v[96:99]
	v_mfma_f32_16x16x32_bf16 v[84:87], v[154:157], v[210:213], v[84:87]
	v_mfma_f32_16x16x32_bf16 v[80:83], v[162:165], v[210:213], v[80:83]
	v_mfma_f32_16x16x32_bf16 v[108:111], v[166:169], v[182:185], v[108:111]
	v_mfma_f32_16x16x32_bf16 v[104:107], v[174:177], v[182:185], v[104:107]
	v_mfma_f32_16x16x32_bf16 v[92:95], v[166:169], v[190:193], v[92:95]
	v_mfma_f32_16x16x32_bf16 v[88:91], v[174:177], v[190:193], v[88:91]
	v_mfma_f32_16x16x32_bf16 v[76:79], v[166:169], v[198:201], v[76:79]
	v_mfma_f32_16x16x32_bf16 v[72:75], v[174:177], v[198:201], v[72:75]
	v_mfma_f32_16x16x32_bf16 v[68:71], v[166:169], v[206:209], v[68:71]
	v_mfma_f32_16x16x32_bf16 v[64:67], v[174:177], v[206:209], v[64:67]
	v_mfma_f32_16x16x32_bf16 v[108:111], v[170:173], v[186:189], v[108:111]
	v_mfma_f32_16x16x32_bf16 v[104:107], v[178:181], v[186:189], v[104:107]
	v_mfma_f32_16x16x32_bf16 v[92:95], v[170:173], v[194:197], v[92:95]
	v_mfma_f32_16x16x32_bf16 v[88:91], v[178:181], v[194:197], v[88:91]
	v_mfma_f32_16x16x32_bf16 v[76:79], v[170:173], v[202:205], v[76:79]
	v_mfma_f32_16x16x32_bf16 v[72:75], v[178:181], v[202:205], v[72:75]
	v_mfma_f32_16x16x32_bf16 v[68:71], v[170:173], v[210:213], v[68:71]
	v_mfma_f32_16x16x32_bf16 v[64:67], v[178:181], v[210:213], v[64:67]
	s_setprio 0
	s_barrier
	s_add_i32 s30, s58, s33
	v_lshl_add_u64 v[214:215], v[214:215], 0, s[16:17]
	s_mov_b32 m0, s30
	ds_read_b128 v[182:185], v149 offset:49152
	ds_read_b128 v[186:189], v149 offset:50176
	ds_read_b128 v[190:193], v149 offset:51200
	ds_read_b128 v[194:197], v149 offset:52224
	ds_read_b128 v[198:201], v149 offset:53248
	ds_read_b128 v[202:205], v149 offset:54272
	ds_read_b128 v[206:209], v149 offset:55296
	ds_read_b128 v[210:213], v149 offset:56320
	global_load_lds_dwordx4 v[214:215], off
	s_add_i32 m0, s30, 0x2000
	s_add_u32 s30, s36, 0xb0080
	v_lshl_add_u64 v[214:215], v[216:217], 0, s[16:17]
	s_addc_u32 s31, s37, 0
	s_add_i32 s36, s59, s33
	global_load_lds_dwordx4 v[214:215], off
	v_lshl_add_u64 v[214:215], s[30:31], 0, v[132:133]
	s_mov_b32 m0, s36
	s_nop 0
	global_load_lds_dwordx4 v[214:215], off
	v_lshl_add_u64 v[214:215], s[30:31], 0, v[128:129]
	s_add_i32 m0, s36, 0x2000
	s_nop 0
	global_load_lds_dwordx4 v[214:215], off
	v_lshl_add_u64 v[214:215], v[218:219], 0, s[16:17]
	s_mov_b32 m0, s45
	s_nop 0
	global_load_lds_dwordx4 v[214:215], off
	v_lshl_add_u64 v[214:215], v[220:221], 0, s[16:17]
	s_mov_b32 m0, s46
	s_nop 0
	global_load_lds_dwordx4 v[214:215], off
	s_waitcnt vmcnt(8)
	s_waitcnt lgkmcnt(0)
	s_barrier
	s_setprio 1
	s_waitcnt lgkmcnt(0)
	v_mfma_f32_16x16x32_bf16 v[60:63], v[150:153], v[182:185], v[60:63]
	v_mfma_f32_16x16x32_bf16 v[56:59], v[158:161], v[182:185], v[56:59]
	v_mfma_f32_16x16x32_bf16 v[52:55], v[150:153], v[190:193], v[52:55]
	v_mfma_f32_16x16x32_bf16 v[48:51], v[158:161], v[190:193], v[48:51]
	v_mfma_f32_16x16x32_bf16 v[36:39], v[150:153], v[198:201], v[36:39]
	v_mfma_f32_16x16x32_bf16 v[32:35], v[158:161], v[198:201], v[32:35]
	v_mfma_f32_16x16x32_bf16 v[20:23], v[150:153], v[206:209], v[20:23]
	v_mfma_f32_16x16x32_bf16 v[16:19], v[158:161], v[206:209], v[16:19]
	v_mfma_f32_16x16x32_bf16 v[60:63], v[154:157], v[186:189], v[60:63]
	v_mfma_f32_16x16x32_bf16 v[56:59], v[162:165], v[186:189], v[56:59]
	v_mfma_f32_16x16x32_bf16 v[52:55], v[154:157], v[194:197], v[52:55]
	v_mfma_f32_16x16x32_bf16 v[48:51], v[162:165], v[194:197], v[48:51]
	v_mfma_f32_16x16x32_bf16 v[36:39], v[154:157], v[202:205], v[36:39]
	v_mfma_f32_16x16x32_bf16 v[32:35], v[162:165], v[202:205], v[32:35]
	v_mfma_f32_16x16x32_bf16 v[20:23], v[154:157], v[210:213], v[20:23]
	v_mfma_f32_16x16x32_bf16 v[16:19], v[162:165], v[210:213], v[16:19]
	v_mfma_f32_16x16x32_bf16 v[44:47], v[166:169], v[182:185], v[44:47]
	v_mfma_f32_16x16x32_bf16 v[40:43], v[174:177], v[182:185], v[40:43]
	v_mfma_f32_16x16x32_bf16 v[28:31], v[166:169], v[190:193], v[28:31]
	v_mfma_f32_16x16x32_bf16 v[24:27], v[174:177], v[190:193], v[24:27]
	v_mfma_f32_16x16x32_bf16 v[12:15], v[166:169], v[198:201], v[12:15]
	v_mfma_f32_16x16x32_bf16 v[8:11], v[174:177], v[198:201], v[8:11]
	v_mfma_f32_16x16x32_bf16 v[4:7], v[166:169], v[206:209], v[4:7]
	v_mfma_f32_16x16x32_bf16 v[0:3], v[174:177], v[206:209], v[0:3]
	v_mfma_f32_16x16x32_bf16 v[44:47], v[170:173], v[186:189], v[44:47]
	v_mfma_f32_16x16x32_bf16 v[40:43], v[178:181], v[186:189], v[40:43]
	v_mfma_f32_16x16x32_bf16 v[28:31], v[170:173], v[194:197], v[28:31]
	v_mfma_f32_16x16x32_bf16 v[24:27], v[178:181], v[194:197], v[24:27]
	v_mfma_f32_16x16x32_bf16 v[12:15], v[170:173], v[202:205], v[12:15]
	v_mfma_f32_16x16x32_bf16 v[8:11], v[178:181], v[202:205], v[8:11]
	v_mfma_f32_16x16x32_bf16 v[4:7], v[170:173], v[210:213], v[4:7]
	v_mfma_f32_16x16x32_bf16 v[0:3], v[178:181], v[210:213], v[0:3]
	s_setprio 0
	s_barrier
	s_add_i32 s57, s57, 2
	s_add_u32 s55, s55, 0x100
	s_addc_u32 s56, s56, 0
	s_cmp_gt_u32 s57, 41
	s_mov_b64 s[30:31], s[34:35]
	s_cbranch_scc0 .LBB0_2021
	s_and_b64 vcc, exec, s[18:19]
	s_cbranch_vccz .LBB0_2024
	s_barrier

.LBB0_2196:
	ds_read_b128 v[0:3], v161
	ds_read_b128 v[4:7], v161 offset:1024
	ds_read_b128 v[8:11], v161 offset:2048
	ds_read_b128 v[12:15], v161 offset:3072
	ds_read_b128 v[16:19], v162
	ds_read_b128 v[20:23], v162 offset:1024
	ds_read_b128 v[24:27], v162 offset:2048
	ds_read_b128 v[28:31], v162 offset:3072
	s_ashr_i32 s35, s34, 31
	s_lshl_b64 s[36:37], s[34:35], 17
	s_add_u32 s36, s8, s36
	s_addc_u32 s37, s9, s37
	s_and_b64 s[38:39], s[6:7], exec
	s_cselect_b32 s49, s37, s43
	s_cselect_b32 s48, s36, s42
	s_ashr_i32 s31, s30, 31
	s_lshl_b64 s[38:39], s[30:31], 17
	s_add_u32 s38, s4, s38
	s_addc_u32 s39, s5, s39
	s_and_b64 s[46:47], s[6:7], exec
	s_cselect_b32 s47, s39, s45
	s_cselect_b32 s46, s38, s44
	s_add_u32 s64, s42, 0x10080
	s_addc_u32 s65, s43, 0
	s_mov_b32 m0, s56
	v_lshl_add_u64 v[64:65], s[64:65], 0, v[140:141]
	ds_read_b128 v[32:35], v163
	ds_read_b128 v[36:39], v163 offset:1024
	ds_read_b128 v[40:43], v163 offset:2048
	ds_read_b128 v[44:47], v163 offset:3072
	ds_read_b128 v[48:51], v163 offset:4096
	ds_read_b128 v[52:55], v163 offset:5120
	ds_read_b128 v[56:59], v163 offset:6144
	ds_read_b128 v[60:63], v163 offset:7168
	global_load_lds_dwordx4 v[64:65], off
	v_lshl_add_u64 v[64:65], s[64:65], 0, v[144:145]
	s_mov_b32 m0, s57
	s_nop 0
	global_load_lds_dwordx4 v[64:65], off
	s_waitcnt vmcnt(8)
	s_waitcnt lgkmcnt(0)
	s_barrier
	s_setprio 1
	s_waitcnt lgkmcnt(0)
	v_mfma_f32_16x16x32_bf16 v[64:67], v[0:3], v[32:35], 0
	v_mfma_f32_16x16x32_bf16 v[68:71], v[8:11], v[32:35], 0
	v_mfma_f32_16x16x32_bf16 v[72:75], v[0:3], v[40:43], 0
	v_mfma_f32_16x16x32_bf16 v[76:79], v[8:11], v[40:43], 0
	v_mfma_f32_16x16x32_bf16 v[80:83], v[0:3], v[48:51], 0
	v_mfma_f32_16x16x32_bf16 v[84:87], v[8:11], v[48:51], 0
	v_mfma_f32_16x16x32_bf16 v[88:91], v[0:3], v[56:59], 0
	v_mfma_f32_16x16x32_bf16 v[92:95], v[8:11], v[56:59], 0
	v_mfma_f32_16x16x32_bf16 v[64:67], v[4:7], v[36:39], v[64:67]
	v_mfma_f32_16x16x32_bf16 v[68:71], v[12:15], v[36:39], v[68:71]
	v_mfma_f32_16x16x32_bf16 v[72:75], v[4:7], v[44:47], v[72:75]
	v_mfma_f32_16x16x32_bf16 v[76:79], v[12:15], v[44:47], v[76:79]
	v_mfma_f32_16x16x32_bf16 v[80:83], v[4:7], v[52:55], v[80:83]
	v_mfma_f32_16x16x32_bf16 v[84:87], v[12:15], v[52:55], v[84:87]
	v_mfma_f32_16x16x32_bf16 v[88:91], v[4:7], v[60:63], v[88:91]
	v_mfma_f32_16x16x32_bf16 v[92:95], v[12:15], v[60:63], v[92:95]
	v_mfma_f32_16x16x32_bf16 v[96:99], v[16:19], v[32:35], 0
	v_mfma_f32_16x16x32_bf16 v[32:35], v[24:27], v[32:35], 0
	v_mfma_f32_16x16x32_bf16 v[96:99], v[20:23], v[36:39], v[96:99]
	v_mfma_f32_16x16x32_bf16 v[32:35], v[28:31], v[36:39], v[32:35]
	v_mfma_f32_16x16x32_bf16 v[36:39], v[16:19], v[40:43], 0
	v_mfma_f32_16x16x32_bf16 v[40:43], v[24:27], v[40:43], 0
	v_mfma_f32_16x16x32_bf16 v[36:39], v[20:23], v[44:47], v[36:39]
	v_mfma_f32_16x16x32_bf16 v[40:43], v[28:31], v[44:47], v[40:43]
	v_mfma_f32_16x16x32_bf16 v[44:47], v[16:19], v[48:51], 0
	v_mfma_f32_16x16x32_bf16 v[48:51], v[24:27], v[48:51], 0
	v_mfma_f32_16x16x32_bf16 v[44:47], v[20:23], v[52:55], v[44:47]
	v_mfma_f32_16x16x32_bf16 v[48:51], v[28:31], v[52:55], v[48:51]
	v_mfma_f32_16x16x32_bf16 v[52:55], v[16:19], v[56:59], 0
	v_mfma_f32_16x16x32_bf16 v[56:59], v[24:27], v[56:59], 0
	v_mfma_f32_16x16x32_bf16 v[52:55], v[20:23], v[60:63], v[52:55]
	v_mfma_f32_16x16x32_bf16 v[56:59], v[28:31], v[60:63], v[56:59]
	s_setprio 0
	s_barrier
	s_add_i32 s64, s3, s33
	v_lshl_add_u64 v[156:157], s[44:45], 0, v[142:143]
	s_add_i32 s31, s64, 0x2000
	v_lshl_add_u64 v[128:129], v[156:157], 0, s[18:19]
	s_mov_b32 m0, s64
	v_lshl_add_u64 v[212:213], s[44:45], 0, v[146:147]
	s_add_u32 s66, s44, 0x10100
	ds_read_b128 v[60:63], v163 offset:16384
	ds_read_b128 v[100:103], v163 offset:17408
	ds_read_b128 v[104:107], v163 offset:18432
	ds_read_b128 v[108:111], v163 offset:19456
	ds_read_b128 v[112:115], v163 offset:20480
	ds_read_b128 v[116:119], v163 offset:21504
	ds_read_b128 v[120:123], v163 offset:22528
	ds_read_b128 v[124:127], v163 offset:23552
	global_load_lds_dwordx4 v[128:129], off
	v_lshl_add_u64 v[128:129], v[212:213], 0, s[18:19]
	s_mov_b32 m0, s31
	s_addc_u32 s67, s45, 0
	s_add_i32 s35, s55, s33
	global_load_lds_dwordx4 v[128:129], off
	v_lshl_add_u64 v[128:129], s[66:67], 0, v[142:143]
	s_mov_b32 m0, s35
	s_add_i32 s63, s35, 0x2000
	global_load_lds_dwordx4 v[128:129], off
	v_lshl_add_u64 v[128:129], s[66:67], 0, v[146:147]
	s_mov_b32 m0, s63
	v_lshl_add_u64 v[214:215], s[42:43], 0, v[140:141]
	global_load_lds_dwordx4 v[128:129], off
	v_lshl_add_u64 v[128:129], v[214:215], 0, s[18:19]
	s_mov_b32 m0, s41
	v_lshl_add_u64 v[216:217], s[42:43], 0, v[144:145]
	global_load_lds_dwordx4 v[128:129], off
	v_lshl_add_u64 v[128:129], v[216:217], 0, s[18:19]
	s_mov_b32 m0, s50
	s_nop 0
	global_load_lds_dwordx4 v[128:129], off
	s_waitcnt vmcnt(8)
	s_waitcnt lgkmcnt(0)
	s_barrier
	s_setprio 1
	s_waitcnt lgkmcnt(0)
	v_mfma_f32_16x16x32_bf16 v[128:131], v[0:3], v[60:63], 0
	v_mfma_f32_16x16x32_bf16 v[136:139], v[0:3], v[104:107], 0
	v_mfma_f32_16x16x32_bf16 v[164:167], v[0:3], v[112:115], 0
	v_mfma_f32_16x16x32_bf16 v[0:3], v[0:3], v[120:123], 0
	v_mfma_f32_16x16x32_bf16 v[128:131], v[4:7], v[100:103], v[128:131]
	v_mfma_f32_16x16x32_bf16 v[136:139], v[4:7], v[108:111], v[136:139]
	v_mfma_f32_16x16x32_bf16 v[164:167], v[4:7], v[116:119], v[164:167]
	v_mfma_f32_16x16x32_bf16 v[0:3], v[4:7], v[124:127], v[0:3]
	v_mfma_f32_16x16x32_bf16 v[4:7], v[8:11], v[120:123], 0
	v_mfma_f32_16x16x32_bf16 v[132:135], v[8:11], v[60:63], 0
	v_mfma_f32_16x16x32_bf16 v[152:155], v[8:11], v[104:107], 0
	v_mfma_f32_16x16x32_bf16 v[168:171], v[8:11], v[112:115], 0
	v_mfma_f32_16x16x32_bf16 v[4:7], v[12:15], v[124:127], v[4:7]
	v_mfma_f32_16x16x32_bf16 v[132:135], v[12:15], v[100:103], v[132:135]
	v_mfma_f32_16x16x32_bf16 v[152:155], v[12:15], v[108:111], v[152:155]
	v_mfma_f32_16x16x32_bf16 v[168:171], v[12:15], v[116:119], v[168:171]
	v_mfma_f32_16x16x32_bf16 v[8:11], v[16:19], v[60:63], 0
	v_mfma_f32_16x16x32_bf16 v[12:15], v[24:27], v[60:63], 0
	v_mfma_f32_16x16x32_bf16 v[8:11], v[20:23], v[100:103], v[8:11]
	v_mfma_f32_16x16x32_bf16 v[12:15], v[28:31], v[100:103], v[12:15]
	v_mfma_f32_16x16x32_bf16 v[60:63], v[16:19], v[104:107], 0
	v_mfma_f32_16x16x32_bf16 v[100:103], v[24:27], v[104:107], 0
	v_mfma_f32_16x16x32_bf16 v[104:107], v[16:19], v[112:115], 0
	v_mfma_f32_16x16x32_bf16 v[16:19], v[16:19], v[120:123], 0
	v_mfma_f32_16x16x32_bf16 v[60:63], v[20:23], v[108:111], v[60:63]
	v_mfma_f32_16x16x32_bf16 v[100:103], v[28:31], v[108:111], v[100:103]
	v_mfma_f32_16x16x32_bf16 v[104:107], v[20:23], v[116:119], v[104:107]
	v_mfma_f32_16x16x32_bf16 v[108:111], v[24:27], v[112:115], 0
	v_mfma_f32_16x16x32_bf16 v[16:19], v[20:23], v[124:127], v[16:19]
	v_mfma_f32_16x16x32_bf16 v[20:23], v[24:27], v[120:123], 0
	v_mfma_f32_16x16x32_bf16 v[108:111], v[28:31], v[116:119], v[108:111]
	v_mfma_f32_16x16x32_bf16 v[20:23], v[28:31], v[124:127], v[20:23]
	s_setprio 0
	s_barrier
	s_add_i32 s65, 0, 0x18000
	s_add_i32 s70, 0, 0x1c000
	v_add_u32_e32 v224, s65, v159
	v_add_u32_e32 v228, s70, v159
	ds_read_b128 v[24:27], v224
	ds_read_b128 v[28:31], v224 offset:1024
	ds_read_b128 v[112:115], v224 offset:2048
	ds_read_b128 v[116:119], v224 offset:3072
	ds_read_b128 v[120:123], v228
	ds_read_b128 v[124:127], v228 offset:1024
	ds_read_b128 v[172:175], v228 offset:2048
	ds_read_b128 v[176:179], v228 offset:3072
	s_add_u32 s66, s42, 0x10100
	s_addc_u32 s67, s43, 0
	s_mov_b32 m0, s51
	v_lshl_add_u64 v[218:219], s[66:67], 0, v[140:141]
	ds_read_b128 v[180:183], v163 offset:32768
	ds_read_b128 v[184:187], v163 offset:33792
	ds_read_b128 v[188:191], v163 offset:34816
	ds_read_b128 v[192:195], v163 offset:35840
	ds_read_b128 v[196:199], v163 offset:36864
	ds_read_b128 v[200:203], v163 offset:37888
	ds_read_b128 v[204:207], v163 offset:38912
	ds_read_b128 v[208:211], v163 offset:39936
	global_load_lds_dwordx4 v[218:219], off
	v_lshl_add_u64 v[218:219], s[66:67], 0, v[144:145]
	s_mov_b32 m0, s52
	s_nop 0
	global_load_lds_dwordx4 v[218:219], off
	s_waitcnt vmcnt(8)
	s_waitcnt lgkmcnt(0)
	s_barrier
	s_setprio 1
	s_waitcnt lgkmcnt(0)
	v_mfma_f32_16x16x32_bf16 v[64:67], v[24:27], v[180:183], v[64:67]
	v_mfma_f32_16x16x32_bf16 v[68:71], v[112:115], v[180:183], v[68:71]
	v_mfma_f32_16x16x32_bf16 v[72:75], v[24:27], v[188:191], v[72:75]
	v_mfma_f32_16x16x32_bf16 v[76:79], v[112:115], v[188:191], v[76:79]
	v_mfma_f32_16x16x32_bf16 v[80:83], v[24:27], v[196:199], v[80:83]
	v_mfma_f32_16x16x32_bf16 v[84:87], v[112:115], v[196:199], v[84:87]
	v_mfma_f32_16x16x32_bf16 v[88:91], v[24:27], v[204:207], v[88:91]
	v_mfma_f32_16x16x32_bf16 v[92:95], v[112:115], v[204:207], v[92:95]
	v_mfma_f32_16x16x32_bf16 v[64:67], v[28:31], v[184:187], v[64:67]
	v_mfma_f32_16x16x32_bf16 v[68:71], v[116:119], v[184:187], v[68:71]
	v_mfma_f32_16x16x32_bf16 v[72:75], v[28:31], v[192:195], v[72:75]
	v_mfma_f32_16x16x32_bf16 v[76:79], v[116:119], v[192:195], v[76:79]
	v_mfma_f32_16x16x32_bf16 v[80:83], v[28:31], v[200:203], v[80:83]
	v_mfma_f32_16x16x32_bf16 v[84:87], v[116:119], v[200:203], v[84:87]
	v_mfma_f32_16x16x32_bf16 v[88:91], v[28:31], v[208:211], v[88:91]
	v_mfma_f32_16x16x32_bf16 v[92:95], v[116:119], v[208:211], v[92:95]
	v_mfma_f32_16x16x32_bf16 v[96:99], v[120:123], v[180:183], v[96:99]
	v_mfma_f32_16x16x32_bf16 v[32:35], v[172:175], v[180:183], v[32:35]
	v_mfma_f32_16x16x32_bf16 v[36:39], v[120:123], v[188:191], v[36:39]
	v_mfma_f32_16x16x32_bf16 v[40:43], v[172:175], v[188:191], v[40:43]
	v_mfma_f32_16x16x32_bf16 v[44:47], v[120:123], v[196:199], v[44:47]
	v_mfma_f32_16x16x32_bf16 v[48:51], v[172:175], v[196:199], v[48:51]
	v_mfma_f32_16x16x32_bf16 v[52:55], v[120:123], v[204:207], v[52:55]
	v_mfma_f32_16x16x32_bf16 v[56:59], v[172:175], v[204:207], v[56:59]
	v_mfma_f32_16x16x32_bf16 v[96:99], v[124:127], v[184:187], v[96:99]
	v_mfma_f32_16x16x32_bf16 v[32:35], v[176:179], v[184:187], v[32:35]
	v_mfma_f32_16x16x32_bf16 v[36:39], v[124:127], v[192:195], v[36:39]
	v_mfma_f32_16x16x32_bf16 v[40:43], v[176:179], v[192:195], v[40:43]
	v_mfma_f32_16x16x32_bf16 v[44:47], v[124:127], v[200:203], v[44:47]
	v_mfma_f32_16x16x32_bf16 v[48:51], v[176:179], v[200:203], v[48:51]
	v_mfma_f32_16x16x32_bf16 v[52:55], v[124:127], v[208:211], v[52:55]
	v_mfma_f32_16x16x32_bf16 v[56:59], v[176:179], v[208:211], v[56:59]
	s_setprio 0
	s_barrier
	s_add_i32 s66, s65, s33
	s_add_i32 s65, s66, 0x2000
	v_lshl_add_u64 v[156:157], v[156:157], 0, s[20:21]
	s_mov_b32 m0, s66
	s_add_u32 s68, s44, 0x10180
	ds_read_b128 v[180:183], v163 offset:49152
	ds_read_b128 v[184:187], v163 offset:50176
	ds_read_b128 v[188:191], v163 offset:51200
	ds_read_b128 v[192:195], v163 offset:52224
	ds_read_b128 v[196:199], v163 offset:53248
	ds_read_b128 v[200:203], v163 offset:54272
	ds_read_b128 v[204:207], v163 offset:55296
	ds_read_b128 v[208:211], v163 offset:56320
	global_load_lds_dwordx4 v[156:157], off
	v_lshl_add_u64 v[156:157], v[212:213], 0, s[20:21]
	s_mov_b32 m0, s65
	s_addc_u32 s69, s45, 0
	s_add_i32 s44, s70, s33
	global_load_lds_dwordx4 v[156:157], off
	v_lshl_add_u64 v[156:157], s[68:69], 0, v[142:143]
	s_mov_b32 m0, s44
	s_add_i32 s45, s44, 0x2000
	global_load_lds_dwordx4 v[156:157], off
	v_lshl_add_u64 v[156:157], s[68:69], 0, v[146:147]
	s_mov_b32 m0, s45
	s_nop 0
	global_load_lds_dwordx4 v[156:157], off
	v_lshl_add_u64 v[156:157], v[214:215], 0, s[20:21]
	s_mov_b32 m0, s53
	s_nop 0
	global_load_lds_dwordx4 v[156:157], off
	v_lshl_add_u64 v[156:157], v[216:217], 0, s[20:21]
	s_mov_b32 m0, s54
	s_nop 0
	global_load_lds_dwordx4 v[156:157], off
	s_waitcnt vmcnt(8)
	s_waitcnt lgkmcnt(0)
	s_barrier
	s_setprio 1
	s_waitcnt lgkmcnt(0)
	v_mfma_f32_16x16x32_bf16 v[0:3], v[24:27], v[204:207], v[0:3]
	v_mfma_f32_16x16x32_bf16 v[4:7], v[112:115], v[204:207], v[4:7]
	v_mfma_f32_16x16x32_bf16 v[128:131], v[24:27], v[180:183], v[128:131]
	v_mfma_f32_16x16x32_bf16 v[132:135], v[112:115], v[180:183], v[132:135]
	v_mfma_f32_16x16x32_bf16 v[136:139], v[24:27], v[188:191], v[136:139]
	v_mfma_f32_16x16x32_bf16 v[152:155], v[112:115], v[188:191], v[152:155]
	v_mfma_f32_16x16x32_bf16 v[164:167], v[24:27], v[196:199], v[164:167]
	v_mfma_f32_16x16x32_bf16 v[168:171], v[112:115], v[196:199], v[168:171]
	v_mfma_f32_16x16x32_bf16 v[0:3], v[28:31], v[208:211], v[0:3]
	v_mfma_f32_16x16x32_bf16 v[4:7], v[116:119], v[208:211], v[4:7]
	v_mfma_f32_16x16x32_bf16 v[128:131], v[28:31], v[184:187], v[128:131]
	v_mfma_f32_16x16x32_bf16 v[132:135], v[116:119], v[184:187], v[132:135]
	v_mfma_f32_16x16x32_bf16 v[136:139], v[28:31], v[192:195], v[136:139]
	v_mfma_f32_16x16x32_bf16 v[152:155], v[116:119], v[192:195], v[152:155]
	v_mfma_f32_16x16x32_bf16 v[164:167], v[28:31], v[200:203], v[164:167]
	v_mfma_f32_16x16x32_bf16 v[168:171], v[116:119], v[200:203], v[168:171]
	v_mfma_f32_16x16x32_bf16 v[8:11], v[120:123], v[180:183], v[8:11]
	v_mfma_f32_16x16x32_bf16 v[12:15], v[172:175], v[180:183], v[12:15]
	v_mfma_f32_16x16x32_bf16 v[24:27], v[120:123], v[188:191], v[60:63]
	v_mfma_f32_16x16x32_bf16 v[28:31], v[172:175], v[188:191], v[100:103]
	v_mfma_f32_16x16x32_bf16 v[60:63], v[120:123], v[196:199], v[104:107]
	v_mfma_f32_16x16x32_bf16 v[100:103], v[172:175], v[196:199], v[108:111]
	v_mfma_f32_16x16x32_bf16 v[16:19], v[120:123], v[204:207], v[16:19]
	v_mfma_f32_16x16x32_bf16 v[20:23], v[172:175], v[204:207], v[20:23]
	v_mfma_f32_16x16x32_bf16 v[8:11], v[124:127], v[184:187], v[8:11]
	v_mfma_f32_16x16x32_bf16 v[12:15], v[176:179], v[184:187], v[12:15]
	v_mfma_f32_16x16x32_bf16 v[24:27], v[124:127], v[192:195], v[24:27]
	v_mfma_f32_16x16x32_bf16 v[28:31], v[176:179], v[192:195], v[28:31]
	v_mfma_f32_16x16x32_bf16 v[60:63], v[124:127], v[200:203], v[60:63]
	v_mfma_f32_16x16x32_bf16 v[100:103], v[176:179], v[200:203], v[100:103]
	v_mfma_f32_16x16x32_bf16 v[16:19], v[124:127], v[208:211], v[16:19]
	v_mfma_f32_16x16x32_bf16 v[20:23], v[176:179], v[208:211], v[20:23]
	s_setprio 0
	s_barrier
	ds_read_b128 v[104:107], v161
	ds_read_b128 v[108:111], v161 offset:1024
	ds_read_b128 v[112:115], v161 offset:2048
	ds_read_b128 v[116:119], v161 offset:3072
	ds_read_b128 v[120:123], v162
	ds_read_b128 v[124:127], v162 offset:1024
	ds_read_b128 v[172:175], v162 offset:2048
	ds_read_b128 v[176:179], v162 offset:3072
	s_add_u32 s42, s42, 0x10180
	s_addc_u32 s43, s43, 0
	s_mov_b32 m0, s56
	v_lshl_add_u64 v[156:157], s[42:43], 0, v[140:141]
	ds_read_b128 v[180:183], v163
	ds_read_b128 v[184:187], v163 offset:1024
	ds_read_b128 v[188:191], v163 offset:2048
	ds_read_b128 v[192:195], v163 offset:3072
	ds_read_b128 v[196:199], v163 offset:4096
	ds_read_b128 v[200:203], v163 offset:5120
	ds_read_b128 v[204:207], v163 offset:6144
	ds_read_b128 v[208:211], v163 offset:7168
	global_load_lds_dwordx4 v[156:157], off
	v_lshl_add_u64 v[156:157], s[42:43], 0, v[144:145]
	s_mov_b32 m0, s57
	s_nop 0
	global_load_lds_dwordx4 v[156:157], off
	s_waitcnt vmcnt(8)
	s_waitcnt lgkmcnt(0)
	s_barrier
	s_setprio 1
	s_waitcnt lgkmcnt(0)
	v_mfma_f32_16x16x32_bf16 v[64:67], v[104:107], v[180:183], v[64:67]
	v_mfma_f32_16x16x32_bf16 v[68:71], v[112:115], v[180:183], v[68:71]
	v_mfma_f32_16x16x32_bf16 v[72:75], v[104:107], v[188:191], v[72:75]
	v_mfma_f32_16x16x32_bf16 v[76:79], v[112:115], v[188:191], v[76:79]
	v_mfma_f32_16x16x32_bf16 v[80:83], v[104:107], v[196:199], v[80:83]
	v_mfma_f32_16x16x32_bf16 v[84:87], v[112:115], v[196:199], v[84:87]
	v_mfma_f32_16x16x32_bf16 v[88:91], v[104:107], v[204:207], v[88:91]
	v_mfma_f32_16x16x32_bf16 v[64:67], v[108:111], v[184:187], v[64:67]
	v_mfma_f32_16x16x32_bf16 v[68:71], v[116:119], v[184:187], v[68:71]
	v_mfma_f32_16x16x32_bf16 v[72:75], v[108:111], v[192:195], v[72:75]
	v_mfma_f32_16x16x32_bf16 v[76:79], v[116:119], v[192:195], v[76:79]
	v_mfma_f32_16x16x32_bf16 v[80:83], v[108:111], v[200:203], v[80:83]
	v_mfma_f32_16x16x32_bf16 v[84:87], v[116:119], v[200:203], v[84:87]
	v_mfma_f32_16x16x32_bf16 v[212:215], v[108:111], v[208:211], v[88:91]
	v_mfma_f32_16x16x32_bf16 v[88:91], v[112:115], v[204:207], v[92:95]
	v_mfma_f32_16x16x32_bf16 v[216:219], v[116:119], v[208:211], v[88:91]
	v_mfma_f32_16x16x32_bf16 v[32:35], v[172:175], v[180:183], v[32:35]
	v_mfma_f32_16x16x32_bf16 v[36:39], v[120:123], v[188:191], v[36:39]
	v_mfma_f32_16x16x32_bf16 v[40:43], v[172:175], v[188:191], v[40:43]
	v_mfma_f32_16x16x32_bf16 v[44:47], v[120:123], v[196:199], v[44:47]
	v_mfma_f32_16x16x32_bf16 v[48:51], v[172:175], v[196:199], v[48:51]
	v_mfma_f32_16x16x32_bf16 v[52:55], v[120:123], v[204:207], v[52:55]
	v_mfma_f32_16x16x32_bf16 v[56:59], v[172:175], v[204:207], v[56:59]
	v_mfma_f32_16x16x32_bf16 v[88:91], v[120:123], v[180:183], v[96:99]
	v_mfma_f32_16x16x32_bf16 v[32:35], v[176:179], v[184:187], v[32:35]
	v_mfma_f32_16x16x32_bf16 v[36:39], v[124:127], v[192:195], v[36:39]
	v_mfma_f32_16x16x32_bf16 v[40:43], v[176:179], v[192:195], v[40:43]
	v_mfma_f32_16x16x32_bf16 v[44:47], v[124:127], v[200:203], v[44:47]
	v_mfma_f32_16x16x32_bf16 v[48:51], v[176:179], v[200:203], v[48:51]
	v_mfma_f32_16x16x32_bf16 v[52:55], v[124:127], v[208:211], v[52:55]
	v_mfma_f32_16x16x32_bf16 v[56:59], v[176:179], v[208:211], v[56:59]
	v_mfma_f32_16x16x32_bf16 v[220:223], v[124:127], v[184:187], v[88:91]
	s_setprio 0
	s_barrier
	s_mov_b32 m0, s64
	v_lshl_add_u64 v[156:157], s[46:47], 0, v[142:143]
	s_add_u32 s42, s46, 0x10000
	ds_read_b128 v[88:91], v163 offset:16384
	ds_read_b128 v[92:95], v163 offset:17408
	ds_read_b128 v[96:99], v163 offset:18432
	ds_read_b128 v[180:183], v163 offset:19456
	ds_read_b128 v[184:187], v163 offset:20480
	ds_read_b128 v[188:191], v163 offset:21504
	ds_read_b128 v[192:195], v163 offset:22528
	ds_read_b128 v[196:199], v163 offset:23552
	global_load_lds_dwordx4 v[156:157], off
	v_lshl_add_u64 v[250:251], s[46:47], 0, v[146:147]
	s_mov_b32 m0, s31
	s_addc_u32 s43, s47, 0
	global_load_lds_dwordx4 v[250:251], off
	v_lshl_add_u64 v[200:201], s[42:43], 0, v[142:143]
	s_mov_b32 m0, s35
	v_lshl_add_u64 v[252:253], s[48:49], 0, v[140:141]
	global_load_lds_dwordx4 v[200:201], off
	v_lshl_add_u64 v[200:201], s[42:43], 0, v[146:147]
	s_mov_b32 m0, s63
	v_lshl_add_u64 v[148:149], s[48:49], 0, v[144:145]
	global_load_lds_dwordx4 v[200:201], off
	s_mov_b32 m0, s41
	s_nop 0
	global_load_lds_dwordx4 v[252:253], off
	s_mov_b32 m0, s50
	s_nop 0
	global_load_lds_dwordx4 v[148:149], off
	s_waitcnt vmcnt(8)
	s_waitcnt lgkmcnt(0)
	s_barrier
	s_setprio 1
	s_waitcnt lgkmcnt(0)
	v_mfma_f32_16x16x32_bf16 v[0:3], v[104:107], v[192:195], v[0:3]
	v_mfma_f32_16x16x32_bf16 v[4:7], v[112:115], v[192:195], v[4:7]
	v_mfma_f32_16x16x32_bf16 v[128:131], v[104:107], v[88:91], v[128:131]
	v_mfma_f32_16x16x32_bf16 v[132:135], v[112:115], v[88:91], v[132:135]
	v_mfma_f32_16x16x32_bf16 v[136:139], v[104:107], v[96:99], v[136:139]
	v_mfma_f32_16x16x32_bf16 v[152:155], v[112:115], v[96:99], v[152:155]
	v_mfma_f32_16x16x32_bf16 v[164:167], v[104:107], v[184:187], v[164:167]
	v_mfma_f32_16x16x32_bf16 v[168:171], v[112:115], v[184:187], v[168:171]
	v_mfma_f32_16x16x32_bf16 v[0:3], v[108:111], v[196:199], v[0:3]
	v_mfma_f32_16x16x32_bf16 v[4:7], v[116:119], v[196:199], v[4:7]
	v_mfma_f32_16x16x32_bf16 v[128:131], v[108:111], v[92:95], v[128:131]
	v_mfma_f32_16x16x32_bf16 v[132:135], v[116:119], v[92:95], v[132:135]
	v_mfma_f32_16x16x32_bf16 v[136:139], v[108:111], v[180:183], v[136:139]
	v_mfma_f32_16x16x32_bf16 v[152:155], v[116:119], v[180:183], v[152:155]
	v_mfma_f32_16x16x32_bf16 v[164:167], v[108:111], v[188:191], v[164:167]
	v_mfma_f32_16x16x32_bf16 v[168:171], v[116:119], v[188:191], v[168:171]
	v_mfma_f32_16x16x32_bf16 v[8:11], v[120:123], v[88:91], v[8:11]
	v_mfma_f32_16x16x32_bf16 v[200:203], v[124:127], v[92:95], v[8:11]
	v_mfma_f32_16x16x32_bf16 v[8:11], v[172:175], v[88:91], v[12:15]
	v_mfma_f32_16x16x32_bf16 v[204:207], v[176:179], v[92:95], v[8:11]
	v_mfma_f32_16x16x32_bf16 v[8:11], v[120:123], v[96:99], v[24:27]
	v_mfma_f32_16x16x32_bf16 v[208:211], v[124:127], v[180:183], v[8:11]
	v_mfma_f32_16x16x32_bf16 v[8:11], v[172:175], v[96:99], v[28:31]
	v_mfma_f32_16x16x32_bf16 v[28:31], v[176:179], v[180:183], v[8:11]
	v_mfma_f32_16x16x32_bf16 v[8:11], v[120:123], v[184:187], v[60:63]
	v_mfma_f32_16x16x32_bf16 v[180:183], v[124:127], v[188:191], v[8:11]
	v_mfma_f32_16x16x32_bf16 v[8:11], v[172:175], v[184:187], v[100:103]
	v_mfma_f32_16x16x32_bf16 v[184:187], v[176:179], v[188:191], v[8:11]
	v_mfma_f32_16x16x32_bf16 v[8:11], v[120:123], v[192:195], v[16:19]
	v_mfma_f32_16x16x32_bf16 v[188:191], v[124:127], v[196:199], v[8:11]
	v_mfma_f32_16x16x32_bf16 v[8:11], v[172:175], v[192:195], v[20:23]
	v_mfma_f32_16x16x32_bf16 v[172:175], v[176:179], v[196:199], v[8:11]
	s_setprio 0
	s_barrier
	s_nop 4
	ds_read_b128 v[8:11], v224
	ds_read_b128 v[12:15], v224 offset:1024
	ds_read_b128 v[20:23], v224 offset:2048
	ds_read_b128 v[176:179], v224 offset:3072
	ds_read_b128 v[192:195], v228
	ds_read_b128 v[196:199], v228 offset:1024
	ds_read_b128 v[224:227], v228 offset:2048
	ds_read_b128 v[230:233], v228 offset:3072
	s_add_u32 s42, s48, 0x10000
	s_addc_u32 s43, s49, 0
	s_mov_b32 m0, s51
	v_lshl_add_u64 v[88:89], s[42:43], 0, v[140:141]
	ds_read_b128 v[16:19], v163 offset:32768
	ds_read_b128 v[24:27], v163 offset:33792
	ds_read_b128 v[60:63], v163 offset:34816
	ds_read_b128 v[104:107], v163 offset:35840
	ds_read_b128 v[234:237], v163 offset:36864
	ds_read_b128 v[238:241], v163 offset:37888
	ds_read_b128 v[242:245], v163 offset:38912
	ds_read_b128 v[246:249], v163 offset:39936
	global_load_lds_dwordx4 v[88:89], off
	v_lshl_add_u64 v[88:89], s[42:43], 0, v[144:145]
	s_mov_b32 m0, s52
	s_nop 0
	global_load_lds_dwordx4 v[88:89], off
	s_waitcnt vmcnt(8)
	s_waitcnt lgkmcnt(0)
	s_barrier
	s_setprio 1
	s_waitcnt lgkmcnt(0)
	v_mfma_f32_16x16x32_bf16 v[64:67], v[8:11], v[16:19], v[64:67]
	v_mfma_f32_16x16x32_bf16 v[112:115], v[12:15], v[24:27], v[64:67]
	v_mfma_f32_16x16x32_bf16 v[64:67], v[20:23], v[16:19], v[68:71]
	v_mfma_f32_16x16x32_bf16 v[116:119], v[176:179], v[24:27], v[64:67]
	v_mfma_f32_16x16x32_bf16 v[64:67], v[8:11], v[60:63], v[72:75]
	v_mfma_f32_16x16x32_bf16 v[96:99], v[12:15], v[104:107], v[64:67]
	v_mfma_f32_16x16x32_bf16 v[64:67], v[20:23], v[60:63], v[76:79]
	v_mfma_f32_16x16x32_bf16 v[100:103], v[176:179], v[104:107], v[64:67]
	v_mfma_f32_16x16x32_bf16 v[64:67], v[8:11], v[234:237], v[80:83]
	v_mfma_f32_16x16x32_bf16 v[92:95], v[12:15], v[238:241], v[64:67]
	v_mfma_f32_16x16x32_bf16 v[64:67], v[20:23], v[234:237], v[84:87]
	v_mfma_f32_16x16x32_bf16 v[88:91], v[176:179], v[238:241], v[64:67]
	v_mfma_f32_16x16x32_bf16 v[64:67], v[8:11], v[242:245], v[212:215]
	v_mfma_f32_16x16x32_bf16 v[76:79], v[12:15], v[246:249], v[64:67]
	v_mfma_f32_16x16x32_bf16 v[64:67], v[20:23], v[242:245], v[216:219]
	v_mfma_f32_16x16x32_bf16 v[72:75], v[176:179], v[246:249], v[64:67]
	v_mfma_f32_16x16x32_bf16 v[64:67], v[192:195], v[16:19], v[220:223]
	v_mfma_f32_16x16x32_bf16 v[16:19], v[224:227], v[16:19], v[32:35]
	v_mfma_f32_16x16x32_bf16 v[124:127], v[230:233], v[24:27], v[16:19]
	v_mfma_f32_16x16x32_bf16 v[16:19], v[192:195], v[60:63], v[36:39]
	v_mfma_f32_16x16x32_bf16 v[108:111], v[196:199], v[104:107], v[16:19]
	v_mfma_f32_16x16x32_bf16 v[16:19], v[224:227], v[60:63], v[40:43]
	v_mfma_f32_16x16x32_bf16 v[104:107], v[230:233], v[104:107], v[16:19]
	v_mfma_f32_16x16x32_bf16 v[16:19], v[192:195], v[234:237], v[44:47]
	v_mfma_f32_16x16x32_bf16 v[84:87], v[196:199], v[238:241], v[16:19]
	v_mfma_f32_16x16x32_bf16 v[16:19], v[224:227], v[234:237], v[48:51]
	v_mfma_f32_16x16x32_bf16 v[80:83], v[230:233], v[238:241], v[16:19]
	v_mfma_f32_16x16x32_bf16 v[16:19], v[192:195], v[242:245], v[52:55]
	v_mfma_f32_16x16x32_bf16 v[68:71], v[196:199], v[246:249], v[16:19]
	v_mfma_f32_16x16x32_bf16 v[16:19], v[224:227], v[242:245], v[56:59]
	v_mfma_f32_16x16x32_bf16 v[120:123], v[196:199], v[24:27], v[64:67]
	v_mfma_f32_16x16x32_bf16 v[64:67], v[230:233], v[246:249], v[16:19]
	s_setprio 0
	s_barrier
	s_mov_b32 m0, s66
	s_nop 2
	v_lshl_add_u64 v[16:17], v[156:157], 0, s[12:13]
	s_add_u32 s42, s46, 0x10080
	ds_read_b128 v[36:39], v163 offset:49152
	ds_read_b128 v[40:43], v163 offset:50176
	ds_read_b128 v[212:215], v163 offset:51200
	ds_read_b128 v[216:219], v163 offset:52224
	ds_read_b128 v[220:223], v163 offset:53248
	ds_read_b128 v[234:237], v163 offset:54272
	ds_read_b128 v[238:241], v163 offset:55296
	ds_read_b128 v[242:245], v163 offset:56320
	global_load_lds_dwordx4 v[16:17], off
	v_lshl_add_u64 v[16:17], v[250:251], 0, s[12:13]
	s_mov_b32 m0, s65
	s_addc_u32 s43, s47, 0
	global_load_lds_dwordx4 v[16:17], off
	v_lshl_add_u64 v[16:17], s[42:43], 0, v[142:143]
	s_mov_b32 m0, s44
	s_nop 0
	global_load_lds_dwordx4 v[16:17], off
	v_lshl_add_u64 v[16:17], s[42:43], 0, v[146:147]
	s_mov_b32 m0, s45
	s_nop 0
	global_load_lds_dwordx4 v[16:17], off
	v_lshl_add_u64 v[16:17], v[252:253], 0, s[12:13]
	s_mov_b32 m0, s53
	s_nop 0
	global_load_lds_dwordx4 v[16:17], off
	v_lshl_add_u64 v[16:17], v[148:149], 0, s[12:13]
	s_mov_b32 m0, s54
	s_nop 0
	global_load_lds_dwordx4 v[16:17], off
	s_waitcnt vmcnt(8)
	s_waitcnt lgkmcnt(0)
	s_barrier
	s_setprio 1
	s_waitcnt lgkmcnt(0)
	v_mfma_f32_16x16x32_bf16 v[16:19], v[8:11], v[36:39], v[128:131]
	v_mfma_f32_16x16x32_bf16 v[60:63], v[12:15], v[40:43], v[16:19]
	v_mfma_f32_16x16x32_bf16 v[16:19], v[20:23], v[36:39], v[132:135]
	v_mfma_f32_16x16x32_bf16 v[56:59], v[176:179], v[40:43], v[16:19]
	v_mfma_f32_16x16x32_bf16 v[16:19], v[8:11], v[212:215], v[136:139]
	v_mfma_f32_16x16x32_bf16 v[44:47], v[12:15], v[216:219], v[16:19]
	v_mfma_f32_16x16x32_bf16 v[16:19], v[20:23], v[212:215], v[152:155]
	v_mfma_f32_16x16x32_bf16 v[32:35], v[176:179], v[216:219], v[16:19]
	v_mfma_f32_16x16x32_bf16 v[16:19], v[8:11], v[220:223], v[164:167]
	v_mfma_f32_16x16x32_bf16 v[0:3], v[8:11], v[238:241], v[0:3]
	v_mfma_f32_16x16x32_bf16 v[24:27], v[12:15], v[234:237], v[16:19]
	v_mfma_f32_16x16x32_bf16 v[16:19], v[20:23], v[220:223], v[168:171]
	v_mfma_f32_16x16x32_bf16 v[12:15], v[12:15], v[242:245], v[0:3]
	v_mfma_f32_16x16x32_bf16 v[0:3], v[20:23], v[238:241], v[4:7]
	v_mfma_f32_16x16x32_bf16 v[16:19], v[176:179], v[234:237], v[16:19]
	v_mfma_f32_16x16x32_bf16 v[8:11], v[176:179], v[242:245], v[0:3]
	v_mfma_f32_16x16x32_bf16 v[0:3], v[192:195], v[36:39], v[200:203]
	v_mfma_f32_16x16x32_bf16 v[52:55], v[196:199], v[40:43], v[0:3]
	v_mfma_f32_16x16x32_bf16 v[0:3], v[224:227], v[36:39], v[204:207]
	v_mfma_f32_16x16x32_bf16 v[48:51], v[230:233], v[40:43], v[0:3]
	v_mfma_f32_16x16x32_bf16 v[0:3], v[192:195], v[212:215], v[208:211]
	v_mfma_f32_16x16x32_bf16 v[40:43], v[196:199], v[216:219], v[0:3]
	v_mfma_f32_16x16x32_bf16 v[0:3], v[224:227], v[212:215], v[28:31]
	v_mfma_f32_16x16x32_bf16 v[36:39], v[230:233], v[216:219], v[0:3]
	v_mfma_f32_16x16x32_bf16 v[0:3], v[192:195], v[220:223], v[180:183]
	v_mfma_f32_16x16x32_bf16 v[28:31], v[196:199], v[234:237], v[0:3]
	v_mfma_f32_16x16x32_bf16 v[0:3], v[224:227], v[220:223], v[184:187]
	v_mfma_f32_16x16x32_bf16 v[20:23], v[230:233], v[234:237], v[0:3]
	v_mfma_f32_16x16x32_bf16 v[0:3], v[192:195], v[238:241], v[188:191]
	v_mfma_f32_16x16x32_bf16 v[4:7], v[196:199], v[242:245], v[0:3]
	v_mfma_f32_16x16x32_bf16 v[0:3], v[224:227], v[238:241], v[172:175]
	v_mfma_f32_16x16x32_bf16 v[0:3], v[230:233], v[242:245], v[0:3]
	s_setprio 0
	s_barrier
	s_andn2_b64 vcc, exec, s[14:15]
	s_cbranch_vccnz .LBB0_2198
	s_barrier
